# tile-boundary waits exact: in the first K-iteration of every tile after the first, the previous epilogue's 8+ stores may stay outstanding (vmcnt 18/22/18/14 instead of 10/14/10/14)
# baseline (speedup 1.0000x reference)
_Z14fwd_megakernel4Args:
	s_mov_b32 s99, 0
	s_mov_b32 s98, 0
	s_mov_b32 s101, 0
	s_load_dwordx8 s[36:43], s[0:1], 0x80
	s_load_dword s3, s[0:1], 0xa8
	s_load_dwordx2 s[14:15], s[0:1], 0xa0
	s_add_u32 s6, s0, 0xa0
	v_and_b32_e32 v241, 0x3ff, v0
	s_addc_u32 s7, s1, 0
	v_cmp_gt_u32_e32 vcc, 64, v241
	s_and_saveexec_b64 s[4:5], vcc
	v_lshl_add_u32 v1, v241, 2, 0
	v_add_u32_e32 v1, 0x20000, v1
	v_mov_b32_e32 v2, 0
	ds_write_b32 v1, v2
	s_or_b64 exec, exec, s[4:5]
	s_waitcnt lgkmcnt(0)
	s_barrier
	s_add_u32 s34, s42, 0xe0000
	s_getreg_b32 s4, hwreg(HW_REG_XCC_ID, 0, 4)
	s_addc_u32 s35, s43, 0
	s_and_b32 s52, s4, 15
	v_cmp_eq_u32_e64 s[62:63], 0, v241
	s_and_saveexec_b64 s[4:5], s[62:63]
	s_cbranch_execz .LBB0_5
	s_mov_b64 s[8:9], exec
	v_mbcnt_lo_u32_b32 v1, s8, 0
	v_mbcnt_hi_u32_b32 v1, s9, v1
	v_cmp_eq_u32_e32 vcc, 0, v1
	s_and_b64 s[10:11], exec, vcc
	s_mov_b64 exec, s[10:11]
	s_cbranch_execz .LBB0_5
	s_lshl_b32 s10, s52, 8
	s_bcnt1_i32_b64 s8, s[8:9]
	v_mov_b32_e32 v1, s10
	v_mov_b32_e32 v2, s8
	global_atomic_add v1, v2, s[34:35] offset:1024
	s_and_b32 s12, s2, 7
	s_lshl_b32 s12, s12, 3
	s_add_u32 s12, s12, 0x3800
	s_add_i32 s13, s52, 1
	v_mov_b32_e32 v3, s12
	v_mov_b32_e32 v4, s13
	s_sub_i32 s13, 16, s52
	v_mov_b32_e32 v5, s13
	global_atomic_umax v3, v4, s[34:35]
	global_atomic_umax v3, v5, s[34:35] offset:4

.Lnostb0:
	s_add_u32 s48, s46, 0xfffc0080
	s_addc_u32 s49, s47, -1
	s_add_i32 s83, 0, 0x10000
	s_cmp_eq_u32 s82, 12
	s_cselect_b32 s49, s39, s49
	s_cselect_b32 s48, s78, s48
	v_add_u32_e32 v140, s83, v146
	s_cselect_b32 s85, s37, s81
	s_cselect_b32 s84, s79, s80
	s_add_i32 s86, 0, 0x14000
	ds_read_b128 v[136:139], v140
	ds_read_b128 v[152:155], v140 offset:1024
	ds_read_b128 v[156:159], v140 offset:2048
	ds_read_b128 v[160:163], v140 offset:3072
	v_add_u32_e32 v140, s86, v146
	ds_read_b128 v[164:167], v140
	ds_read_b128 v[168:171], v140 offset:1024
	ds_read_b128 v[172:175], v140 offset:2048
	ds_read_b128 v[176:179], v140 offset:3072
	v_lshl_add_u64 v[140:141], s[46:47], 0, v[132:133]
	s_add_i32 m0, s45, 0xc000
	ds_read_b128 v[180:183], v150
	ds_read_b128 v[184:187], v150 offset:1024
	ds_read_b128 v[188:191], v150 offset:2048
	ds_read_b128 v[192:195], v150 offset:3072
	ds_read_b128 v[196:199], v150 offset:4096
	ds_read_b128 v[200:203], v150 offset:5120
	ds_read_b128 v[204:207], v150 offset:6144
	ds_read_b128 v[208:211], v150 offset:7168
	global_load_lds_dwordx4 v[140:141], off
	v_lshl_add_u64 v[140:141], v[140:141], 0, s[12:13]
	s_add_i32 m0, s45, 0xe000
	s_nop 0
	global_load_lds_dwordx4 v[140:141], off
	s_cmp_eq_u32 s101, 0
	s_cbranch_scc1 .Lbw0_0s
	s_waitcnt vmcnt(18)
	s_branch .Lbw0_0d
.Lbw0_0s:
	s_waitcnt vmcnt(10)
.Lbw0_0d:
	s_waitcnt lgkmcnt(0)
	s_barrier
	s_setprio 1
	s_waitcnt lgkmcnt(0)
	v_mfma_f32_16x16x32_bf16 v[124:127], v[136:139], v[180:183], 0
	v_mfma_f32_16x16x32_bf16 v[120:123], v[156:159], v[180:183], 0
	v_mfma_f32_16x16x32_bf16 v[112:115], v[136:139], v[188:191], 0
	v_mfma_f32_16x16x32_bf16 v[104:107], v[156:159], v[188:191], 0
	v_mfma_f32_16x16x32_bf16 v[96:99], v[136:139], v[196:199], 0
	v_mfma_f32_16x16x32_bf16 v[88:91], v[156:159], v[196:199], 0
	v_mfma_f32_16x16x32_bf16 v[80:83], v[136:139], v[204:207], 0
	v_mfma_f32_16x16x32_bf16 v[72:75], v[156:159], v[204:207], 0
	v_mfma_f32_16x16x32_bf16 v[124:127], v[152:155], v[184:187], v[124:127]
	v_mfma_f32_16x16x32_bf16 v[120:123], v[160:163], v[184:187], v[120:123]
	v_mfma_f32_16x16x32_bf16 v[112:115], v[152:155], v[192:195], v[112:115]
	v_mfma_f32_16x16x32_bf16 v[104:107], v[160:163], v[192:195], v[104:107]
	v_mfma_f32_16x16x32_bf16 v[96:99], v[152:155], v[200:203], v[96:99]
	v_mfma_f32_16x16x32_bf16 v[88:91], v[160:163], v[200:203], v[88:91]
	v_mfma_f32_16x16x32_bf16 v[80:83], v[152:155], v[208:211], v[80:83]
	v_mfma_f32_16x16x32_bf16 v[72:75], v[160:163], v[208:211], v[72:75]
	s_setprio 0
	s_setprio 1
	v_mfma_f32_16x16x32_bf16 v[116:119], v[164:167], v[180:183], 0
	v_mfma_f32_16x16x32_bf16 v[108:111], v[172:175], v[180:183], 0
	v_mfma_f32_16x16x32_bf16 v[100:103], v[164:167], v[188:191], 0
	v_mfma_f32_16x16x32_bf16 v[92:95], v[172:175], v[188:191], 0
	v_mfma_f32_16x16x32_bf16 v[84:87], v[164:167], v[196:199], 0
	v_mfma_f32_16x16x32_bf16 v[76:79], v[172:175], v[196:199], 0
	v_mfma_f32_16x16x32_bf16 v[68:71], v[164:167], v[204:207], 0
	v_mfma_f32_16x16x32_bf16 v[64:67], v[172:175], v[204:207], 0
	v_mfma_f32_16x16x32_bf16 v[116:119], v[168:171], v[184:187], v[116:119]
	v_mfma_f32_16x16x32_bf16 v[108:111], v[176:179], v[184:187], v[108:111]
	v_mfma_f32_16x16x32_bf16 v[100:103], v[168:171], v[192:195], v[100:103]
	v_mfma_f32_16x16x32_bf16 v[92:95], v[176:179], v[192:195], v[92:95]
	v_mfma_f32_16x16x32_bf16 v[84:87], v[168:171], v[200:203], v[84:87]
	v_mfma_f32_16x16x32_bf16 v[76:79], v[176:179], v[200:203], v[76:79]
	v_mfma_f32_16x16x32_bf16 v[68:71], v[168:171], v[208:211], v[68:71]
	v_mfma_f32_16x16x32_bf16 v[64:67], v[176:179], v[208:211], v[64:67]
	s_setprio 0
	s_barrier
	s_add_i32 s83, s83, s69
	v_lshl_add_u64 v[140:141], s[84:85], 0, v[128:129]
	s_mov_b32 m0, s83
	ds_read_b128 v[180:183], v150 offset:16384
	ds_read_b128 v[184:187], v150 offset:17408
	ds_read_b128 v[188:191], v150 offset:18432
	ds_read_b128 v[192:195], v150 offset:19456
	ds_read_b128 v[196:199], v150 offset:20480
	ds_read_b128 v[200:203], v150 offset:21504
	ds_read_b128 v[204:207], v150 offset:22528
	ds_read_b128 v[208:211], v150 offset:23552
	global_load_lds_dwordx4 v[140:141], off
	v_lshl_add_u64 v[212:213], v[140:141], 0, s[12:13]
	s_add_i32 m0, s83, 0x2000
	s_add_i32 s83, s86, s69
	global_load_lds_dwordx4 v[212:213], off
	v_lshl_add_u64 v[212:213], v[140:141], 0, s[14:15]
	s_mov_b32 m0, s83
	s_nop 0
	global_load_lds_dwordx4 v[212:213], off
	v_lshl_add_u64 v[212:213], v[140:141], 0, s[16:17]
	s_add_i32 m0, s83, 0x2000
	s_nop 0
	global_load_lds_dwordx4 v[212:213], off
	v_lshl_add_u64 v[212:213], s[48:49], 0, v[130:131]
	s_mov_b32 m0, s45
	v_lshl_add_u64 v[214:215], v[212:213], 0, s[12:13]
	global_load_lds_dwordx4 v[212:213], off
	s_mov_b32 m0, s71
	s_nop 0
	global_load_lds_dwordx4 v[214:215], off
	s_cmp_eq_u32 s101, 0
	s_cbranch_scc1 .Lbw0_1s
	s_waitcnt vmcnt(22)
	s_branch .Lbw0_1d
.Lbw0_1s:
	s_waitcnt vmcnt(14)
.Lbw0_1d:
	s_waitcnt lgkmcnt(0)
	s_barrier
	s_setprio 1
	s_waitcnt lgkmcnt(0)
	v_mfma_f32_16x16x32_bf16 v[60:63], v[136:139], v[180:183], 0
	v_mfma_f32_16x16x32_bf16 v[56:59], v[156:159], v[180:183], 0
	v_mfma_f32_16x16x32_bf16 v[48:51], v[136:139], v[188:191], 0
	v_mfma_f32_16x16x32_bf16 v[40:43], v[156:159], v[188:191], 0
	v_mfma_f32_16x16x32_bf16 v[32:35], v[136:139], v[196:199], 0
	v_mfma_f32_16x16x32_bf16 v[24:27], v[156:159], v[196:199], 0
	v_mfma_f32_16x16x32_bf16 v[16:19], v[136:139], v[204:207], 0
	v_mfma_f32_16x16x32_bf16 v[8:11], v[156:159], v[204:207], 0
	v_mfma_f32_16x16x32_bf16 v[60:63], v[152:155], v[184:187], v[60:63]
	v_mfma_f32_16x16x32_bf16 v[56:59], v[160:163], v[184:187], v[56:59]
	v_mfma_f32_16x16x32_bf16 v[48:51], v[152:155], v[192:195], v[48:51]
	v_mfma_f32_16x16x32_bf16 v[40:43], v[160:163], v[192:195], v[40:43]
	v_mfma_f32_16x16x32_bf16 v[32:35], v[152:155], v[200:203], v[32:35]
	v_mfma_f32_16x16x32_bf16 v[24:27], v[160:163], v[200:203], v[24:27]
	v_mfma_f32_16x16x32_bf16 v[16:19], v[152:155], v[208:211], v[16:19]
	v_mfma_f32_16x16x32_bf16 v[8:11], v[160:163], v[208:211], v[8:11]
	s_setprio 0
	s_setprio 1
	v_mfma_f32_16x16x32_bf16 v[52:55], v[164:167], v[180:183], 0
	v_mfma_f32_16x16x32_bf16 v[44:47], v[172:175], v[180:183], 0
	v_mfma_f32_16x16x32_bf16 v[36:39], v[164:167], v[188:191], 0
	v_mfma_f32_16x16x32_bf16 v[28:31], v[172:175], v[188:191], 0
	v_mfma_f32_16x16x32_bf16 v[20:23], v[164:167], v[196:199], 0
	v_mfma_f32_16x16x32_bf16 v[12:15], v[172:175], v[196:199], 0
	v_mfma_f32_16x16x32_bf16 v[4:7], v[164:167], v[204:207], 0
	v_mfma_f32_16x16x32_bf16 v[0:3], v[172:175], v[204:207], 0
	v_mfma_f32_16x16x32_bf16 v[52:55], v[168:171], v[184:187], v[52:55]
	v_mfma_f32_16x16x32_bf16 v[44:47], v[176:179], v[184:187], v[44:47]
	v_mfma_f32_16x16x32_bf16 v[36:39], v[168:171], v[192:195], v[36:39]
	v_mfma_f32_16x16x32_bf16 v[28:31], v[176:179], v[192:195], v[28:31]
	v_mfma_f32_16x16x32_bf16 v[20:23], v[168:171], v[200:203], v[20:23]
	v_mfma_f32_16x16x32_bf16 v[12:15], v[176:179], v[200:203], v[12:15]
	v_mfma_f32_16x16x32_bf16 v[4:7], v[168:171], v[208:211], v[4:7]
	v_mfma_f32_16x16x32_bf16 v[0:3], v[176:179], v[208:211], v[0:3]
	s_setprio 0
	s_barrier
	s_add_i32 s48, 0, 0x18000
	v_add_u32_e32 v151, s48, v146
	s_add_i32 s49, 0, 0x1c000
	ds_read_b128 v[136:139], v151
	ds_read_b128 v[152:155], v151 offset:1024
	ds_read_b128 v[156:159], v151 offset:2048
	ds_read_b128 v[160:163], v151 offset:3072
	v_add_u32_e32 v151, s49, v146
	ds_read_b128 v[164:167], v151
	ds_read_b128 v[168:171], v151 offset:1024
	ds_read_b128 v[172:175], v151 offset:2048
	ds_read_b128 v[176:179], v151 offset:3072
	s_mov_b32 m0, s72
	v_lshl_add_u64 v[214:215], v[212:213], 0, s[14:15]
	ds_read_b128 v[180:183], v150 offset:32768
	ds_read_b128 v[184:187], v150 offset:33792
	ds_read_b128 v[188:191], v150 offset:34816
	ds_read_b128 v[192:195], v150 offset:35840
	ds_read_b128 v[196:199], v150 offset:36864
	ds_read_b128 v[200:203], v150 offset:37888
	ds_read_b128 v[204:207], v150 offset:38912
	ds_read_b128 v[208:211], v150 offset:39936
	global_load_lds_dwordx4 v[214:215], off
	v_lshl_add_u64 v[214:215], v[212:213], 0, s[16:17]
	s_mov_b32 m0, s73
	s_nop 0
	global_load_lds_dwordx4 v[214:215], off
	s_cmp_eq_u32 s101, 0
	s_cbranch_scc1 .Lbw0_2s
	s_waitcnt vmcnt(18)
	s_branch .Lbw0_2d

.Lbw0_2d:
	s_waitcnt lgkmcnt(0)
	s_barrier
	s_setprio 1
	s_waitcnt lgkmcnt(0)
	v_mfma_f32_16x16x32_bf16 v[124:127], v[136:139], v[180:183], v[124:127]
	v_mfma_f32_16x16x32_bf16 v[120:123], v[156:159], v[180:183], v[120:123]
	v_mfma_f32_16x16x32_bf16 v[112:115], v[136:139], v[188:191], v[112:115]
	v_mfma_f32_16x16x32_bf16 v[104:107], v[156:159], v[188:191], v[104:107]
	v_mfma_f32_16x16x32_bf16 v[96:99], v[136:139], v[196:199], v[96:99]
	v_mfma_f32_16x16x32_bf16 v[88:91], v[156:159], v[196:199], v[88:91]
	v_mfma_f32_16x16x32_bf16 v[80:83], v[136:139], v[204:207], v[80:83]
	v_mfma_f32_16x16x32_bf16 v[72:75], v[156:159], v[204:207], v[72:75]
	v_mfma_f32_16x16x32_bf16 v[124:127], v[152:155], v[184:187], v[124:127]
	v_mfma_f32_16x16x32_bf16 v[120:123], v[160:163], v[184:187], v[120:123]
	v_mfma_f32_16x16x32_bf16 v[112:115], v[152:155], v[192:195], v[112:115]
	v_mfma_f32_16x16x32_bf16 v[104:107], v[160:163], v[192:195], v[104:107]
	v_mfma_f32_16x16x32_bf16 v[96:99], v[152:155], v[200:203], v[96:99]
	v_mfma_f32_16x16x32_bf16 v[88:91], v[160:163], v[200:203], v[88:91]
	v_mfma_f32_16x16x32_bf16 v[80:83], v[152:155], v[208:211], v[80:83]
	v_mfma_f32_16x16x32_bf16 v[72:75], v[160:163], v[208:211], v[72:75]
	s_setprio 0
	s_setprio 1
	v_mfma_f32_16x16x32_bf16 v[116:119], v[164:167], v[180:183], v[116:119]
	v_mfma_f32_16x16x32_bf16 v[108:111], v[172:175], v[180:183], v[108:111]
	v_mfma_f32_16x16x32_bf16 v[100:103], v[164:167], v[188:191], v[100:103]
	v_mfma_f32_16x16x32_bf16 v[92:95], v[172:175], v[188:191], v[92:95]
	v_mfma_f32_16x16x32_bf16 v[84:87], v[164:167], v[196:199], v[84:87]
	v_mfma_f32_16x16x32_bf16 v[76:79], v[172:175], v[196:199], v[76:79]
	v_mfma_f32_16x16x32_bf16 v[68:71], v[164:167], v[204:207], v[68:71]
	v_mfma_f32_16x16x32_bf16 v[64:67], v[172:175], v[204:207], v[64:67]
	v_mfma_f32_16x16x32_bf16 v[116:119], v[168:171], v[184:187], v[116:119]
	v_mfma_f32_16x16x32_bf16 v[108:111], v[176:179], v[184:187], v[108:111]
	v_mfma_f32_16x16x32_bf16 v[100:103], v[168:171], v[192:195], v[100:103]
	v_mfma_f32_16x16x32_bf16 v[92:95], v[176:179], v[192:195], v[92:95]
	v_mfma_f32_16x16x32_bf16 v[84:87], v[168:171], v[200:203], v[84:87]
	v_mfma_f32_16x16x32_bf16 v[76:79], v[176:179], v[200:203], v[76:79]
	v_mfma_f32_16x16x32_bf16 v[68:71], v[168:171], v[208:211], v[68:71]
	v_mfma_f32_16x16x32_bf16 v[64:67], v[176:179], v[208:211], v[64:67]
	s_setprio 0
	s_barrier
	s_add_i32 s48, s48, s69
	v_lshl_add_u64 v[214:215], v[140:141], 0, s[18:19]
	s_mov_b32 m0, s48
	ds_read_b128 v[180:183], v150 offset:49152
	ds_read_b128 v[184:187], v150 offset:50176
	ds_read_b128 v[188:191], v150 offset:51200
	ds_read_b128 v[192:195], v150 offset:52224
	ds_read_b128 v[196:199], v150 offset:53248
	ds_read_b128 v[200:203], v150 offset:54272
	ds_read_b128 v[204:207], v150 offset:55296
	ds_read_b128 v[208:211], v150 offset:56320
	global_load_lds_dwordx4 v[214:215], off
	v_lshl_add_u64 v[214:215], v[140:141], 0, s[20:21]
	s_add_i32 m0, s48, 0x2000
	s_add_i32 s48, s49, s69
	global_load_lds_dwordx4 v[214:215], off
	v_lshl_add_u64 v[214:215], v[140:141], 0, s[22:23]
	s_mov_b32 m0, s48
	v_lshl_add_u64 v[140:141], v[140:141], 0, s[24:25]
	global_load_lds_dwordx4 v[214:215], off
	s_add_i32 m0, s48, 0x2000
	s_nop 0
	global_load_lds_dwordx4 v[140:141], off
	v_lshl_add_u64 v[140:141], v[212:213], 0, s[18:19]
	s_mov_b32 m0, s10
	s_nop 0
	global_load_lds_dwordx4 v[140:141], off
	v_lshl_add_u64 v[140:141], v[212:213], 0, s[20:21]
	s_mov_b32 m0, s74
	s_nop 0
	global_load_lds_dwordx4 v[140:141], off
	s_waitcnt vmcnt(14)
	s_waitcnt lgkmcnt(0)
	s_barrier
	s_setprio 1
	s_waitcnt lgkmcnt(0)
	v_mfma_f32_16x16x32_bf16 v[60:63], v[136:139], v[180:183], v[60:63]
	v_mfma_f32_16x16x32_bf16 v[56:59], v[156:159], v[180:183], v[56:59]
	v_mfma_f32_16x16x32_bf16 v[48:51], v[136:139], v[188:191], v[48:51]
	v_mfma_f32_16x16x32_bf16 v[40:43], v[156:159], v[188:191], v[40:43]
	v_mfma_f32_16x16x32_bf16 v[32:35], v[136:139], v[196:199], v[32:35]
	v_mfma_f32_16x16x32_bf16 v[24:27], v[156:159], v[196:199], v[24:27]
	v_mfma_f32_16x16x32_bf16 v[16:19], v[136:139], v[204:207], v[16:19]
	v_mfma_f32_16x16x32_bf16 v[8:11], v[156:159], v[204:207], v[8:11]
	v_mfma_f32_16x16x32_bf16 v[60:63], v[152:155], v[184:187], v[60:63]
	v_mfma_f32_16x16x32_bf16 v[56:59], v[160:163], v[184:187], v[56:59]
	v_mfma_f32_16x16x32_bf16 v[48:51], v[152:155], v[192:195], v[48:51]
	v_mfma_f32_16x16x32_bf16 v[40:43], v[160:163], v[192:195], v[40:43]
	v_mfma_f32_16x16x32_bf16 v[32:35], v[152:155], v[200:203], v[32:35]
	v_mfma_f32_16x16x32_bf16 v[24:27], v[160:163], v[200:203], v[24:27]
	v_mfma_f32_16x16x32_bf16 v[16:19], v[152:155], v[208:211], v[16:19]
	v_mfma_f32_16x16x32_bf16 v[8:11], v[160:163], v[208:211], v[8:11]
	s_setprio 0
	s_setprio 1
	v_mfma_f32_16x16x32_bf16 v[52:55], v[164:167], v[180:183], v[52:55]
	v_mfma_f32_16x16x32_bf16 v[44:47], v[172:175], v[180:183], v[44:47]
	v_mfma_f32_16x16x32_bf16 v[36:39], v[164:167], v[188:191], v[36:39]
	v_mfma_f32_16x16x32_bf16 v[28:31], v[172:175], v[188:191], v[28:31]
	v_mfma_f32_16x16x32_bf16 v[20:23], v[164:167], v[196:199], v[20:23]
	v_mfma_f32_16x16x32_bf16 v[12:15], v[172:175], v[196:199], v[12:15]
	v_mfma_f32_16x16x32_bf16 v[4:7], v[164:167], v[204:207], v[4:7]
	v_mfma_f32_16x16x32_bf16 v[0:3], v[172:175], v[204:207], v[0:3]
	v_mfma_f32_16x16x32_bf16 v[52:55], v[168:171], v[184:187], v[52:55]
	v_mfma_f32_16x16x32_bf16 v[44:47], v[176:179], v[184:187], v[44:47]
	v_mfma_f32_16x16x32_bf16 v[36:39], v[168:171], v[192:195], v[36:39]
	v_mfma_f32_16x16x32_bf16 v[28:31], v[176:179], v[192:195], v[28:31]
	v_mfma_f32_16x16x32_bf16 v[20:23], v[168:171], v[200:203], v[20:23]
	v_mfma_f32_16x16x32_bf16 v[12:15], v[176:179], v[200:203], v[12:15]
	v_mfma_f32_16x16x32_bf16 v[4:7], v[168:171], v[208:211], v[4:7]
	v_mfma_f32_16x16x32_bf16 v[0:3], v[176:179], v[208:211], v[0:3]
	s_setprio 0
	s_barrier
	s_add_i32 s82, s82, 2
	s_add_u32 s46, s46, 0x100
	s_addc_u32 s47, s47, 0
	s_add_u32 s80, s80, 0x100
	s_addc_u32 s81, s81, 0
	s_cmp_gt_u32 s82, 13

.LBB0_195:
	s_and_saveexec_b64 s[46:47], s[0:1]
	ds_write_b32 v147, v143
	s_or_b64 exec, exec, s[46:47]
	s_waitcnt lgkmcnt(0)
	s_barrier
	ds_read2_b32 v[152:153], v148 offset1:16
	ds_read2_b32 v[154:155], v148 offset0:32 offset1:48
	ds_read2_b32 v[140:141], v148 offset0:128 offset1:144
	ds_read2_b32 v[138:139], v148 offset0:160 offset1:176
	v_lshl_add_u32 v136, s44, 8, v145
	v_lshl_or_b32 v156, s77, 8, v149
	v_ashrrev_i32_e32 v137, 31, v136
	s_waitcnt lgkmcnt(0)
	v_pk_mul_f32 v[124:125], v[124:125], v[152:153] op_sel_hi:[1,0]
	v_pk_mul_f32 v[120:121], v[120:121], v[152:153] op_sel_hi:[1,0]
	v_ashrrev_i32_e32 v157, 31, v156
	v_pk_mul_f32 v[126:127], v[126:127], v[152:153] op_sel_hi:[1,0]
	v_pk_mul_f32 v[158:159], v[122:123], v[152:153] op_sel_hi:[1,0]
	v_cvt_pk_bf16_f32 v122, v124, v125
	v_cvt_pk_bf16_f32 v123, v126, v127
	v_cvt_pk_bf16_f32 v124, v120, v121
	v_lshlrev_b64 v[120:121], s75, v[136:137]
	v_lshl_add_u64 v[126:127], v[120:121], 1, s[28:29]
	v_lshlrev_b64 v[120:121], 1, v[156:157]
	v_lshl_add_u64 v[126:127], v[126:127], 0, v[120:121]
	v_cvt_pk_bf16_f32 v125, v158, v159
	global_store_dwordx4 v[126:127], v[122:125], off
	v_pk_mul_f32 v[116:117], v[116:117], v[152:153] op_sel_hi:[1,0]
	v_pk_mul_f32 v[118:119], v[118:119], v[152:153] op_sel_hi:[1,0]
	v_pk_mul_f32 v[122:123], v[110:111], v[152:153] op_sel_hi:[1,0]
	v_pk_mul_f32 v[110:111], v[108:109], v[152:153] op_sel_hi:[1,0]
	v_cvt_pk_bf16_f32 v108, v116, v117
	v_cvt_pk_bf16_f32 v109, v118, v119
	v_pk_mul_f32 v[96:97], v[96:97], v[154:155] op_sel_hi:[1,0]
	v_cvt_pk_bf16_f32 v110, v110, v111
	v_cvt_pk_bf16_f32 v111, v122, v123
	global_store_dwordx4 v[126:127], v[108:111], off offset:256
	v_pk_mul_f32 v[84:85], v[84:85], v[154:155] op_sel_hi:[1,0]
	v_pk_mul_f32 v[86:87], v[86:87], v[154:155] op_sel_hi:[1,0]
	v_or_b32_e32 v108, 16, v136
	v_ashrrev_i32_e32 v109, 31, v108
	v_lshlrev_b64 v[108:109], s75, v[108:109]
	v_mov_b32_e32 v110, v153
	v_lshl_add_u64 v[108:109], v[108:109], 1, s[28:29]
	v_pk_mul_f32 v[114:115], v[114:115], v[110:111] op_sel_hi:[1,0]
	v_pk_mul_f32 v[112:113], v[112:113], v[110:111] op_sel_hi:[1,0]
	v_pk_mul_f32 v[116:117], v[106:107], v[110:111] op_sel_hi:[1,0]
	v_pk_mul_f32 v[106:107], v[104:105], v[110:111] op_sel_hi:[1,0]
	v_cvt_pk_bf16_f32 v104, v112, v113
	v_cvt_pk_bf16_f32 v105, v114, v115
	v_lshl_add_u64 v[108:109], v[108:109], 0, v[120:121]
	v_cvt_pk_bf16_f32 v106, v106, v107
	v_cvt_pk_bf16_f32 v107, v116, v117
	global_store_dwordx4 v[108:109], v[104:107], off
	v_pk_mul_f32 v[100:101], v[100:101], v[110:111] op_sel_hi:[1,0]
	v_pk_mul_f32 v[102:103], v[102:103], v[110:111] op_sel_hi:[1,0]
	v_pk_mul_f32 v[104:105], v[94:95], v[110:111] op_sel_hi:[1,0]
	v_pk_mul_f32 v[94:95], v[92:93], v[110:111] op_sel_hi:[1,0]
	v_cvt_pk_bf16_f32 v92, v100, v101
	v_cvt_pk_bf16_f32 v93, v102, v103
	v_pk_mul_f32 v[60:61], v[60:61], v[140:141] op_sel_hi:[1,0]
	v_cvt_pk_bf16_f32 v94, v94, v95
	v_cvt_pk_bf16_f32 v95, v104, v105
	global_store_dwordx4 v[108:109], v[92:95], off offset:256
	v_pk_mul_f32 v[62:63], v[62:63], v[140:141] op_sel_hi:[1,0]
	v_pk_mul_f32 v[52:53], v[52:53], v[140:141] op_sel_hi:[1,0]
	v_or_b32_e32 v92, 32, v136
	v_ashrrev_i32_e32 v93, 31, v92
	v_lshlrev_b64 v[92:93], s75, v[92:93]
	v_lshl_add_u64 v[92:93], v[92:93], 1, s[28:29]
	v_pk_mul_f32 v[94:95], v[98:99], v[154:155] op_sel_hi:[1,0]
	v_pk_mul_f32 v[98:99], v[90:91], v[154:155] op_sel_hi:[1,0]
	v_pk_mul_f32 v[90:91], v[88:89], v[154:155] op_sel_hi:[1,0]
	v_cvt_pk_bf16_f32 v88, v96, v97
	v_cvt_pk_bf16_f32 v89, v94, v95
	v_lshl_add_u64 v[92:93], v[92:93], 0, v[120:121]
	v_cvt_pk_bf16_f32 v90, v90, v91
	v_cvt_pk_bf16_f32 v91, v98, v99
	global_store_dwordx4 v[92:93], v[88:91], off
	v_pk_mul_f32 v[54:55], v[54:55], v[140:141] op_sel_hi:[1,0]
	v_pk_mul_f32 v[32:33], v[32:33], v[138:139] op_sel_hi:[1,0]
	v_pk_mul_f32 v[88:89], v[78:79], v[154:155] op_sel_hi:[1,0]
	v_pk_mul_f32 v[78:79], v[76:77], v[154:155] op_sel_hi:[1,0]
	v_cvt_pk_bf16_f32 v76, v84, v85
	v_cvt_pk_bf16_f32 v77, v86, v87
	v_pk_mul_f32 v[20:21], v[20:21], v[138:139] op_sel_hi:[1,0]
	v_cvt_pk_bf16_f32 v78, v78, v79
	v_cvt_pk_bf16_f32 v79, v88, v89
	global_store_dwordx4 v[92:93], v[76:79], off offset:256
	v_pk_mul_f32 v[22:23], v[22:23], v[138:139] op_sel_hi:[1,0]
	s_andn2_b64 vcc, exec, s[4:5]
	v_or_b32_e32 v76, 48, v136
	v_ashrrev_i32_e32 v77, 31, v76
	v_lshlrev_b64 v[76:77], s75, v[76:77]
	v_mov_b32_e32 v78, v155
	v_lshl_add_u64 v[76:77], v[76:77], 1, s[28:29]
	v_pk_mul_f32 v[82:83], v[82:83], v[78:79] op_sel_hi:[1,0]
	v_pk_mul_f32 v[80:81], v[80:81], v[78:79] op_sel_hi:[1,0]
	v_pk_mul_f32 v[84:85], v[74:75], v[78:79] op_sel_hi:[1,0]
	v_pk_mul_f32 v[74:75], v[72:73], v[78:79] op_sel_hi:[1,0]
	v_cvt_pk_bf16_f32 v72, v80, v81
	v_cvt_pk_bf16_f32 v73, v82, v83
	v_lshl_add_u64 v[76:77], v[76:77], 0, v[120:121]
	v_cvt_pk_bf16_f32 v74, v74, v75
	v_cvt_pk_bf16_f32 v75, v84, v85
	global_store_dwordx4 v[76:77], v[72:75], off
	v_pk_mul_f32 v[68:69], v[68:69], v[78:79] op_sel_hi:[1,0]
	v_pk_mul_f32 v[70:71], v[70:71], v[78:79] op_sel_hi:[1,0]
	v_pk_mul_f32 v[72:73], v[66:67], v[78:79] op_sel_hi:[1,0]
	v_pk_mul_f32 v[66:67], v[64:65], v[78:79] op_sel_hi:[1,0]
	v_cvt_pk_bf16_f32 v64, v68, v69
	v_cvt_pk_bf16_f32 v65, v70, v71
	s_mov_b64 s[4:5], -1
	v_cvt_pk_bf16_f32 v66, v66, v67
	v_cvt_pk_bf16_f32 v67, v72, v73
	global_store_dwordx4 v[76:77], v[64:67], off offset:256
	s_nop 1
	v_add_u32_e32 v64, 0x80, v136
	v_ashrrev_i32_e32 v65, 31, v64
	v_pk_mul_f32 v[66:67], v[58:59], v[140:141] op_sel_hi:[1,0]
	v_pk_mul_f32 v[58:59], v[56:57], v[140:141] op_sel_hi:[1,0]
	v_cvt_pk_bf16_f32 v56, v60, v61
	v_lshlrev_b64 v[60:61], s75, v[64:65]
	v_lshl_add_u64 v[60:61], v[60:61], 1, s[28:29]
	v_cvt_pk_bf16_f32 v57, v62, v63
	v_lshl_add_u64 v[60:61], v[60:61], 0, v[120:121]
	v_cvt_pk_bf16_f32 v58, v58, v59
	v_cvt_pk_bf16_f32 v59, v66, v67
	global_store_dwordx4 v[60:61], v[56:59], off
	s_nop 1
	v_pk_mul_f32 v[56:57], v[46:47], v[140:141] op_sel_hi:[1,0]
	v_pk_mul_f32 v[46:47], v[44:45], v[140:141] op_sel_hi:[1,0]
	v_cvt_pk_bf16_f32 v44, v52, v53
	v_cvt_pk_bf16_f32 v45, v54, v55
	s_nop 0
	v_cvt_pk_bf16_f32 v46, v46, v47
	v_cvt_pk_bf16_f32 v47, v56, v57
	global_store_dwordx4 v[60:61], v[44:47], off offset:256
	s_nop 1
	v_add_u32_e32 v44, 0x90, v136
	v_ashrrev_i32_e32 v45, 31, v44
	v_lshlrev_b64 v[44:45], s75, v[44:45]
	v_mov_b32_e32 v46, v141
	v_lshl_add_u64 v[44:45], v[44:45], 1, s[28:29]
	v_pk_mul_f32 v[50:51], v[50:51], v[46:47] op_sel_hi:[1,0]
	v_pk_mul_f32 v[48:49], v[48:49], v[46:47] op_sel_hi:[1,0]
	v_pk_mul_f32 v[52:53], v[42:43], v[46:47] op_sel_hi:[1,0]
	v_pk_mul_f32 v[42:43], v[40:41], v[46:47] op_sel_hi:[1,0]
	v_cvt_pk_bf16_f32 v40, v48, v49
	v_cvt_pk_bf16_f32 v41, v50, v51
	v_lshl_add_u64 v[44:45], v[44:45], 0, v[120:121]
	v_cvt_pk_bf16_f32 v42, v42, v43
	v_cvt_pk_bf16_f32 v43, v52, v53
	global_store_dwordx4 v[44:45], v[40:43], off
	v_pk_mul_f32 v[36:37], v[36:37], v[46:47] op_sel_hi:[1,0]
	v_pk_mul_f32 v[38:39], v[38:39], v[46:47] op_sel_hi:[1,0]
	v_pk_mul_f32 v[40:41], v[30:31], v[46:47] op_sel_hi:[1,0]
	v_pk_mul_f32 v[30:31], v[28:29], v[46:47] op_sel_hi:[1,0]
	v_cvt_pk_bf16_f32 v28, v36, v37
	v_cvt_pk_bf16_f32 v29, v38, v39
	s_nop 0
	v_cvt_pk_bf16_f32 v30, v30, v31
	v_cvt_pk_bf16_f32 v31, v40, v41
	global_store_dwordx4 v[44:45], v[28:31], off offset:256
	s_nop 1
	v_add_u32_e32 v28, 0xa0, v136
	v_ashrrev_i32_e32 v29, 31, v28
	v_lshlrev_b64 v[28:29], s75, v[28:29]
	v_lshl_add_u64 v[28:29], v[28:29], 1, s[28:29]
	v_pk_mul_f32 v[30:31], v[34:35], v[138:139] op_sel_hi:[1,0]
	v_pk_mul_f32 v[34:35], v[26:27], v[138:139] op_sel_hi:[1,0]
	v_pk_mul_f32 v[26:27], v[24:25], v[138:139] op_sel_hi:[1,0]
	v_cvt_pk_bf16_f32 v24, v32, v33
	v_cvt_pk_bf16_f32 v25, v30, v31
	v_lshl_add_u64 v[28:29], v[28:29], 0, v[120:121]
	v_cvt_pk_bf16_f32 v26, v26, v27
	v_cvt_pk_bf16_f32 v27, v34, v35
	global_store_dwordx4 v[28:29], v[24:27], off
	s_nop 1
	v_pk_mul_f32 v[24:25], v[14:15], v[138:139] op_sel_hi:[1,0]
	v_pk_mul_f32 v[14:15], v[12:13], v[138:139] op_sel_hi:[1,0]
	v_cvt_pk_bf16_f32 v12, v20, v21
	v_cvt_pk_bf16_f32 v13, v22, v23
	s_nop 0
	v_cvt_pk_bf16_f32 v14, v14, v15
	v_cvt_pk_bf16_f32 v15, v24, v25
	global_store_dwordx4 v[28:29], v[12:15], off offset:256
	s_nop 1
	v_add_u32_e32 v12, 0xb0, v136
	v_ashrrev_i32_e32 v13, 31, v12
	v_lshlrev_b64 v[12:13], s75, v[12:13]
	v_mov_b32_e32 v14, v139
	v_lshl_add_u64 v[12:13], v[12:13], 1, s[28:29]
	v_pk_mul_f32 v[18:19], v[18:19], v[14:15] op_sel_hi:[1,0]
	v_pk_mul_f32 v[16:17], v[16:17], v[14:15] op_sel_hi:[1,0]
	v_pk_mul_f32 v[20:21], v[10:11], v[14:15] op_sel_hi:[1,0]
	v_pk_mul_f32 v[10:11], v[8:9], v[14:15] op_sel_hi:[1,0]
	v_cvt_pk_bf16_f32 v8, v16, v17
	v_cvt_pk_bf16_f32 v9, v18, v19
	v_lshl_add_u64 v[12:13], v[12:13], 0, v[120:121]
	v_cvt_pk_bf16_f32 v10, v10, v11
	v_cvt_pk_bf16_f32 v11, v20, v21
	global_store_dwordx4 v[12:13], v[8:11], off
	v_pk_mul_f32 v[6:7], v[6:7], v[14:15] op_sel_hi:[1,0]
	v_pk_mul_f32 v[4:5], v[4:5], v[14:15] op_sel_hi:[1,0]
	v_pk_mul_f32 v[8:9], v[2:3], v[14:15] op_sel_hi:[1,0]
	v_pk_mul_f32 v[2:3], v[0:1], v[14:15] op_sel_hi:[1,0]
	v_cvt_pk_bf16_f32 v0, v4, v5
	v_cvt_pk_bf16_f32 v1, v6, v7
	s_nop 0
	v_cvt_pk_bf16_f32 v2, v2, v3
	v_cvt_pk_bf16_f32 v3, v8, v9
	global_store_dwordx4 v[12:13], v[0:3], off offset:256
	s_cbranch_vccnz .LBB0_184
	s_mov_b32 s101, 1
	s_andn2_b64 vcc, exec, s[26:27]
	s_cbranch_vccnz .LBB0_183
	s_mov_b32 s98, 1
	s_branch .LBB0_183

.Lnostb1:
	s_add_u32 s14, s60, 0xfffc0080
	s_addc_u32 s15, s61, -1
	s_add_i32 s18, 0, 0x10000
	s_cmp_eq_u32 s85, 12
	s_cselect_b32 s15, s22, s15
	s_cselect_b32 s14, s45, s14
	v_add_u32_e32 v137, s18, v141
	s_cselect_b32 vcc_hi, s43, s17
	s_cselect_b32 vcc_lo, s84, s16
	s_add_i32 s21, 0, 0x14000
	ds_read_b128 v[146:149], v137
	ds_read_b128 v[150:153], v137 offset:1024
	ds_read_b128 v[154:157], v137 offset:2048
	ds_read_b128 v[158:161], v137 offset:3072
	v_add_u32_e32 v137, s21, v141
	ds_read_b128 v[162:165], v137
	ds_read_b128 v[166:169], v137 offset:1024
	ds_read_b128 v[170:173], v137 offset:2048
	ds_read_b128 v[174:177], v137 offset:3072
	v_lshl_add_u64 v[138:139], s[60:61], 0, v[184:185]
	s_add_i32 m0, s25, 0xc000
	ds_read_b128 v[178:181], v145
	ds_read_b128 v[194:197], v145 offset:1024
	ds_read_b128 v[198:201], v145 offset:2048
	ds_read_b128 v[202:205], v145 offset:3072
	ds_read_b128 v[206:209], v145 offset:4096
	ds_read_b128 v[210:213], v145 offset:5120
	ds_read_b128 v[214:217], v145 offset:6144
	ds_read_b128 v[218:221], v145 offset:7168
	global_load_lds_dwordx4 v[138:139], off
	v_lshl_add_u64 v[138:139], v[138:139], 0, s[34:35]
	s_add_i32 m0, s25, 0xe000
	s_nop 0
	global_load_lds_dwordx4 v[138:139], off
	s_cmp_eq_u32 s101, 0
	s_cbranch_scc1 .Lbw1_0s
	s_waitcnt vmcnt(18)
	s_branch .Lbw1_0d

.Lbw1_0d:
	s_waitcnt lgkmcnt(0)
	s_barrier
	s_setprio 1
	s_waitcnt lgkmcnt(0)
	v_mfma_f32_16x16x32_bf16 v[124:127], v[146:149], v[178:181], 0
	v_mfma_f32_16x16x32_bf16 v[120:123], v[154:157], v[178:181], 0
	v_mfma_f32_16x16x32_bf16 v[112:115], v[146:149], v[198:201], 0
	v_mfma_f32_16x16x32_bf16 v[104:107], v[154:157], v[198:201], 0
	v_mfma_f32_16x16x32_bf16 v[96:99], v[146:149], v[206:209], 0
	v_mfma_f32_16x16x32_bf16 v[88:91], v[154:157], v[206:209], 0
	v_mfma_f32_16x16x32_bf16 v[80:83], v[146:149], v[214:217], 0
	v_mfma_f32_16x16x32_bf16 v[72:75], v[154:157], v[214:217], 0
	v_mfma_f32_16x16x32_bf16 v[124:127], v[150:153], v[194:197], v[124:127]
	v_mfma_f32_16x16x32_bf16 v[120:123], v[158:161], v[194:197], v[120:123]
	v_mfma_f32_16x16x32_bf16 v[112:115], v[150:153], v[202:205], v[112:115]
	v_mfma_f32_16x16x32_bf16 v[104:107], v[158:161], v[202:205], v[104:107]
	v_mfma_f32_16x16x32_bf16 v[96:99], v[150:153], v[210:213], v[96:99]
	v_mfma_f32_16x16x32_bf16 v[88:91], v[158:161], v[210:213], v[88:91]
	v_mfma_f32_16x16x32_bf16 v[80:83], v[150:153], v[218:221], v[80:83]
	v_mfma_f32_16x16x32_bf16 v[72:75], v[158:161], v[218:221], v[72:75]
	s_setprio 0
	s_setprio 1
	v_mfma_f32_16x16x32_bf16 v[116:119], v[162:165], v[178:181], 0
	v_mfma_f32_16x16x32_bf16 v[108:111], v[170:173], v[178:181], 0
	v_mfma_f32_16x16x32_bf16 v[100:103], v[162:165], v[198:201], 0
	v_mfma_f32_16x16x32_bf16 v[92:95], v[170:173], v[198:201], 0
	v_mfma_f32_16x16x32_bf16 v[84:87], v[162:165], v[206:209], 0
	v_mfma_f32_16x16x32_bf16 v[76:79], v[170:173], v[206:209], 0
	v_mfma_f32_16x16x32_bf16 v[68:71], v[162:165], v[214:217], 0
	v_mfma_f32_16x16x32_bf16 v[64:67], v[170:173], v[214:217], 0
	v_mfma_f32_16x16x32_bf16 v[116:119], v[166:169], v[194:197], v[116:119]
	v_mfma_f32_16x16x32_bf16 v[108:111], v[174:177], v[194:197], v[108:111]
	v_mfma_f32_16x16x32_bf16 v[100:103], v[166:169], v[202:205], v[100:103]
	v_mfma_f32_16x16x32_bf16 v[92:95], v[174:177], v[202:205], v[92:95]
	v_mfma_f32_16x16x32_bf16 v[84:87], v[166:169], v[210:213], v[84:87]
	v_mfma_f32_16x16x32_bf16 v[76:79], v[174:177], v[210:213], v[76:79]
	v_mfma_f32_16x16x32_bf16 v[68:71], v[166:169], v[218:221], v[68:71]
	v_mfma_f32_16x16x32_bf16 v[64:67], v[174:177], v[218:221], v[64:67]
	s_setprio 0
	s_barrier
	s_add_i32 s18, s18, s23
	v_lshl_add_u64 v[138:139], vcc, 0, v[128:129]
	s_mov_b32 m0, s18
	ds_read_b128 v[178:181], v145 offset:16384
	ds_read_b128 v[194:197], v145 offset:17408
	ds_read_b128 v[198:201], v145 offset:18432
	ds_read_b128 v[202:205], v145 offset:19456
	ds_read_b128 v[206:209], v145 offset:20480
	ds_read_b128 v[210:213], v145 offset:21504
	ds_read_b128 v[214:217], v145 offset:22528
	ds_read_b128 v[218:221], v145 offset:23552
	global_load_lds_dwordx4 v[138:139], off
	v_lshl_add_u64 v[182:183], v[138:139], 0, s[34:35]
	s_add_i32 m0, s18, 0x2000
	s_add_i32 s18, s21, s23
	global_load_lds_dwordx4 v[182:183], off
	v_lshl_add_u64 v[182:183], v[138:139], 0, s[92:93]
	s_mov_b32 m0, s18
	s_nop 0
	global_load_lds_dwordx4 v[182:183], off
	v_lshl_add_u64 v[182:183], v[138:139], 0, s[52:53]
	s_add_i32 m0, s18, 0x2000
	s_nop 0
	global_load_lds_dwordx4 v[182:183], off
	v_lshl_add_u64 v[182:183], s[14:15], 0, v[130:131]
	s_mov_b32 m0, s25
	v_lshl_add_u64 v[186:187], v[182:183], 0, s[34:35]
	global_load_lds_dwordx4 v[182:183], off
	s_mov_b32 m0, s26
	s_nop 0
	global_load_lds_dwordx4 v[186:187], off
	s_cmp_eq_u32 s101, 0
	s_cbranch_scc1 .Lbw1_1s
	s_waitcnt vmcnt(22)
	s_branch .Lbw1_1d

.Lbw1_1d:
	s_waitcnt lgkmcnt(0)
	s_barrier
	s_setprio 1
	s_waitcnt lgkmcnt(0)
	v_mfma_f32_16x16x32_bf16 v[60:63], v[146:149], v[178:181], 0
	v_mfma_f32_16x16x32_bf16 v[56:59], v[154:157], v[178:181], 0
	v_mfma_f32_16x16x32_bf16 v[48:51], v[146:149], v[198:201], 0
	v_mfma_f32_16x16x32_bf16 v[40:43], v[154:157], v[198:201], 0
	v_mfma_f32_16x16x32_bf16 v[32:35], v[146:149], v[206:209], 0
	v_mfma_f32_16x16x32_bf16 v[24:27], v[154:157], v[206:209], 0
	v_mfma_f32_16x16x32_bf16 v[16:19], v[146:149], v[214:217], 0
	v_mfma_f32_16x16x32_bf16 v[8:11], v[154:157], v[214:217], 0
	v_mfma_f32_16x16x32_bf16 v[60:63], v[150:153], v[194:197], v[60:63]
	v_mfma_f32_16x16x32_bf16 v[56:59], v[158:161], v[194:197], v[56:59]
	v_mfma_f32_16x16x32_bf16 v[48:51], v[150:153], v[202:205], v[48:51]
	v_mfma_f32_16x16x32_bf16 v[40:43], v[158:161], v[202:205], v[40:43]
	v_mfma_f32_16x16x32_bf16 v[32:35], v[150:153], v[210:213], v[32:35]
	v_mfma_f32_16x16x32_bf16 v[24:27], v[158:161], v[210:213], v[24:27]
	v_mfma_f32_16x16x32_bf16 v[16:19], v[150:153], v[218:221], v[16:19]
	v_mfma_f32_16x16x32_bf16 v[8:11], v[158:161], v[218:221], v[8:11]
	s_setprio 0
	s_setprio 1
	v_mfma_f32_16x16x32_bf16 v[52:55], v[162:165], v[178:181], 0
	v_mfma_f32_16x16x32_bf16 v[44:47], v[170:173], v[178:181], 0
	v_mfma_f32_16x16x32_bf16 v[36:39], v[162:165], v[198:201], 0
	v_mfma_f32_16x16x32_bf16 v[28:31], v[170:173], v[198:201], 0
	v_mfma_f32_16x16x32_bf16 v[20:23], v[162:165], v[206:209], 0
	v_mfma_f32_16x16x32_bf16 v[12:15], v[170:173], v[206:209], 0
	v_mfma_f32_16x16x32_bf16 v[4:7], v[162:165], v[214:217], 0
	v_mfma_f32_16x16x32_bf16 v[0:3], v[170:173], v[214:217], 0
	v_mfma_f32_16x16x32_bf16 v[52:55], v[166:169], v[194:197], v[52:55]
	v_mfma_f32_16x16x32_bf16 v[44:47], v[174:177], v[194:197], v[44:47]
	v_mfma_f32_16x16x32_bf16 v[36:39], v[166:169], v[202:205], v[36:39]
	v_mfma_f32_16x16x32_bf16 v[28:31], v[174:177], v[202:205], v[28:31]
	v_mfma_f32_16x16x32_bf16 v[20:23], v[166:169], v[210:213], v[20:23]
	v_mfma_f32_16x16x32_bf16 v[12:15], v[174:177], v[210:213], v[12:15]
	v_mfma_f32_16x16x32_bf16 v[4:7], v[166:169], v[218:221], v[4:7]
	v_mfma_f32_16x16x32_bf16 v[0:3], v[174:177], v[218:221], v[0:3]
	s_setprio 0
	s_barrier
	s_add_i32 s14, 0, 0x18000
	v_add_u32_e32 v137, s14, v141
	s_add_i32 s15, 0, 0x1c000
	ds_read_b128 v[146:149], v137
	ds_read_b128 v[150:153], v137 offset:1024
	ds_read_b128 v[154:157], v137 offset:2048
	ds_read_b128 v[158:161], v137 offset:3072
	v_add_u32_e32 v137, s15, v141
	ds_read_b128 v[162:165], v137
	ds_read_b128 v[166:169], v137 offset:1024
	ds_read_b128 v[170:173], v137 offset:2048
	ds_read_b128 v[174:177], v137 offset:3072
	s_mov_b32 m0, s27
	v_lshl_add_u64 v[186:187], v[182:183], 0, s[92:93]
	ds_read_b128 v[178:181], v145 offset:32768
	ds_read_b128 v[194:197], v145 offset:33792
	ds_read_b128 v[198:201], v145 offset:34816
	ds_read_b128 v[202:205], v145 offset:35840
	ds_read_b128 v[206:209], v145 offset:36864
	ds_read_b128 v[210:213], v145 offset:37888
	ds_read_b128 v[214:217], v145 offset:38912
	ds_read_b128 v[218:221], v145 offset:39936
	global_load_lds_dwordx4 v[186:187], off
	v_lshl_add_u64 v[186:187], v[182:183], 0, s[52:53]
	s_mov_b32 m0, s28
	s_nop 0
	global_load_lds_dwordx4 v[186:187], off
	s_cmp_eq_u32 s101, 0
	s_cbranch_scc1 .Lbw1_2s
	s_waitcnt vmcnt(18)
	s_branch .Lbw1_2d

.Lbw1_2d:
	s_waitcnt lgkmcnt(0)
	s_barrier
	s_setprio 1
	s_waitcnt lgkmcnt(0)
	v_mfma_f32_16x16x32_bf16 v[124:127], v[146:149], v[178:181], v[124:127]
	v_mfma_f32_16x16x32_bf16 v[120:123], v[154:157], v[178:181], v[120:123]
	v_mfma_f32_16x16x32_bf16 v[112:115], v[146:149], v[198:201], v[112:115]
	v_mfma_f32_16x16x32_bf16 v[104:107], v[154:157], v[198:201], v[104:107]
	v_mfma_f32_16x16x32_bf16 v[96:99], v[146:149], v[206:209], v[96:99]
	v_mfma_f32_16x16x32_bf16 v[88:91], v[154:157], v[206:209], v[88:91]
	v_mfma_f32_16x16x32_bf16 v[80:83], v[146:149], v[214:217], v[80:83]
	v_mfma_f32_16x16x32_bf16 v[72:75], v[154:157], v[214:217], v[72:75]
	v_mfma_f32_16x16x32_bf16 v[124:127], v[150:153], v[194:197], v[124:127]
	v_mfma_f32_16x16x32_bf16 v[120:123], v[158:161], v[194:197], v[120:123]
	v_mfma_f32_16x16x32_bf16 v[112:115], v[150:153], v[202:205], v[112:115]
	v_mfma_f32_16x16x32_bf16 v[104:107], v[158:161], v[202:205], v[104:107]
	v_mfma_f32_16x16x32_bf16 v[96:99], v[150:153], v[210:213], v[96:99]
	v_mfma_f32_16x16x32_bf16 v[88:91], v[158:161], v[210:213], v[88:91]
	v_mfma_f32_16x16x32_bf16 v[80:83], v[150:153], v[218:221], v[80:83]
	v_mfma_f32_16x16x32_bf16 v[72:75], v[158:161], v[218:221], v[72:75]
	s_setprio 0
	s_setprio 1
	v_mfma_f32_16x16x32_bf16 v[116:119], v[162:165], v[178:181], v[116:119]
	v_mfma_f32_16x16x32_bf16 v[108:111], v[170:173], v[178:181], v[108:111]
	v_mfma_f32_16x16x32_bf16 v[100:103], v[162:165], v[198:201], v[100:103]
	v_mfma_f32_16x16x32_bf16 v[92:95], v[170:173], v[198:201], v[92:95]
	v_mfma_f32_16x16x32_bf16 v[84:87], v[162:165], v[206:209], v[84:87]
	v_mfma_f32_16x16x32_bf16 v[76:79], v[170:173], v[206:209], v[76:79]
	v_mfma_f32_16x16x32_bf16 v[68:71], v[162:165], v[214:217], v[68:71]
	v_mfma_f32_16x16x32_bf16 v[64:67], v[170:173], v[214:217], v[64:67]
	v_mfma_f32_16x16x32_bf16 v[116:119], v[166:169], v[194:197], v[116:119]
	v_mfma_f32_16x16x32_bf16 v[108:111], v[174:177], v[194:197], v[108:111]
	v_mfma_f32_16x16x32_bf16 v[100:103], v[166:169], v[202:205], v[100:103]
	v_mfma_f32_16x16x32_bf16 v[92:95], v[174:177], v[202:205], v[92:95]
	v_mfma_f32_16x16x32_bf16 v[84:87], v[166:169], v[210:213], v[84:87]
	v_mfma_f32_16x16x32_bf16 v[76:79], v[174:177], v[210:213], v[76:79]
	v_mfma_f32_16x16x32_bf16 v[68:71], v[166:169], v[218:221], v[68:71]
	v_mfma_f32_16x16x32_bf16 v[64:67], v[174:177], v[218:221], v[64:67]
	s_setprio 0
	s_barrier
	s_add_i32 s14, s14, s23
	v_lshl_add_u64 v[186:187], v[138:139], 0, s[56:57]
	s_mov_b32 m0, s14
	ds_read_b128 v[178:181], v145 offset:49152
	ds_read_b128 v[194:197], v145 offset:50176
	ds_read_b128 v[198:201], v145 offset:51200
	ds_read_b128 v[202:205], v145 offset:52224
	ds_read_b128 v[206:209], v145 offset:53248
	ds_read_b128 v[210:213], v145 offset:54272
	ds_read_b128 v[214:217], v145 offset:55296
	ds_read_b128 v[218:221], v145 offset:56320
	global_load_lds_dwordx4 v[186:187], off
	v_lshl_add_u64 v[186:187], v[138:139], 0, s[96:97]
	s_add_i32 m0, s14, 0x2000
	s_add_i32 s14, s15, s23
	global_load_lds_dwordx4 v[186:187], off
	v_lshl_add_u64 v[186:187], v[138:139], 0, s[88:89]
	s_mov_b32 m0, s14
	v_lshl_add_u64 v[138:139], v[138:139], 0, s[68:69]
	global_load_lds_dwordx4 v[186:187], off
	s_add_i32 m0, s14, 0x2000
	s_nop 0
	global_load_lds_dwordx4 v[138:139], off
	v_lshl_add_u64 v[138:139], v[182:183], 0, s[56:57]
	s_mov_b32 m0, s29
	s_nop 0
	global_load_lds_dwordx4 v[138:139], off
	v_lshl_add_u64 v[138:139], v[182:183], 0, s[96:97]
	s_mov_b32 m0, s30
	s_nop 0
	global_load_lds_dwordx4 v[138:139], off
	s_waitcnt vmcnt(14)
	s_waitcnt lgkmcnt(0)
	s_barrier
	s_setprio 1
	s_waitcnt lgkmcnt(0)
	v_mfma_f32_16x16x32_bf16 v[60:63], v[146:149], v[178:181], v[60:63]
	v_mfma_f32_16x16x32_bf16 v[56:59], v[154:157], v[178:181], v[56:59]
	v_mfma_f32_16x16x32_bf16 v[48:51], v[146:149], v[198:201], v[48:51]
	v_mfma_f32_16x16x32_bf16 v[40:43], v[154:157], v[198:201], v[40:43]
	v_mfma_f32_16x16x32_bf16 v[32:35], v[146:149], v[206:209], v[32:35]
	v_mfma_f32_16x16x32_bf16 v[24:27], v[154:157], v[206:209], v[24:27]
	v_mfma_f32_16x16x32_bf16 v[16:19], v[146:149], v[214:217], v[16:19]
	v_mfma_f32_16x16x32_bf16 v[8:11], v[154:157], v[214:217], v[8:11]
	v_mfma_f32_16x16x32_bf16 v[60:63], v[150:153], v[194:197], v[60:63]
	v_mfma_f32_16x16x32_bf16 v[56:59], v[158:161], v[194:197], v[56:59]
	v_mfma_f32_16x16x32_bf16 v[48:51], v[150:153], v[202:205], v[48:51]
	v_mfma_f32_16x16x32_bf16 v[40:43], v[158:161], v[202:205], v[40:43]
	v_mfma_f32_16x16x32_bf16 v[32:35], v[150:153], v[210:213], v[32:35]
	v_mfma_f32_16x16x32_bf16 v[24:27], v[158:161], v[210:213], v[24:27]
	v_mfma_f32_16x16x32_bf16 v[16:19], v[150:153], v[218:221], v[16:19]
	v_mfma_f32_16x16x32_bf16 v[8:11], v[158:161], v[218:221], v[8:11]
	s_setprio 0
	s_setprio 1
	v_mfma_f32_16x16x32_bf16 v[52:55], v[162:165], v[178:181], v[52:55]
	v_mfma_f32_16x16x32_bf16 v[44:47], v[170:173], v[178:181], v[44:47]
	v_mfma_f32_16x16x32_bf16 v[36:39], v[162:165], v[198:201], v[36:39]
	v_mfma_f32_16x16x32_bf16 v[28:31], v[170:173], v[198:201], v[28:31]
	v_mfma_f32_16x16x32_bf16 v[20:23], v[162:165], v[206:209], v[20:23]
	v_mfma_f32_16x16x32_bf16 v[12:15], v[170:173], v[206:209], v[12:15]
	v_mfma_f32_16x16x32_bf16 v[4:7], v[162:165], v[214:217], v[4:7]
	v_mfma_f32_16x16x32_bf16 v[0:3], v[170:173], v[214:217], v[0:3]
	v_mfma_f32_16x16x32_bf16 v[52:55], v[166:169], v[194:197], v[52:55]
	v_mfma_f32_16x16x32_bf16 v[44:47], v[174:177], v[194:197], v[44:47]
	v_mfma_f32_16x16x32_bf16 v[36:39], v[166:169], v[202:205], v[36:39]
	v_mfma_f32_16x16x32_bf16 v[28:31], v[174:177], v[202:205], v[28:31]
	v_mfma_f32_16x16x32_bf16 v[20:23], v[166:169], v[210:213], v[20:23]
	v_mfma_f32_16x16x32_bf16 v[12:15], v[174:177], v[210:213], v[12:15]
	v_mfma_f32_16x16x32_bf16 v[4:7], v[166:169], v[218:221], v[4:7]
	v_mfma_f32_16x16x32_bf16 v[0:3], v[174:177], v[218:221], v[0:3]
	s_setprio 0
	s_barrier
	s_add_i32 s85, s85, 2
	s_add_u32 s60, s60, 0x100
	s_addc_u32 s61, s61, 0
	s_add_u32 s16, s16, 0x100
	s_addc_u32 s17, s17, 0
	s_cmp_gt_u32 s85, 13

.LBB0_234:
	s_or_b64 exec, exec, s[14:15]
	s_waitcnt lgkmcnt(0)
	s_barrier
	ds_read2_b32 v[148:149], v143 offset1:16
	ds_read2_b32 v[150:151], v143 offset0:32 offset1:48
	ds_read2_b32 v[138:139], v143 offset0:128 offset1:144
	ds_read2_b32 v[136:137], v143 offset0:160 offset1:176
	v_lshl_add_u32 v146, s50, 8, v140
	v_lshl_or_b32 v152, s51, 8, v144
	v_ashrrev_i32_e32 v147, 31, v146
	s_waitcnt lgkmcnt(0)
	v_pk_mul_f32 v[124:125], v[124:125], v[148:149] op_sel_hi:[1,0]
	v_pk_mul_f32 v[120:121], v[120:121], v[148:149] op_sel_hi:[1,0]
	v_ashrrev_i32_e32 v153, 31, v152
	v_pk_mul_f32 v[126:127], v[126:127], v[148:149] op_sel_hi:[1,0]
	v_pk_mul_f32 v[154:155], v[122:123], v[148:149] op_sel_hi:[1,0]
	v_cvt_pk_bf16_f32 v122, v124, v125
	v_cvt_pk_bf16_f32 v123, v126, v127
	v_cvt_pk_bf16_f32 v124, v120, v121
	v_lshlrev_b64 v[120:121], 11, v[146:147]
	v_lshl_add_u64 v[120:121], s[72:73], 0, v[120:121]
	v_lshlrev_b64 v[126:127], 1, v[152:153]
	v_lshl_add_u64 v[120:121], v[120:121], 0, v[126:127]
	v_cvt_pk_bf16_f32 v125, v154, v155
	global_store_dwordx4 v[120:121], v[122:125], off
	v_pk_mul_f32 v[116:117], v[116:117], v[148:149] op_sel_hi:[1,0]
	v_pk_mul_f32 v[118:119], v[118:119], v[148:149] op_sel_hi:[1,0]
	v_pk_mul_f32 v[122:123], v[110:111], v[148:149] op_sel_hi:[1,0]
	v_pk_mul_f32 v[110:111], v[108:109], v[148:149] op_sel_hi:[1,0]
	v_cvt_pk_bf16_f32 v108, v116, v117
	v_cvt_pk_bf16_f32 v109, v118, v119
	v_pk_mul_f32 v[96:97], v[96:97], v[150:151] op_sel_hi:[1,0]
	v_cvt_pk_bf16_f32 v110, v110, v111
	v_cvt_pk_bf16_f32 v111, v122, v123
	global_store_dwordx4 v[120:121], v[108:111], off offset:256
	v_pk_mul_f32 v[84:85], v[84:85], v[150:151] op_sel_hi:[1,0]
	v_pk_mul_f32 v[86:87], v[86:87], v[150:151] op_sel_hi:[1,0]
	v_or_b32_e32 v108, 16, v146
	v_ashrrev_i32_e32 v109, 31, v108
	v_lshlrev_b64 v[108:109], 11, v[108:109]
	v_mov_b32_e32 v110, v149
	v_lshl_add_u64 v[108:109], s[72:73], 0, v[108:109]
	v_pk_mul_f32 v[114:115], v[114:115], v[110:111] op_sel_hi:[1,0]
	v_pk_mul_f32 v[112:113], v[112:113], v[110:111] op_sel_hi:[1,0]
	v_pk_mul_f32 v[116:117], v[106:107], v[110:111] op_sel_hi:[1,0]
	v_pk_mul_f32 v[106:107], v[104:105], v[110:111] op_sel_hi:[1,0]
	v_cvt_pk_bf16_f32 v104, v112, v113
	v_cvt_pk_bf16_f32 v105, v114, v115
	v_lshl_add_u64 v[108:109], v[108:109], 0, v[126:127]
	v_cvt_pk_bf16_f32 v106, v106, v107
	v_cvt_pk_bf16_f32 v107, v116, v117
	global_store_dwordx4 v[108:109], v[104:107], off
	v_pk_mul_f32 v[100:101], v[100:101], v[110:111] op_sel_hi:[1,0]
	v_pk_mul_f32 v[102:103], v[102:103], v[110:111] op_sel_hi:[1,0]
	v_pk_mul_f32 v[104:105], v[94:95], v[110:111] op_sel_hi:[1,0]
	v_pk_mul_f32 v[94:95], v[92:93], v[110:111] op_sel_hi:[1,0]
	v_cvt_pk_bf16_f32 v92, v100, v101
	v_cvt_pk_bf16_f32 v93, v102, v103
	v_pk_mul_f32 v[62:63], v[62:63], v[138:139] op_sel_hi:[1,0]
	v_cvt_pk_bf16_f32 v94, v94, v95
	v_cvt_pk_bf16_f32 v95, v104, v105
	global_store_dwordx4 v[108:109], v[92:95], off offset:256
	s_mov_b32 s14, 0x40000
	v_pk_mul_f32 v[60:61], v[60:61], v[138:139] op_sel_hi:[1,0]
	v_or_b32_e32 v92, 32, v146
	v_ashrrev_i32_e32 v93, 31, v92
	v_lshlrev_b64 v[92:93], 11, v[92:93]
	v_lshl_add_u64 v[92:93], s[72:73], 0, v[92:93]
	v_pk_mul_f32 v[94:95], v[98:99], v[150:151] op_sel_hi:[1,0]
	v_pk_mul_f32 v[98:99], v[90:91], v[150:151] op_sel_hi:[1,0]
	v_pk_mul_f32 v[90:91], v[88:89], v[150:151] op_sel_hi:[1,0]
	v_cvt_pk_bf16_f32 v88, v96, v97
	v_cvt_pk_bf16_f32 v89, v94, v95
	v_lshl_add_u64 v[92:93], v[92:93], 0, v[126:127]
	v_cvt_pk_bf16_f32 v90, v90, v91
	v_cvt_pk_bf16_f32 v91, v98, v99
	global_store_dwordx4 v[92:93], v[88:91], off
	v_pk_mul_f32 v[52:53], v[52:53], v[138:139] op_sel_hi:[1,0]
	v_pk_mul_f32 v[54:55], v[54:55], v[138:139] op_sel_hi:[1,0]
	v_pk_mul_f32 v[88:89], v[78:79], v[150:151] op_sel_hi:[1,0]
	v_pk_mul_f32 v[78:79], v[76:77], v[150:151] op_sel_hi:[1,0]
	v_cvt_pk_bf16_f32 v76, v84, v85
	v_cvt_pk_bf16_f32 v77, v86, v87
	v_pk_mul_f32 v[20:21], v[20:21], v[136:137] op_sel_hi:[1,0]
	v_cvt_pk_bf16_f32 v78, v78, v79
	v_cvt_pk_bf16_f32 v79, v88, v89
	global_store_dwordx4 v[92:93], v[76:79], off offset:256
	v_pk_mul_f32 v[22:23], v[22:23], v[136:137] op_sel_hi:[1,0]
	s_nop 0
	v_or_b32_e32 v76, 48, v146
	v_ashrrev_i32_e32 v77, 31, v76
	v_lshlrev_b64 v[76:77], 11, v[76:77]
	v_mov_b32_e32 v78, v151
	v_lshl_add_u64 v[76:77], s[72:73], 0, v[76:77]
	v_pk_mul_f32 v[82:83], v[82:83], v[78:79] op_sel_hi:[1,0]
	v_pk_mul_f32 v[80:81], v[80:81], v[78:79] op_sel_hi:[1,0]
	v_pk_mul_f32 v[84:85], v[74:75], v[78:79] op_sel_hi:[1,0]
	v_pk_mul_f32 v[74:75], v[72:73], v[78:79] op_sel_hi:[1,0]
	v_cvt_pk_bf16_f32 v72, v80, v81
	v_cvt_pk_bf16_f32 v73, v82, v83
	v_lshl_add_u64 v[76:77], v[76:77], 0, v[126:127]
	v_cvt_pk_bf16_f32 v74, v74, v75
	v_cvt_pk_bf16_f32 v75, v84, v85
	global_store_dwordx4 v[76:77], v[72:75], off
	v_pk_mul_f32 v[70:71], v[70:71], v[78:79] op_sel_hi:[1,0]
	v_pk_mul_f32 v[68:69], v[68:69], v[78:79] op_sel_hi:[1,0]
	v_pk_mul_f32 v[72:73], v[66:67], v[78:79] op_sel_hi:[1,0]
	v_pk_mul_f32 v[66:67], v[64:65], v[78:79] op_sel_hi:[1,0]
	v_cvt_pk_bf16_f32 v64, v68, v69
	v_cvt_pk_bf16_f32 v65, v70, v71
	s_nop 0
	v_cvt_pk_bf16_f32 v66, v66, v67
	v_cvt_pk_bf16_f32 v67, v72, v73
	global_store_dwordx4 v[76:77], v[64:67], off offset:256
	s_nop 1
	v_pk_mul_f32 v[64:65], v[58:59], v[138:139] op_sel_hi:[1,0]
	v_pk_mul_f32 v[58:59], v[56:57], v[138:139] op_sel_hi:[1,0]
	v_cvt_pk_bf16_f32 v56, v60, v61
	v_cvt_pk_bf16_f32 v57, v62, v63
	v_add_co_u32_e32 v62, vcc, s14, v120
	v_cvt_pk_bf16_f32 v58, v58, v59
	v_cvt_pk_bf16_f32 v59, v64, v65
	v_lshl_add_u64 v[60:61], v[120:121], 0, s[92:93]
	s_nop 0
	v_addc_co_u32_e32 v63, vcc, 0, v121, vcc
	global_store_dwordx4 v[62:63], v[56:59], off
	s_mov_b64 s[14:15], 0x48000
	s_nop 0
	v_pk_mul_f32 v[56:57], v[46:47], v[138:139] op_sel_hi:[1,0]
	v_pk_mul_f32 v[46:47], v[44:45], v[138:139] op_sel_hi:[1,0]
	v_cvt_pk_bf16_f32 v44, v52, v53
	v_cvt_pk_bf16_f32 v45, v54, v55
	s_nop 0
	v_cvt_pk_bf16_f32 v46, v46, v47
	v_cvt_pk_bf16_f32 v47, v56, v57
	global_store_dwordx4 v[60:61], v[44:47], off offset:256
	s_nop 1
	v_mov_b32_e32 v44, v139
	v_pk_mul_f32 v[46:47], v[50:51], v[44:45] op_sel_hi:[1,0]
	v_pk_mul_f32 v[48:49], v[48:49], v[44:45] op_sel_hi:[1,0]
	v_pk_mul_f32 v[50:51], v[42:43], v[44:45] op_sel_hi:[1,0]
	v_pk_mul_f32 v[42:43], v[40:41], v[44:45] op_sel_hi:[1,0]
	v_cvt_pk_bf16_f32 v40, v48, v49
	v_cvt_pk_bf16_f32 v41, v46, v47
	v_lshl_add_u64 v[46:47], v[120:121], 0, s[14:15]
	s_mov_b32 s14, 0x48000
	v_add_co_u32_e32 v48, vcc, s14, v120
	v_cvt_pk_bf16_f32 v42, v42, v43
	v_cvt_pk_bf16_f32 v43, v50, v51
	v_pk_mul_f32 v[38:39], v[38:39], v[44:45] op_sel_hi:[1,0]
	s_nop 0
	v_addc_co_u32_e32 v49, vcc, 0, v121, vcc
	global_store_dwordx4 v[48:49], v[40:43], off
	v_pk_mul_f32 v[36:37], v[36:37], v[44:45] op_sel_hi:[1,0]
	s_mov_b64 s[14:15], 0x50000
	v_pk_mul_f32 v[40:41], v[30:31], v[44:45] op_sel_hi:[1,0]
	v_pk_mul_f32 v[30:31], v[28:29], v[44:45] op_sel_hi:[1,0]
	v_cvt_pk_bf16_f32 v28, v36, v37
	v_cvt_pk_bf16_f32 v29, v38, v39
	s_nop 0
	v_cvt_pk_bf16_f32 v30, v30, v31
	v_cvt_pk_bf16_f32 v31, v40, v41
	global_store_dwordx4 v[46:47], v[28:31], off offset:256
	s_nop 1
	v_pk_mul_f32 v[28:29], v[34:35], v[136:137] op_sel_hi:[1,0]
	v_pk_mul_f32 v[30:31], v[32:33], v[136:137] op_sel_hi:[1,0]
	v_pk_mul_f32 v[32:33], v[26:27], v[136:137] op_sel_hi:[1,0]
	v_pk_mul_f32 v[26:27], v[24:25], v[136:137] op_sel_hi:[1,0]
	v_cvt_pk_bf16_f32 v24, v30, v31
	v_cvt_pk_bf16_f32 v25, v28, v29
	v_lshl_add_u64 v[28:29], v[120:121], 0, s[14:15]
	s_mov_b32 s14, 0x50000
	v_add_co_u32_e32 v30, vcc, s14, v120
	v_cvt_pk_bf16_f32 v26, v26, v27
	v_cvt_pk_bf16_f32 v27, v32, v33
	s_mov_b32 s14, 0x58000
	s_nop 0
	v_addc_co_u32_e32 v31, vcc, 0, v121, vcc
	global_store_dwordx4 v[30:31], v[24:27], off
	s_nop 1
	v_pk_mul_f32 v[24:25], v[14:15], v[136:137] op_sel_hi:[1,0]
	v_pk_mul_f32 v[14:15], v[12:13], v[136:137] op_sel_hi:[1,0]
	v_cvt_pk_bf16_f32 v12, v20, v21
	v_cvt_pk_bf16_f32 v13, v22, v23
	s_nop 0
	v_cvt_pk_bf16_f32 v14, v14, v15
	v_cvt_pk_bf16_f32 v15, v24, v25
	global_store_dwordx4 v[28:29], v[12:15], off offset:256
	s_nop 1
	v_mov_b32_e32 v12, v137
	v_pk_mul_f32 v[16:17], v[16:17], v[12:13] op_sel_hi:[1,0]
	v_pk_mul_f32 v[14:15], v[18:19], v[12:13] op_sel_hi:[1,0]
	v_pk_mul_f32 v[18:19], v[10:11], v[12:13] op_sel_hi:[1,0]
	v_pk_mul_f32 v[10:11], v[8:9], v[12:13] op_sel_hi:[1,0]
	v_cvt_pk_bf16_f32 v8, v16, v17
	v_add_co_u32_e32 v16, vcc, s14, v120
	v_cvt_pk_bf16_f32 v9, v14, v15
	v_cvt_pk_bf16_f32 v10, v10, v11
	v_cvt_pk_bf16_f32 v11, v18, v19
	v_lshl_add_u64 v[14:15], v[120:121], 0, s[2:3]
	s_nop 0
	v_addc_co_u32_e32 v17, vcc, 0, v121, vcc
	global_store_dwordx4 v[16:17], v[8:11], off
	s_andn2_b64 vcc, exec, s[38:39]
	s_mov_b64 s[14:15], -1
	v_pk_mul_f32 v[8:9], v[2:3], v[12:13] op_sel_hi:[1,0]
	v_pk_mul_f32 v[2:3], v[0:1], v[12:13] op_sel_hi:[1,0]
	v_pk_mul_f32 v[6:7], v[6:7], v[12:13] op_sel_hi:[1,0]
	v_pk_mul_f32 v[4:5], v[4:5], v[12:13] op_sel_hi:[1,0]
	s_nop 0
	v_cvt_pk_bf16_f32 v0, v4, v5
	v_cvt_pk_bf16_f32 v1, v6, v7
	v_cvt_pk_bf16_f32 v2, v2, v3
	v_cvt_pk_bf16_f32 v3, v8, v9
	global_store_dwordx4 v[14:15], v[0:3], off offset:256
	s_cbranch_vccnz .LBB0_225
	s_lshl_b32 s14, s44, 8
	s_ashr_i32 s15, s14, 31
	v_lshl_add_u64 v[0:1], s[14:15], 2, v[132:133]
	global_load_dword v136, v[0:1], off
	s_mov_b32 s101, 1
	s_andn2_b64 vcc, exec, s[12:13]
	s_cbranch_vccnz .LBB0_224
	s_mov_b32 s98, 1
	s_branch .LBB0_224

.Lnostb2:
	s_add_u32 s14, s60, 0xfffc0080
	s_addc_u32 s15, s61, -1
	s_add_i32 s18, 0, 0x10000
	s_cmp_eq_u32 s85, 12
	s_cselect_b32 s15, s22, s15
	s_cselect_b32 s14, s45, s14
	s_waitcnt lgkmcnt(0)
	v_add_u32_e32 v137, s18, v149
	s_cselect_b32 vcc_hi, s43, s17
	s_cselect_b32 vcc_lo, s84, s16
	s_add_i32 s21, 0, 0x14000
	ds_read_b128 v[138:141], v137
	ds_read_b128 v[142:145], v137 offset:1024
	ds_read_b128 v[154:157], v137 offset:2048
	ds_read_b128 v[158:161], v137 offset:3072
	v_add_u32_e32 v137, s21, v149
	ds_read_b128 v[162:165], v137
	ds_read_b128 v[166:169], v137 offset:1024
	ds_read_b128 v[170:173], v137 offset:2048
	ds_read_b128 v[174:177], v137 offset:3072
	v_lshl_add_u64 v[146:147], s[60:61], 0, v[134:135]
	s_add_i32 m0, s25, 0xc000
	ds_read_b128 v[178:181], v153
	ds_read_b128 v[194:197], v153 offset:1024
	ds_read_b128 v[198:201], v153 offset:2048
	ds_read_b128 v[202:205], v153 offset:3072
	ds_read_b128 v[206:209], v153 offset:4096
	ds_read_b128 v[210:213], v153 offset:5120
	ds_read_b128 v[214:217], v153 offset:6144
	ds_read_b128 v[218:221], v153 offset:7168
	global_load_lds_dwordx4 v[146:147], off
	v_lshl_add_u64 v[146:147], v[146:147], 0, s[34:35]
	s_add_i32 m0, s25, 0xe000
	s_nop 0
	global_load_lds_dwordx4 v[146:147], off
	s_cmp_eq_u32 s101, 0
	s_cbranch_scc1 .Lbw2_0s
	s_waitcnt vmcnt(18)
	s_branch .Lbw2_0d

.Lbw2_0d:
	s_waitcnt lgkmcnt(0)
	s_barrier
	s_setprio 1
	s_waitcnt lgkmcnt(0)
	v_mfma_f32_16x16x32_bf16 v[124:127], v[138:141], v[178:181], 0
	v_mfma_f32_16x16x32_bf16 v[120:123], v[154:157], v[178:181], 0
	v_mfma_f32_16x16x32_bf16 v[108:111], v[138:141], v[198:201], 0
	v_mfma_f32_16x16x32_bf16 v[104:107], v[154:157], v[198:201], 0
	v_mfma_f32_16x16x32_bf16 v[96:99], v[138:141], v[206:209], 0
	v_mfma_f32_16x16x32_bf16 v[88:91], v[154:157], v[206:209], 0
	v_mfma_f32_16x16x32_bf16 v[80:83], v[138:141], v[214:217], 0
	v_mfma_f32_16x16x32_bf16 v[72:75], v[154:157], v[214:217], 0
	v_mfma_f32_16x16x32_bf16 v[124:127], v[142:145], v[194:197], v[124:127]
	v_mfma_f32_16x16x32_bf16 v[120:123], v[158:161], v[194:197], v[120:123]
	v_mfma_f32_16x16x32_bf16 v[108:111], v[142:145], v[202:205], v[108:111]
	v_mfma_f32_16x16x32_bf16 v[104:107], v[158:161], v[202:205], v[104:107]
	v_mfma_f32_16x16x32_bf16 v[96:99], v[142:145], v[210:213], v[96:99]
	v_mfma_f32_16x16x32_bf16 v[88:91], v[158:161], v[210:213], v[88:91]
	v_mfma_f32_16x16x32_bf16 v[80:83], v[142:145], v[218:221], v[80:83]
	v_mfma_f32_16x16x32_bf16 v[72:75], v[158:161], v[218:221], v[72:75]
	s_setprio 0
	s_setprio 1
	v_mfma_f32_16x16x32_bf16 v[116:119], v[162:165], v[178:181], 0
	v_mfma_f32_16x16x32_bf16 v[112:115], v[170:173], v[178:181], 0
	v_mfma_f32_16x16x32_bf16 v[100:103], v[162:165], v[198:201], 0
	v_mfma_f32_16x16x32_bf16 v[92:95], v[170:173], v[198:201], 0
	v_mfma_f32_16x16x32_bf16 v[84:87], v[162:165], v[206:209], 0
	v_mfma_f32_16x16x32_bf16 v[76:79], v[170:173], v[206:209], 0
	v_mfma_f32_16x16x32_bf16 v[68:71], v[162:165], v[214:217], 0
	v_mfma_f32_16x16x32_bf16 v[64:67], v[170:173], v[214:217], 0
	v_mfma_f32_16x16x32_bf16 v[116:119], v[166:169], v[194:197], v[116:119]
	v_mfma_f32_16x16x32_bf16 v[112:115], v[174:177], v[194:197], v[112:115]
	v_mfma_f32_16x16x32_bf16 v[100:103], v[166:169], v[202:205], v[100:103]
	v_mfma_f32_16x16x32_bf16 v[92:95], v[174:177], v[202:205], v[92:95]
	v_mfma_f32_16x16x32_bf16 v[84:87], v[166:169], v[210:213], v[84:87]
	v_mfma_f32_16x16x32_bf16 v[76:79], v[174:177], v[210:213], v[76:79]
	v_mfma_f32_16x16x32_bf16 v[68:71], v[166:169], v[218:221], v[68:71]
	v_mfma_f32_16x16x32_bf16 v[64:67], v[174:177], v[218:221], v[64:67]
	s_setprio 0
	s_barrier
	s_add_i32 s18, s18, s23
	v_lshl_add_u64 v[146:147], vcc, 0, v[128:129]
	s_mov_b32 m0, s18
	ds_read_b128 v[178:181], v153 offset:16384
	ds_read_b128 v[194:197], v153 offset:17408
	ds_read_b128 v[198:201], v153 offset:18432
	ds_read_b128 v[202:205], v153 offset:19456
	ds_read_b128 v[206:209], v153 offset:20480
	ds_read_b128 v[210:213], v153 offset:21504
	ds_read_b128 v[214:217], v153 offset:22528
	ds_read_b128 v[218:221], v153 offset:23552
	global_load_lds_dwordx4 v[146:147], off
	v_lshl_add_u64 v[182:183], v[146:147], 0, s[34:35]
	s_add_i32 m0, s18, 0x2000
	s_add_i32 s18, s21, s23
	global_load_lds_dwordx4 v[182:183], off
	v_lshl_add_u64 v[182:183], v[146:147], 0, s[92:93]
	s_mov_b32 m0, s18
	s_nop 0
	global_load_lds_dwordx4 v[182:183], off
	v_lshl_add_u64 v[182:183], v[146:147], 0, s[52:53]
	s_add_i32 m0, s18, 0x2000
	s_nop 0
	global_load_lds_dwordx4 v[182:183], off
	v_lshl_add_u64 v[182:183], s[14:15], 0, v[130:131]
	s_mov_b32 m0, s25
	v_lshl_add_u64 v[186:187], v[182:183], 0, s[34:35]
	global_load_lds_dwordx4 v[182:183], off
	s_mov_b32 m0, s26
	s_nop 0
	global_load_lds_dwordx4 v[186:187], off
	s_cmp_eq_u32 s101, 0
	s_cbranch_scc1 .Lbw2_1s
	s_waitcnt vmcnt(22)
	s_branch .Lbw2_1d

.Lbw2_1d:
	s_waitcnt lgkmcnt(0)
	s_barrier
	s_setprio 1
	s_waitcnt lgkmcnt(0)
	v_mfma_f32_16x16x32_bf16 v[60:63], v[138:141], v[178:181], 0
	v_mfma_f32_16x16x32_bf16 v[56:59], v[154:157], v[178:181], 0
	v_mfma_f32_16x16x32_bf16 v[48:51], v[138:141], v[198:201], 0
	v_mfma_f32_16x16x32_bf16 v[40:43], v[154:157], v[198:201], 0
	v_mfma_f32_16x16x32_bf16 v[32:35], v[138:141], v[206:209], 0
	v_mfma_f32_16x16x32_bf16 v[24:27], v[154:157], v[206:209], 0
	v_mfma_f32_16x16x32_bf16 v[16:19], v[138:141], v[214:217], 0
	v_mfma_f32_16x16x32_bf16 v[8:11], v[154:157], v[214:217], 0
	v_mfma_f32_16x16x32_bf16 v[60:63], v[142:145], v[194:197], v[60:63]
	v_mfma_f32_16x16x32_bf16 v[56:59], v[158:161], v[194:197], v[56:59]
	v_mfma_f32_16x16x32_bf16 v[48:51], v[142:145], v[202:205], v[48:51]
	v_mfma_f32_16x16x32_bf16 v[40:43], v[158:161], v[202:205], v[40:43]
	v_mfma_f32_16x16x32_bf16 v[32:35], v[142:145], v[210:213], v[32:35]
	v_mfma_f32_16x16x32_bf16 v[24:27], v[158:161], v[210:213], v[24:27]
	v_mfma_f32_16x16x32_bf16 v[16:19], v[142:145], v[218:221], v[16:19]
	v_mfma_f32_16x16x32_bf16 v[8:11], v[158:161], v[218:221], v[8:11]
	s_setprio 0
	s_setprio 1
	v_mfma_f32_16x16x32_bf16 v[52:55], v[162:165], v[178:181], 0
	v_mfma_f32_16x16x32_bf16 v[44:47], v[170:173], v[178:181], 0
	v_mfma_f32_16x16x32_bf16 v[36:39], v[162:165], v[198:201], 0
	v_mfma_f32_16x16x32_bf16 v[28:31], v[170:173], v[198:201], 0
	v_mfma_f32_16x16x32_bf16 v[20:23], v[162:165], v[206:209], 0
	v_mfma_f32_16x16x32_bf16 v[12:15], v[170:173], v[206:209], 0
	v_mfma_f32_16x16x32_bf16 v[4:7], v[162:165], v[214:217], 0
	v_mfma_f32_16x16x32_bf16 v[0:3], v[170:173], v[214:217], 0
	v_mfma_f32_16x16x32_bf16 v[52:55], v[166:169], v[194:197], v[52:55]
	v_mfma_f32_16x16x32_bf16 v[44:47], v[174:177], v[194:197], v[44:47]
	v_mfma_f32_16x16x32_bf16 v[36:39], v[166:169], v[202:205], v[36:39]
	v_mfma_f32_16x16x32_bf16 v[28:31], v[174:177], v[202:205], v[28:31]
	v_mfma_f32_16x16x32_bf16 v[20:23], v[166:169], v[210:213], v[20:23]
	v_mfma_f32_16x16x32_bf16 v[12:15], v[174:177], v[210:213], v[12:15]
	v_mfma_f32_16x16x32_bf16 v[4:7], v[166:169], v[218:221], v[4:7]
	v_mfma_f32_16x16x32_bf16 v[0:3], v[174:177], v[218:221], v[0:3]
	s_setprio 0
	s_barrier
	s_add_i32 s14, 0, 0x18000
	v_add_u32_e32 v137, s14, v149
	s_add_i32 s15, 0, 0x1c000
	ds_read_b128 v[138:141], v137
	ds_read_b128 v[142:145], v137 offset:1024
	ds_read_b128 v[154:157], v137 offset:2048
	ds_read_b128 v[158:161], v137 offset:3072
	v_add_u32_e32 v137, s15, v149
	ds_read_b128 v[162:165], v137
	ds_read_b128 v[166:169], v137 offset:1024
	ds_read_b128 v[170:173], v137 offset:2048
	ds_read_b128 v[174:177], v137 offset:3072
	s_mov_b32 m0, s27
	v_lshl_add_u64 v[186:187], v[182:183], 0, s[92:93]
	ds_read_b128 v[178:181], v153 offset:32768
	ds_read_b128 v[194:197], v153 offset:33792
	ds_read_b128 v[198:201], v153 offset:34816
	ds_read_b128 v[202:205], v153 offset:35840
	ds_read_b128 v[206:209], v153 offset:36864
	ds_read_b128 v[210:213], v153 offset:37888
	ds_read_b128 v[214:217], v153 offset:38912
	ds_read_b128 v[218:221], v153 offset:39936
	global_load_lds_dwordx4 v[186:187], off
	v_lshl_add_u64 v[186:187], v[182:183], 0, s[52:53]
	s_mov_b32 m0, s28
	s_nop 0
	global_load_lds_dwordx4 v[186:187], off
	s_cmp_eq_u32 s101, 0
	s_cbranch_scc1 .Lbw2_2s
	s_waitcnt vmcnt(18)
	s_branch .Lbw2_2d

.Lbw2_2d:
	s_waitcnt lgkmcnt(0)
	s_barrier
	s_setprio 1
	s_waitcnt lgkmcnt(0)
	v_mfma_f32_16x16x32_bf16 v[124:127], v[138:141], v[178:181], v[124:127]
	v_mfma_f32_16x16x32_bf16 v[120:123], v[154:157], v[178:181], v[120:123]
	v_mfma_f32_16x16x32_bf16 v[108:111], v[138:141], v[198:201], v[108:111]
	v_mfma_f32_16x16x32_bf16 v[104:107], v[154:157], v[198:201], v[104:107]
	v_mfma_f32_16x16x32_bf16 v[96:99], v[138:141], v[206:209], v[96:99]
	v_mfma_f32_16x16x32_bf16 v[88:91], v[154:157], v[206:209], v[88:91]
	v_mfma_f32_16x16x32_bf16 v[80:83], v[138:141], v[214:217], v[80:83]
	v_mfma_f32_16x16x32_bf16 v[72:75], v[154:157], v[214:217], v[72:75]
	v_mfma_f32_16x16x32_bf16 v[124:127], v[142:145], v[194:197], v[124:127]
	v_mfma_f32_16x16x32_bf16 v[120:123], v[158:161], v[194:197], v[120:123]
	v_mfma_f32_16x16x32_bf16 v[108:111], v[142:145], v[202:205], v[108:111]
	v_mfma_f32_16x16x32_bf16 v[104:107], v[158:161], v[202:205], v[104:107]
	v_mfma_f32_16x16x32_bf16 v[96:99], v[142:145], v[210:213], v[96:99]
	v_mfma_f32_16x16x32_bf16 v[88:91], v[158:161], v[210:213], v[88:91]
	v_mfma_f32_16x16x32_bf16 v[80:83], v[142:145], v[218:221], v[80:83]
	v_mfma_f32_16x16x32_bf16 v[72:75], v[158:161], v[218:221], v[72:75]
	s_setprio 0
	s_setprio 1
	v_mfma_f32_16x16x32_bf16 v[116:119], v[162:165], v[178:181], v[116:119]
	v_mfma_f32_16x16x32_bf16 v[112:115], v[170:173], v[178:181], v[112:115]
	v_mfma_f32_16x16x32_bf16 v[100:103], v[162:165], v[198:201], v[100:103]
	v_mfma_f32_16x16x32_bf16 v[92:95], v[170:173], v[198:201], v[92:95]
	v_mfma_f32_16x16x32_bf16 v[84:87], v[162:165], v[206:209], v[84:87]
	v_mfma_f32_16x16x32_bf16 v[76:79], v[170:173], v[206:209], v[76:79]
	v_mfma_f32_16x16x32_bf16 v[68:71], v[162:165], v[214:217], v[68:71]
	v_mfma_f32_16x16x32_bf16 v[64:67], v[170:173], v[214:217], v[64:67]
	v_mfma_f32_16x16x32_bf16 v[116:119], v[166:169], v[194:197], v[116:119]
	v_mfma_f32_16x16x32_bf16 v[112:115], v[174:177], v[194:197], v[112:115]
	v_mfma_f32_16x16x32_bf16 v[100:103], v[166:169], v[202:205], v[100:103]
	v_mfma_f32_16x16x32_bf16 v[92:95], v[174:177], v[202:205], v[92:95]
	v_mfma_f32_16x16x32_bf16 v[84:87], v[166:169], v[210:213], v[84:87]
	v_mfma_f32_16x16x32_bf16 v[76:79], v[174:177], v[210:213], v[76:79]
	v_mfma_f32_16x16x32_bf16 v[68:71], v[166:169], v[218:221], v[68:71]
	v_mfma_f32_16x16x32_bf16 v[64:67], v[174:177], v[218:221], v[64:67]
	s_setprio 0
	s_barrier
	s_add_i32 s14, s14, s23
	v_lshl_add_u64 v[186:187], v[146:147], 0, s[56:57]
	s_mov_b32 m0, s14
	ds_read_b128 v[178:181], v153 offset:49152
	ds_read_b128 v[194:197], v153 offset:50176
	ds_read_b128 v[198:201], v153 offset:51200
	ds_read_b128 v[202:205], v153 offset:52224
	ds_read_b128 v[206:209], v153 offset:53248
	ds_read_b128 v[210:213], v153 offset:54272
	ds_read_b128 v[214:217], v153 offset:55296
	ds_read_b128 v[218:221], v153 offset:56320
	global_load_lds_dwordx4 v[186:187], off
	v_lshl_add_u64 v[186:187], v[146:147], 0, s[96:97]
	s_add_i32 m0, s14, 0x2000
	s_add_i32 s14, s15, s23
	global_load_lds_dwordx4 v[186:187], off
	v_lshl_add_u64 v[186:187], v[146:147], 0, s[88:89]
	s_mov_b32 m0, s14
	v_lshl_add_u64 v[146:147], v[146:147], 0, s[68:69]
	global_load_lds_dwordx4 v[186:187], off
	s_add_i32 m0, s14, 0x2000
	s_nop 0
	global_load_lds_dwordx4 v[146:147], off
	v_lshl_add_u64 v[146:147], v[182:183], 0, s[56:57]
	s_mov_b32 m0, s29
	s_nop 0
	global_load_lds_dwordx4 v[146:147], off
	v_lshl_add_u64 v[146:147], v[182:183], 0, s[96:97]
	s_mov_b32 m0, s30
	s_nop 0
	global_load_lds_dwordx4 v[146:147], off
	s_waitcnt vmcnt(14)
	s_waitcnt lgkmcnt(0)
	s_barrier
	s_setprio 1
	s_waitcnt lgkmcnt(0)
	v_mfma_f32_16x16x32_bf16 v[60:63], v[138:141], v[178:181], v[60:63]
	v_mfma_f32_16x16x32_bf16 v[56:59], v[154:157], v[178:181], v[56:59]
	v_mfma_f32_16x16x32_bf16 v[48:51], v[138:141], v[198:201], v[48:51]
	v_mfma_f32_16x16x32_bf16 v[40:43], v[154:157], v[198:201], v[40:43]
	v_mfma_f32_16x16x32_bf16 v[32:35], v[138:141], v[206:209], v[32:35]
	v_mfma_f32_16x16x32_bf16 v[24:27], v[154:157], v[206:209], v[24:27]
	v_mfma_f32_16x16x32_bf16 v[16:19], v[138:141], v[214:217], v[16:19]
	v_mfma_f32_16x16x32_bf16 v[8:11], v[154:157], v[214:217], v[8:11]
	v_mfma_f32_16x16x32_bf16 v[60:63], v[142:145], v[194:197], v[60:63]
	v_mfma_f32_16x16x32_bf16 v[56:59], v[158:161], v[194:197], v[56:59]
	v_mfma_f32_16x16x32_bf16 v[48:51], v[142:145], v[202:205], v[48:51]
	v_mfma_f32_16x16x32_bf16 v[40:43], v[158:161], v[202:205], v[40:43]
	v_mfma_f32_16x16x32_bf16 v[32:35], v[142:145], v[210:213], v[32:35]
	v_mfma_f32_16x16x32_bf16 v[24:27], v[158:161], v[210:213], v[24:27]
	v_mfma_f32_16x16x32_bf16 v[16:19], v[142:145], v[218:221], v[16:19]
	v_mfma_f32_16x16x32_bf16 v[8:11], v[158:161], v[218:221], v[8:11]
	s_setprio 0
	s_setprio 1
	v_mfma_f32_16x16x32_bf16 v[52:55], v[162:165], v[178:181], v[52:55]
	v_mfma_f32_16x16x32_bf16 v[44:47], v[170:173], v[178:181], v[44:47]
	v_mfma_f32_16x16x32_bf16 v[36:39], v[162:165], v[198:201], v[36:39]
	v_mfma_f32_16x16x32_bf16 v[28:31], v[170:173], v[198:201], v[28:31]
	v_mfma_f32_16x16x32_bf16 v[20:23], v[162:165], v[206:209], v[20:23]
	v_mfma_f32_16x16x32_bf16 v[12:15], v[170:173], v[206:209], v[12:15]
	v_mfma_f32_16x16x32_bf16 v[4:7], v[162:165], v[214:217], v[4:7]
	v_mfma_f32_16x16x32_bf16 v[0:3], v[170:173], v[214:217], v[0:3]
	v_mfma_f32_16x16x32_bf16 v[52:55], v[166:169], v[194:197], v[52:55]
	v_mfma_f32_16x16x32_bf16 v[44:47], v[174:177], v[194:197], v[44:47]
	v_mfma_f32_16x16x32_bf16 v[36:39], v[166:169], v[202:205], v[36:39]
	v_mfma_f32_16x16x32_bf16 v[28:31], v[174:177], v[202:205], v[28:31]
	v_mfma_f32_16x16x32_bf16 v[20:23], v[166:169], v[210:213], v[20:23]
	v_mfma_f32_16x16x32_bf16 v[12:15], v[174:177], v[210:213], v[12:15]
	v_mfma_f32_16x16x32_bf16 v[4:7], v[166:169], v[218:221], v[4:7]
	v_mfma_f32_16x16x32_bf16 v[0:3], v[174:177], v[218:221], v[0:3]
	s_setprio 0
	s_barrier
	s_add_i32 s85, s85, 2
	s_add_u32 s60, s60, 0x100
	s_addc_u32 s61, s61, 0
	s_add_u32 s16, s16, 0x100
	s_addc_u32 s17, s17, 0
	s_cmp_gt_u32 s85, 13

.LBB0_259:
	s_lshl_b32 s14, s44, 8
	s_ashr_i32 s15, s14, 31
	v_lshl_add_u64 v[0:1], s[14:15], 2, v[132:133]
	s_waitcnt lgkmcnt(0)
	global_load_dword v136, v[0:1], off
	s_mov_b32 s101, 1
	s_andn2_b64 vcc, exec, s[12:13]
	s_cbranch_vccnz .LBB0_244
	s_mov_b32 s98, 1
	s_branch .LBB0_244

.Lnostb3:
	s_add_u32 s14, s50, 0xfffa8080
	s_addc_u32 s15, s51, -1
	s_add_i32 s22, 0, 0x10000
	s_cmp_eq_u32 s85, 18
	s_cselect_b32 s15, s1, s15
	s_cselect_b32 s14, s0, s14
	s_cselect_b32 s17, s49, s84
	s_cselect_b32 s16, s48, s70
	s_add_i32 s23, 0, 0x14000
	v_add_u32_e32 v0, s22, v221
	v_add_u32_e32 v4, s23, v221
	ds_read_b128 v[24:27], v0
	ds_read_b128 v[28:31], v0 offset:1024
	ds_read_b128 v[16:19], v0 offset:2048
	ds_read_b128 v[20:23], v0 offset:3072
	ds_read_b128 v[8:11], v4
	ds_read_b128 v[12:15], v4 offset:1024
	ds_read_b128 v[0:3], v4 offset:2048
	ds_read_b128 v[4:7], v4 offset:3072
	v_lshl_add_u64 v[206:207], s[50:51], 0, v[196:197]
	s_add_i32 m0, s19, 0xc000
	ds_read_b128 v[160:163], v223
	ds_read_b128 v[164:167], v223 offset:1024
	ds_read_b128 v[168:171], v223 offset:2048
	ds_read_b128 v[172:175], v223 offset:3072
	ds_read_b128 v[176:179], v223 offset:4096
	ds_read_b128 v[180:183], v223 offset:5120
	ds_read_b128 v[198:201], v223 offset:6144
	ds_read_b128 v[202:205], v223 offset:7168
	global_load_lds_dwordx4 v[206:207], off
	v_lshl_add_u64 v[206:207], v[206:207], 0, vcc
	s_add_i32 m0, s19, 0xe000
	s_nop 0
	global_load_lds_dwordx4 v[206:207], off
	s_cmp_eq_u32 s101, 0
	s_cbranch_scc1 .Lbw3_0s
	s_waitcnt vmcnt(18)
	s_branch .Lbw3_0d

.Lbw3_0d:
	s_waitcnt lgkmcnt(0)
	s_barrier
	s_setprio 1
	s_waitcnt lgkmcnt(0)
	v_mfma_scale_f32_16x16x128_f8f6f4 v[156:159], v[24:31], v[160:167], 0, v240, v240 op_sel_hi:[0,0,0]
	v_mfma_scale_f32_16x16x128_f8f6f4 v[152:155], v[16:23], v[160:167], 0, v240, v240 op_sel_hi:[0,0,0]
	v_mfma_scale_f32_16x16x128_f8f6f4 v[140:143], v[24:31], v[168:175], 0, v240, v240 op_sel_hi:[0,0,0]
	v_mfma_scale_f32_16x16x128_f8f6f4 v[136:139], v[16:23], v[168:175], 0, v240, v240 op_sel_hi:[0,0,0]
	v_mfma_scale_f32_16x16x128_f8f6f4 v[124:127], v[24:31], v[176:183], 0, v240, v240 op_sel_hi:[0,0,0]
	v_mfma_scale_f32_16x16x128_f8f6f4 v[120:123], v[16:23], v[176:183], 0, v240, v240 op_sel_hi:[0,0,0]
	v_mfma_scale_f32_16x16x128_f8f6f4 v[108:111], v[24:31], v[198:205], 0, v240, v240 op_sel_hi:[0,0,0]
	v_mfma_scale_f32_16x16x128_f8f6f4 v[104:107], v[16:23], v[198:205], 0, v240, v240 op_sel_hi:[0,0,0]
	s_setprio 0
	s_setprio 1
	v_mfma_scale_f32_16x16x128_f8f6f4 v[148:151], v[8:15], v[160:167], 0, v240, v240 op_sel_hi:[0,0,0]
	v_mfma_scale_f32_16x16x128_f8f6f4 v[144:147], v[0:7], v[160:167], 0, v240, v240 op_sel_hi:[0,0,0]
	v_mfma_scale_f32_16x16x128_f8f6f4 v[132:135], v[8:15], v[168:175], 0, v240, v240 op_sel_hi:[0,0,0]
	v_mfma_scale_f32_16x16x128_f8f6f4 v[128:131], v[0:7], v[168:175], 0, v240, v240 op_sel_hi:[0,0,0]
	v_mfma_scale_f32_16x16x128_f8f6f4 v[116:119], v[8:15], v[176:183], 0, v240, v240 op_sel_hi:[0,0,0]
	v_mfma_scale_f32_16x16x128_f8f6f4 v[112:115], v[0:7], v[176:183], 0, v240, v240 op_sel_hi:[0,0,0]
	v_mfma_scale_f32_16x16x128_f8f6f4 v[100:103], v[8:15], v[198:205], 0, v240, v240 op_sel_hi:[0,0,0]
	v_mfma_scale_f32_16x16x128_f8f6f4 v[96:99], v[0:7], v[198:205], 0, v240, v240 op_sel_hi:[0,0,0]
	s_setprio 0
	s_barrier
	v_lshl_add_u64 v[160:161], s[16:17], 0, v[184:185]
	s_add_i32 s16, s22, s6
	s_mov_b32 m0, s16
	ds_read_b128 v[164:167], v223 offset:16384
	ds_read_b128 v[168:171], v223 offset:17408
	ds_read_b128 v[172:175], v223 offset:18432
	ds_read_b128 v[176:179], v223 offset:19456
	ds_read_b128 v[198:201], v223 offset:20480
	ds_read_b128 v[202:205], v223 offset:21504
	ds_read_b128 v[206:209], v223 offset:22528
	ds_read_b128 v[210:213], v223 offset:23552
	global_load_lds_dwordx4 v[160:161], off
	v_lshl_add_u64 v[162:163], v[160:161], 0, vcc
	s_add_i32 m0, s16, 0x2000
	s_add_i32 s16, s23, s6
	global_load_lds_dwordx4 v[162:163], off
	v_lshl_add_u64 v[162:163], v[160:161], 0, s[2:3]
	s_mov_b32 m0, s16
	s_nop 0
	global_load_lds_dwordx4 v[162:163], off
	v_lshl_add_u64 v[162:163], v[160:161], 0, s[82:83]
	s_add_i32 m0, s16, 0x2000
	s_nop 0
	global_load_lds_dwordx4 v[162:163], off
	v_lshl_add_u64 v[162:163], s[14:15], 0, v[194:195]
	s_mov_b32 m0, s19
	v_lshl_add_u64 v[180:181], v[162:163], 0, vcc
	global_load_lds_dwordx4 v[162:163], off
	s_mov_b32 m0, s20
	s_nop 0
	global_load_lds_dwordx4 v[180:181], off
	s_cmp_eq_u32 s101, 0
	s_cbranch_scc1 .Lbw3_1s
	s_waitcnt vmcnt(22)
	s_branch .Lbw3_1d

.Lbw3_1d:
	s_waitcnt lgkmcnt(0)
	s_barrier
	s_setprio 1
	s_waitcnt lgkmcnt(0)
	v_mfma_scale_f32_16x16x128_f8f6f4 v[92:95], v[24:31], v[164:171], 0, v240, v240 op_sel_hi:[0,0,0]
	v_mfma_scale_f32_16x16x128_f8f6f4 v[88:91], v[16:23], v[164:171], 0, v240, v240 op_sel_hi:[0,0,0]
	v_mfma_scale_f32_16x16x128_f8f6f4 v[76:79], v[24:31], v[172:179], 0, v240, v240 op_sel_hi:[0,0,0]
	v_mfma_scale_f32_16x16x128_f8f6f4 v[72:75], v[16:23], v[172:179], 0, v240, v240 op_sel_hi:[0,0,0]
	v_mfma_scale_f32_16x16x128_f8f6f4 v[60:63], v[24:31], v[198:205], 0, v240, v240 op_sel_hi:[0,0,0]
	v_mfma_scale_f32_16x16x128_f8f6f4 v[56:59], v[16:23], v[198:205], 0, v240, v240 op_sel_hi:[0,0,0]
	v_mfma_scale_f32_16x16x128_f8f6f4 v[44:47], v[24:31], v[206:213], 0, v240, v240 op_sel_hi:[0,0,0]
	v_mfma_scale_f32_16x16x128_f8f6f4 v[40:43], v[16:23], v[206:213], 0, v240, v240 op_sel_hi:[0,0,0]
	s_setprio 0
	s_setprio 1
	v_mfma_scale_f32_16x16x128_f8f6f4 v[84:87], v[8:15], v[164:171], 0, v240, v240 op_sel_hi:[0,0,0]
	v_mfma_scale_f32_16x16x128_f8f6f4 v[80:83], v[0:7], v[164:171], 0, v240, v240 op_sel_hi:[0,0,0]
	v_mfma_scale_f32_16x16x128_f8f6f4 v[68:71], v[8:15], v[172:179], 0, v240, v240 op_sel_hi:[0,0,0]
	v_mfma_scale_f32_16x16x128_f8f6f4 v[64:67], v[0:7], v[172:179], 0, v240, v240 op_sel_hi:[0,0,0]
	v_mfma_scale_f32_16x16x128_f8f6f4 v[52:55], v[8:15], v[198:205], 0, v240, v240 op_sel_hi:[0,0,0]
	v_mfma_scale_f32_16x16x128_f8f6f4 v[48:51], v[0:7], v[198:205], 0, v240, v240 op_sel_hi:[0,0,0]
	v_mfma_scale_f32_16x16x128_f8f6f4 v[36:39], v[8:15], v[206:213], 0, v240, v240 op_sel_hi:[0,0,0]
	v_mfma_scale_f32_16x16x128_f8f6f4 v[32:35], v[0:7], v[206:213], 0, v240, v240 op_sel_hi:[0,0,0]
	s_setprio 0
	s_barrier
	s_add_i32 s14, 0, 0x18000
	s_add_i32 s15, 0, 0x1c000
	v_add_u32_e32 v12, s14, v221
	v_add_u32_e32 v28, s15, v221
	ds_read_b128 v[0:3], v12
	ds_read_b128 v[4:7], v12 offset:1024
	ds_read_b128 v[8:11], v12 offset:2048
	ds_read_b128 v[12:15], v12 offset:3072
	ds_read_b128 v[16:19], v28
	ds_read_b128 v[20:23], v28 offset:1024
	ds_read_b128 v[24:27], v28 offset:2048
	ds_read_b128 v[28:31], v28 offset:3072
	s_mov_b32 m0, s25
	v_lshl_add_u64 v[180:181], v[162:163], 0, s[2:3]
	ds_read_b128 v[164:167], v223 offset:32768
	ds_read_b128 v[168:171], v223 offset:33792
	ds_read_b128 v[172:175], v223 offset:34816
	ds_read_b128 v[176:179], v223 offset:35840
	ds_read_b128 v[198:201], v223 offset:36864
	ds_read_b128 v[202:205], v223 offset:37888
	ds_read_b128 v[206:209], v223 offset:38912
	ds_read_b128 v[210:213], v223 offset:39936
	global_load_lds_dwordx4 v[180:181], off
	v_lshl_add_u64 v[180:181], v[162:163], 0, s[82:83]
	s_mov_b32 m0, s26
	s_nop 0
	global_load_lds_dwordx4 v[180:181], off
	s_cmp_eq_u32 s101, 0
	s_cbranch_scc1 .Lbw3_2s
	s_waitcnt vmcnt(18)
	s_branch .Lbw3_2d

.Lbw3_2d:
	s_waitcnt lgkmcnt(0)
	s_barrier
	s_setprio 1
	s_waitcnt lgkmcnt(0)
	v_mfma_scale_f32_16x16x128_f8f6f4 v[156:159], v[0:7], v[164:171], v[156:159], v240, v240 op_sel_hi:[0,0,0]
	v_mfma_scale_f32_16x16x128_f8f6f4 v[152:155], v[8:15], v[164:171], v[152:155], v240, v240 op_sel_hi:[0,0,0]
	v_mfma_scale_f32_16x16x128_f8f6f4 v[140:143], v[0:7], v[172:179], v[140:143], v240, v240 op_sel_hi:[0,0,0]
	v_mfma_scale_f32_16x16x128_f8f6f4 v[136:139], v[8:15], v[172:179], v[136:139], v240, v240 op_sel_hi:[0,0,0]
	v_mfma_scale_f32_16x16x128_f8f6f4 v[124:127], v[0:7], v[198:205], v[124:127], v240, v240 op_sel_hi:[0,0,0]
	v_mfma_scale_f32_16x16x128_f8f6f4 v[120:123], v[8:15], v[198:205], v[120:123], v240, v240 op_sel_hi:[0,0,0]
	v_mfma_scale_f32_16x16x128_f8f6f4 v[108:111], v[0:7], v[206:213], v[108:111], v240, v240 op_sel_hi:[0,0,0]
	v_mfma_scale_f32_16x16x128_f8f6f4 v[104:107], v[8:15], v[206:213], v[104:107], v240, v240 op_sel_hi:[0,0,0]
	s_setprio 0
	s_setprio 1
	v_mfma_scale_f32_16x16x128_f8f6f4 v[148:151], v[16:23], v[164:171], v[148:151], v240, v240 op_sel_hi:[0,0,0]
	v_mfma_scale_f32_16x16x128_f8f6f4 v[144:147], v[24:31], v[164:171], v[144:147], v240, v240 op_sel_hi:[0,0,0]
	v_mfma_scale_f32_16x16x128_f8f6f4 v[132:135], v[16:23], v[172:179], v[132:135], v240, v240 op_sel_hi:[0,0,0]
	v_mfma_scale_f32_16x16x128_f8f6f4 v[128:131], v[24:31], v[172:179], v[128:131], v240, v240 op_sel_hi:[0,0,0]
	v_mfma_scale_f32_16x16x128_f8f6f4 v[116:119], v[16:23], v[198:205], v[116:119], v240, v240 op_sel_hi:[0,0,0]
	v_mfma_scale_f32_16x16x128_f8f6f4 v[112:115], v[24:31], v[198:205], v[112:115], v240, v240 op_sel_hi:[0,0,0]
	v_mfma_scale_f32_16x16x128_f8f6f4 v[100:103], v[16:23], v[206:213], v[100:103], v240, v240 op_sel_hi:[0,0,0]
	v_mfma_scale_f32_16x16x128_f8f6f4 v[96:99], v[24:31], v[206:213], v[96:99], v240, v240 op_sel_hi:[0,0,0]
	s_setprio 0
	s_barrier
	s_add_i32 s14, s14, s6
	v_lshl_add_u64 v[180:181], v[160:161], 0, s[56:57]
	s_mov_b32 m0, s14
	ds_read_b128 v[164:167], v223 offset:49152
	ds_read_b128 v[168:171], v223 offset:50176
	ds_read_b128 v[172:175], v223 offset:51200
	ds_read_b128 v[176:179], v223 offset:52224
	ds_read_b128 v[198:201], v223 offset:53248
	ds_read_b128 v[202:205], v223 offset:54272
	ds_read_b128 v[206:209], v223 offset:55296
	ds_read_b128 v[210:213], v223 offset:56320
	global_load_lds_dwordx4 v[180:181], off
	v_lshl_add_u64 v[180:181], v[160:161], 0, s[80:81]
	s_add_i32 m0, s14, 0x2000
	s_add_i32 s14, s15, s6
	global_load_lds_dwordx4 v[180:181], off
	v_lshl_add_u64 v[180:181], v[160:161], 0, s[74:75]
	s_mov_b32 m0, s14
	v_lshl_add_u64 v[160:161], v[160:161], 0, s[62:63]
	global_load_lds_dwordx4 v[180:181], off
	s_add_i32 m0, s14, 0x2000
	s_nop 0
	global_load_lds_dwordx4 v[160:161], off
	v_lshl_add_u64 v[160:161], v[162:163], 0, s[56:57]
	s_mov_b32 m0, s28
	s_nop 0
	global_load_lds_dwordx4 v[160:161], off
	v_lshl_add_u64 v[160:161], v[162:163], 0, s[80:81]
	s_mov_b32 m0, s29
	s_nop 0
	global_load_lds_dwordx4 v[160:161], off
	s_waitcnt vmcnt(14)
	s_waitcnt lgkmcnt(0)
	s_barrier
	s_setprio 1
	s_waitcnt lgkmcnt(0)
	v_mfma_scale_f32_16x16x128_f8f6f4 v[92:95], v[0:7], v[164:171], v[92:95], v240, v240 op_sel_hi:[0,0,0]
	v_mfma_scale_f32_16x16x128_f8f6f4 v[88:91], v[8:15], v[164:171], v[88:91], v240, v240 op_sel_hi:[0,0,0]
	v_mfma_scale_f32_16x16x128_f8f6f4 v[76:79], v[0:7], v[172:179], v[76:79], v240, v240 op_sel_hi:[0,0,0]
	v_mfma_scale_f32_16x16x128_f8f6f4 v[72:75], v[8:15], v[172:179], v[72:75], v240, v240 op_sel_hi:[0,0,0]
	v_mfma_scale_f32_16x16x128_f8f6f4 v[60:63], v[0:7], v[198:205], v[60:63], v240, v240 op_sel_hi:[0,0,0]
	v_mfma_scale_f32_16x16x128_f8f6f4 v[56:59], v[8:15], v[198:205], v[56:59], v240, v240 op_sel_hi:[0,0,0]
	v_mfma_scale_f32_16x16x128_f8f6f4 v[44:47], v[0:7], v[206:213], v[44:47], v240, v240 op_sel_hi:[0,0,0]
	v_mfma_scale_f32_16x16x128_f8f6f4 v[40:43], v[8:15], v[206:213], v[40:43], v240, v240 op_sel_hi:[0,0,0]
	s_setprio 0
	s_setprio 1
	v_mfma_scale_f32_16x16x128_f8f6f4 v[84:87], v[16:23], v[164:171], v[84:87], v240, v240 op_sel_hi:[0,0,0]
	v_mfma_scale_f32_16x16x128_f8f6f4 v[80:83], v[24:31], v[164:171], v[80:83], v240, v240 op_sel_hi:[0,0,0]
	v_mfma_scale_f32_16x16x128_f8f6f4 v[68:71], v[16:23], v[172:179], v[68:71], v240, v240 op_sel_hi:[0,0,0]
	v_mfma_scale_f32_16x16x128_f8f6f4 v[64:67], v[24:31], v[172:179], v[64:67], v240, v240 op_sel_hi:[0,0,0]
	v_mfma_scale_f32_16x16x128_f8f6f4 v[52:55], v[16:23], v[198:205], v[52:55], v240, v240 op_sel_hi:[0,0,0]
	v_mfma_scale_f32_16x16x128_f8f6f4 v[48:51], v[24:31], v[198:205], v[48:51], v240, v240 op_sel_hi:[0,0,0]
	v_mfma_scale_f32_16x16x128_f8f6f4 v[36:39], v[16:23], v[206:213], v[36:39], v240, v240 op_sel_hi:[0,0,0]
	v_mfma_scale_f32_16x16x128_f8f6f4 v[32:35], v[24:31], v[206:213], v[32:35], v240, v240 op_sel_hi:[0,0,0]
	s_setprio 0
	s_barrier
	s_add_i32 s85, s85, 2
	s_add_u32 s50, s50, 0x100
	s_addc_u32 s51, s51, 0
	s_add_u32 s70, s70, 0x100
	s_addc_u32 s84, s84, 0
	s_cmp_gt_u32 s85, 19

.LBB0_336:
	s_or_b64 exec, exec, s[14:15]
	s_and_b64 vcc, exec, s[38:39]
	s_mov_b64 s[14:15], -1
	s_cbranch_vccnz .LBB0_305
	s_mov_b32 s101, 1
	s_andn2_b64 vcc, exec, s[42:43]
	s_cbranch_vccnz .LBB0_304
	s_mov_b32 s98, 1
	s_branch .LBB0_304

.Lnostb4:
	s_add_i32 s24, s14, 2
	s_add_u32 s46, vcc_lo, 0x80
	s_addc_u32 s15, vcc_hi, 0
	s_add_i32 s18, 0, 0x10000
	s_cmp_eq_u32 s6, s14
	s_cselect_b32 s15, s1, s15
	s_cselect_b32 s14, s0, s46
	s_cselect_b32 s47, s13, s17
	s_cselect_b32 s46, s12, s16
	s_add_i32 s21, 0, 0x14000
	v_add_u32_e32 v140, s18, v223
	v_add_u32_e32 v156, s21, v223
	s_waitcnt lgkmcnt(0)
	ds_read_b128 v[128:131], v140
	ds_read_b128 v[132:135], v140 offset:1024
	ds_read_b128 v[136:139], v140 offset:2048
	ds_read_b128 v[140:143], v140 offset:3072
	ds_read_b128 v[144:147], v156
	ds_read_b128 v[148:151], v156 offset:1024
	ds_read_b128 v[152:155], v156 offset:2048
	ds_read_b128 v[156:159], v156 offset:3072
	v_lshl_add_u64 v[186:187], vcc, 0, v[196:197]
	s_add_i32 m0, s28, 0xc000
	ds_read_b128 v[160:163], v225
	ds_read_b128 v[164:167], v225 offset:1024
	ds_read_b128 v[168:171], v225 offset:2048
	ds_read_b128 v[172:175], v225 offset:3072
	ds_read_b128 v[176:179], v225 offset:4096
	ds_read_b128 v[180:183], v225 offset:5120
	ds_read_b128 v[200:203], v225 offset:6144
	ds_read_b128 v[204:207], v225 offset:7168
	global_load_lds_dwordx4 v[186:187], off
	v_lshl_add_u64 v[186:187], vcc, 0, v[198:199]
	s_add_i32 m0, s28, 0xe000
	s_nop 0
	global_load_lds_dwordx4 v[186:187], off
	s_cmp_eq_u32 s101, 0
	s_cbranch_scc1 .Lbw4_0s
	s_waitcnt vmcnt(18)
	s_branch .Lbw4_0d

.Lbw4_0d:
	s_waitcnt lgkmcnt(0)
	s_barrier
	s_setprio 1
	s_waitcnt lgkmcnt(0)
	v_mfma_f32_16x16x32_bf16 v[124:127], v[128:131], v[160:163], 0
	v_mfma_f32_16x16x32_bf16 v[120:123], v[136:139], v[160:163], 0
	v_mfma_f32_16x16x32_bf16 v[108:111], v[128:131], v[168:171], 0
	v_mfma_f32_16x16x32_bf16 v[104:107], v[136:139], v[168:171], 0
	v_mfma_f32_16x16x32_bf16 v[92:95], v[128:131], v[176:179], 0
	v_mfma_f32_16x16x32_bf16 v[88:91], v[136:139], v[176:179], 0
	v_mfma_f32_16x16x32_bf16 v[76:79], v[128:131], v[200:203], 0
	v_mfma_f32_16x16x32_bf16 v[72:75], v[136:139], v[200:203], 0
	v_mfma_f32_16x16x32_bf16 v[124:127], v[132:135], v[164:167], v[124:127]
	v_mfma_f32_16x16x32_bf16 v[120:123], v[140:143], v[164:167], v[120:123]
	v_mfma_f32_16x16x32_bf16 v[108:111], v[132:135], v[172:175], v[108:111]
	v_mfma_f32_16x16x32_bf16 v[104:107], v[140:143], v[172:175], v[104:107]
	v_mfma_f32_16x16x32_bf16 v[92:95], v[132:135], v[180:183], v[92:95]
	v_mfma_f32_16x16x32_bf16 v[88:91], v[140:143], v[180:183], v[88:91]
	v_mfma_f32_16x16x32_bf16 v[76:79], v[132:135], v[204:207], v[76:79]
	v_mfma_f32_16x16x32_bf16 v[72:75], v[140:143], v[204:207], v[72:75]
	s_setprio 0
	s_setprio 1
	v_mfma_f32_16x16x32_bf16 v[116:119], v[144:147], v[160:163], 0
	v_mfma_f32_16x16x32_bf16 v[112:115], v[152:155], v[160:163], 0
	v_mfma_f32_16x16x32_bf16 v[100:103], v[144:147], v[168:171], 0
	v_mfma_f32_16x16x32_bf16 v[96:99], v[152:155], v[168:171], 0
	v_mfma_f32_16x16x32_bf16 v[84:87], v[144:147], v[176:179], 0
	v_mfma_f32_16x16x32_bf16 v[80:83], v[152:155], v[176:179], 0
	v_mfma_f32_16x16x32_bf16 v[68:71], v[144:147], v[200:203], 0
	v_mfma_f32_16x16x32_bf16 v[64:67], v[152:155], v[200:203], 0
	v_mfma_f32_16x16x32_bf16 v[116:119], v[148:151], v[164:167], v[116:119]
	v_mfma_f32_16x16x32_bf16 v[112:115], v[156:159], v[164:167], v[112:115]
	v_mfma_f32_16x16x32_bf16 v[100:103], v[148:151], v[172:175], v[100:103]
	v_mfma_f32_16x16x32_bf16 v[96:99], v[156:159], v[172:175], v[96:99]
	v_mfma_f32_16x16x32_bf16 v[84:87], v[148:151], v[180:183], v[84:87]
	v_mfma_f32_16x16x32_bf16 v[80:83], v[156:159], v[180:183], v[80:83]
	v_mfma_f32_16x16x32_bf16 v[68:71], v[148:151], v[204:207], v[68:71]
	v_mfma_f32_16x16x32_bf16 v[64:67], v[156:159], v[204:207], v[64:67]
	s_setprio 0
	s_barrier
	s_add_i32 s18, s18, s27
	v_lshl_add_u64 v[186:187], s[46:47], 0, v[184:185]
	s_mov_b32 m0, s18
	ds_read_b128 v[160:163], v225 offset:16384
	ds_read_b128 v[164:167], v225 offset:17408
	ds_read_b128 v[168:171], v225 offset:18432
	ds_read_b128 v[172:175], v225 offset:19456
	ds_read_b128 v[176:179], v225 offset:20480
	ds_read_b128 v[180:183], v225 offset:21504
	ds_read_b128 v[200:203], v225 offset:22528
	ds_read_b128 v[204:207], v225 offset:23552
	global_load_lds_dwordx4 v[186:187], off
	s_add_i32 m0, s18, 0x2000
	s_add_u32 s46, s46, s44
	v_lshl_add_u64 v[188:189], v[186:187], 0, s[70:71]
	s_addc_u32 s47, s47, 0
	s_add_i32 s18, s21, s27
	global_load_lds_dwordx4 v[188:189], off
	v_lshl_add_u64 v[208:209], s[46:47], 0, v[184:185]
	s_mov_b32 m0, s18
	v_lshl_add_u64 v[210:211], v[208:209], 0, s[70:71]
	global_load_lds_dwordx4 v[208:209], off
	s_add_i32 m0, s18, 0x2000
	v_lshl_add_u64 v[212:213], s[14:15], 0, v[194:195]
	global_load_lds_dwordx4 v[210:211], off
	s_mov_b32 m0, s28
	v_lshl_add_u64 v[214:215], v[212:213], 0, s[70:71]
	global_load_lds_dwordx4 v[212:213], off
	s_mov_b32 m0, s29
	s_nop 0
	global_load_lds_dwordx4 v[214:215], off
	s_cmp_eq_u32 s101, 0
	s_cbranch_scc1 .Lbw4_1s
	s_waitcnt vmcnt(22)
	s_branch .Lbw4_1d

.Lbw4_1d:
	s_waitcnt lgkmcnt(0)
	s_barrier
	s_setprio 1
	s_waitcnt lgkmcnt(0)
	v_mfma_f32_16x16x32_bf16 v[60:63], v[128:131], v[160:163], 0
	v_mfma_f32_16x16x32_bf16 v[56:59], v[136:139], v[160:163], 0
	v_mfma_f32_16x16x32_bf16 v[44:47], v[128:131], v[168:171], 0
	v_mfma_f32_16x16x32_bf16 v[40:43], v[136:139], v[168:171], 0
	v_mfma_f32_16x16x32_bf16 v[28:31], v[128:131], v[176:179], 0
	v_mfma_f32_16x16x32_bf16 v[24:27], v[136:139], v[176:179], 0
	v_mfma_f32_16x16x32_bf16 v[12:15], v[128:131], v[200:203], 0
	v_mfma_f32_16x16x32_bf16 v[8:11], v[136:139], v[200:203], 0
	v_mfma_f32_16x16x32_bf16 v[60:63], v[132:135], v[164:167], v[60:63]
	v_mfma_f32_16x16x32_bf16 v[56:59], v[140:143], v[164:167], v[56:59]
	v_mfma_f32_16x16x32_bf16 v[44:47], v[132:135], v[172:175], v[44:47]
	v_mfma_f32_16x16x32_bf16 v[40:43], v[140:143], v[172:175], v[40:43]
	v_mfma_f32_16x16x32_bf16 v[28:31], v[132:135], v[180:183], v[28:31]
	v_mfma_f32_16x16x32_bf16 v[24:27], v[140:143], v[180:183], v[24:27]
	v_mfma_f32_16x16x32_bf16 v[12:15], v[132:135], v[204:207], v[12:15]
	v_mfma_f32_16x16x32_bf16 v[8:11], v[140:143], v[204:207], v[8:11]
	s_setprio 0
	s_setprio 1
	v_mfma_f32_16x16x32_bf16 v[52:55], v[144:147], v[160:163], 0
	v_mfma_f32_16x16x32_bf16 v[48:51], v[152:155], v[160:163], 0
	v_mfma_f32_16x16x32_bf16 v[36:39], v[144:147], v[168:171], 0
	v_mfma_f32_16x16x32_bf16 v[32:35], v[152:155], v[168:171], 0
	v_mfma_f32_16x16x32_bf16 v[20:23], v[144:147], v[176:179], 0
	v_mfma_f32_16x16x32_bf16 v[16:19], v[152:155], v[176:179], 0
	v_mfma_f32_16x16x32_bf16 v[4:7], v[144:147], v[200:203], 0
	v_mfma_f32_16x16x32_bf16 v[0:3], v[152:155], v[200:203], 0
	v_mfma_f32_16x16x32_bf16 v[52:55], v[148:151], v[164:167], v[52:55]
	v_mfma_f32_16x16x32_bf16 v[48:51], v[156:159], v[164:167], v[48:51]
	v_mfma_f32_16x16x32_bf16 v[36:39], v[148:151], v[172:175], v[36:39]
	v_mfma_f32_16x16x32_bf16 v[32:35], v[156:159], v[172:175], v[32:35]
	v_mfma_f32_16x16x32_bf16 v[20:23], v[148:151], v[180:183], v[20:23]
	v_mfma_f32_16x16x32_bf16 v[16:19], v[156:159], v[180:183], v[16:19]
	v_mfma_f32_16x16x32_bf16 v[4:7], v[148:151], v[204:207], v[4:7]
	v_mfma_f32_16x16x32_bf16 v[0:3], v[156:159], v[204:207], v[0:3]
	s_setprio 0
	s_barrier
	s_add_i32 s18, 0, 0x18000
	s_add_i32 s21, 0, 0x1c000
	v_add_u32_e32 v140, s18, v223
	v_add_u32_e32 v156, s21, v223
	ds_read_b128 v[128:131], v140
	ds_read_b128 v[132:135], v140 offset:1024
	ds_read_b128 v[136:139], v140 offset:2048
	ds_read_b128 v[140:143], v140 offset:3072
	ds_read_b128 v[144:147], v156
	ds_read_b128 v[148:151], v156 offset:1024
	ds_read_b128 v[152:155], v156 offset:2048
	ds_read_b128 v[156:159], v156 offset:3072
	s_add_u32 s14, s14, s44
	s_addc_u32 s15, s15, 0
	s_mov_b32 m0, s30
	v_lshl_add_u64 v[216:217], s[14:15], 0, v[194:195]
	ds_read_b128 v[160:163], v225 offset:32768
	ds_read_b128 v[164:167], v225 offset:33792
	ds_read_b128 v[168:171], v225 offset:34816
	ds_read_b128 v[172:175], v225 offset:35840
	ds_read_b128 v[176:179], v225 offset:36864
	ds_read_b128 v[180:183], v225 offset:37888
	ds_read_b128 v[200:203], v225 offset:38912
	ds_read_b128 v[204:207], v225 offset:39936
	global_load_lds_dwordx4 v[216:217], off
	v_lshl_add_u64 v[216:217], v[216:217], 0, s[70:71]
	s_mov_b32 m0, s31
	s_nop 0
	global_load_lds_dwordx4 v[216:217], off
	s_cmp_eq_u32 s101, 0
	s_cbranch_scc1 .Lbw4_2s
	s_waitcnt vmcnt(18)
	s_branch .Lbw4_2d

.Lbw4_2d:
	s_waitcnt lgkmcnt(0)
	s_barrier
	s_setprio 1
	s_waitcnt lgkmcnt(0)
	v_mfma_f32_16x16x32_bf16 v[124:127], v[128:131], v[160:163], v[124:127]
	v_mfma_f32_16x16x32_bf16 v[120:123], v[136:139], v[160:163], v[120:123]
	v_mfma_f32_16x16x32_bf16 v[108:111], v[128:131], v[168:171], v[108:111]
	v_mfma_f32_16x16x32_bf16 v[104:107], v[136:139], v[168:171], v[104:107]
	v_mfma_f32_16x16x32_bf16 v[92:95], v[128:131], v[176:179], v[92:95]
	v_mfma_f32_16x16x32_bf16 v[88:91], v[136:139], v[176:179], v[88:91]
	v_mfma_f32_16x16x32_bf16 v[76:79], v[128:131], v[200:203], v[76:79]
	v_mfma_f32_16x16x32_bf16 v[72:75], v[136:139], v[200:203], v[72:75]
	v_mfma_f32_16x16x32_bf16 v[124:127], v[132:135], v[164:167], v[124:127]
	v_mfma_f32_16x16x32_bf16 v[120:123], v[140:143], v[164:167], v[120:123]
	v_mfma_f32_16x16x32_bf16 v[108:111], v[132:135], v[172:175], v[108:111]
	v_mfma_f32_16x16x32_bf16 v[104:107], v[140:143], v[172:175], v[104:107]
	v_mfma_f32_16x16x32_bf16 v[92:95], v[132:135], v[180:183], v[92:95]
	v_mfma_f32_16x16x32_bf16 v[88:91], v[140:143], v[180:183], v[88:91]
	v_mfma_f32_16x16x32_bf16 v[76:79], v[132:135], v[204:207], v[76:79]
	v_mfma_f32_16x16x32_bf16 v[72:75], v[140:143], v[204:207], v[72:75]
	s_setprio 0
	s_setprio 1
	v_mfma_f32_16x16x32_bf16 v[116:119], v[144:147], v[160:163], v[116:119]
	v_mfma_f32_16x16x32_bf16 v[112:115], v[152:155], v[160:163], v[112:115]
	v_mfma_f32_16x16x32_bf16 v[100:103], v[144:147], v[168:171], v[100:103]
	v_mfma_f32_16x16x32_bf16 v[96:99], v[152:155], v[168:171], v[96:99]
	v_mfma_f32_16x16x32_bf16 v[84:87], v[144:147], v[176:179], v[84:87]
	v_mfma_f32_16x16x32_bf16 v[80:83], v[152:155], v[176:179], v[80:83]
	v_mfma_f32_16x16x32_bf16 v[68:71], v[144:147], v[200:203], v[68:71]
	v_mfma_f32_16x16x32_bf16 v[64:67], v[152:155], v[200:203], v[64:67]
	v_mfma_f32_16x16x32_bf16 v[116:119], v[148:151], v[164:167], v[116:119]
	v_mfma_f32_16x16x32_bf16 v[112:115], v[156:159], v[164:167], v[112:115]
	v_mfma_f32_16x16x32_bf16 v[100:103], v[148:151], v[172:175], v[100:103]
	v_mfma_f32_16x16x32_bf16 v[96:99], v[156:159], v[172:175], v[96:99]
	v_mfma_f32_16x16x32_bf16 v[84:87], v[148:151], v[180:183], v[84:87]
	v_mfma_f32_16x16x32_bf16 v[80:83], v[156:159], v[180:183], v[80:83]
	v_mfma_f32_16x16x32_bf16 v[68:71], v[148:151], v[204:207], v[68:71]
	v_mfma_f32_16x16x32_bf16 v[64:67], v[156:159], v[204:207], v[64:67]
	s_setprio 0
	s_barrier
	s_add_i32 s14, s18, s27
	v_lshl_add_u64 v[186:187], v[186:187], 0, s[56:57]
	s_mov_b32 m0, s14
	ds_read_b128 v[160:163], v225 offset:49152
	ds_read_b128 v[164:167], v225 offset:50176
	ds_read_b128 v[168:171], v225 offset:51200
	ds_read_b128 v[172:175], v225 offset:52224
	ds_read_b128 v[176:179], v225 offset:53248
	ds_read_b128 v[180:183], v225 offset:54272
	ds_read_b128 v[200:203], v225 offset:55296
	ds_read_b128 v[204:207], v225 offset:56320
	global_load_lds_dwordx4 v[186:187], off
	v_lshl_add_u64 v[186:187], v[188:189], 0, s[56:57]
	s_add_i32 m0, s14, 0x2000
	s_add_i32 s14, s21, s27
	global_load_lds_dwordx4 v[186:187], off
	v_lshl_add_u64 v[186:187], v[208:209], 0, s[56:57]
	s_mov_b32 m0, s14
	s_nop 0
	global_load_lds_dwordx4 v[186:187], off
	v_lshl_add_u64 v[186:187], v[210:211], 0, s[56:57]
	s_add_i32 m0, s14, 0x2000
	s_nop 0
	global_load_lds_dwordx4 v[186:187], off
	v_lshl_add_u64 v[186:187], v[212:213], 0, s[56:57]
	s_mov_b32 m0, s19
	s_nop 0
	global_load_lds_dwordx4 v[186:187], off
	v_lshl_add_u64 v[186:187], v[214:215], 0, s[56:57]
	s_mov_b32 m0, s20
	s_nop 0
	global_load_lds_dwordx4 v[186:187], off
	s_waitcnt vmcnt(14)
	s_waitcnt lgkmcnt(0)
	s_barrier
	s_setprio 1
	s_waitcnt lgkmcnt(0)
	v_mfma_f32_16x16x32_bf16 v[60:63], v[128:131], v[160:163], v[60:63]
	v_mfma_f32_16x16x32_bf16 v[56:59], v[136:139], v[160:163], v[56:59]
	v_mfma_f32_16x16x32_bf16 v[44:47], v[128:131], v[168:171], v[44:47]
	v_mfma_f32_16x16x32_bf16 v[40:43], v[136:139], v[168:171], v[40:43]
	v_mfma_f32_16x16x32_bf16 v[28:31], v[128:131], v[176:179], v[28:31]
	v_mfma_f32_16x16x32_bf16 v[24:27], v[136:139], v[176:179], v[24:27]
	v_mfma_f32_16x16x32_bf16 v[12:15], v[128:131], v[200:203], v[12:15]
	v_mfma_f32_16x16x32_bf16 v[8:11], v[136:139], v[200:203], v[8:11]
	v_mfma_f32_16x16x32_bf16 v[60:63], v[132:135], v[164:167], v[60:63]
	v_mfma_f32_16x16x32_bf16 v[56:59], v[140:143], v[164:167], v[56:59]
	v_mfma_f32_16x16x32_bf16 v[44:47], v[132:135], v[172:175], v[44:47]
	v_mfma_f32_16x16x32_bf16 v[40:43], v[140:143], v[172:175], v[40:43]
	v_mfma_f32_16x16x32_bf16 v[28:31], v[132:135], v[180:183], v[28:31]
	v_mfma_f32_16x16x32_bf16 v[24:27], v[140:143], v[180:183], v[24:27]
	v_mfma_f32_16x16x32_bf16 v[12:15], v[132:135], v[204:207], v[12:15]
	v_mfma_f32_16x16x32_bf16 v[8:11], v[140:143], v[204:207], v[8:11]
	s_setprio 0
	s_setprio 1
	v_mfma_f32_16x16x32_bf16 v[52:55], v[144:147], v[160:163], v[52:55]
	v_mfma_f32_16x16x32_bf16 v[48:51], v[152:155], v[160:163], v[48:51]
	v_mfma_f32_16x16x32_bf16 v[36:39], v[144:147], v[168:171], v[36:39]
	v_mfma_f32_16x16x32_bf16 v[32:35], v[152:155], v[168:171], v[32:35]
	v_mfma_f32_16x16x32_bf16 v[20:23], v[144:147], v[176:179], v[20:23]
	v_mfma_f32_16x16x32_bf16 v[16:19], v[152:155], v[176:179], v[16:19]
	v_mfma_f32_16x16x32_bf16 v[4:7], v[144:147], v[200:203], v[4:7]
	v_mfma_f32_16x16x32_bf16 v[0:3], v[152:155], v[200:203], v[0:3]
	v_mfma_f32_16x16x32_bf16 v[52:55], v[148:151], v[164:167], v[52:55]
	v_mfma_f32_16x16x32_bf16 v[48:51], v[156:159], v[164:167], v[48:51]
	v_mfma_f32_16x16x32_bf16 v[36:39], v[148:151], v[172:175], v[36:39]
	v_mfma_f32_16x16x32_bf16 v[32:35], v[156:159], v[172:175], v[32:35]
	v_mfma_f32_16x16x32_bf16 v[20:23], v[148:151], v[180:183], v[20:23]
	v_mfma_f32_16x16x32_bf16 v[16:19], v[156:159], v[180:183], v[16:19]
	v_mfma_f32_16x16x32_bf16 v[4:7], v[148:151], v[204:207], v[4:7]
	v_mfma_f32_16x16x32_bf16 v[0:3], v[156:159], v[204:207], v[0:3]
	s_setprio 0
	s_barrier
	s_add_u32 vcc_lo, vcc_lo, 0x100
	s_addc_u32 vcc_hi, vcc_hi, 0
	s_add_u32 s16, s16, 0x100
	s_addc_u32 s17, s17, 0
	s_cmp_ge_u32 s24, s84
	s_mov_b32 s14, s24

.LBB0_400:
	s_mov_b32 s101, 1
	s_andn2_b64 vcc, exec, s[50:51]
	s_cbranch_vccnz .LBB0_349
	s_mov_b32 s98, 1
	s_branch .LBB0_349

.Lnostb5:
	s_add_i32 s23, s14, 2
	s_add_u32 s24, s44, 0x80
	s_addc_u32 s15, s45, 0
	s_add_i32 s49, 0, 0x10000
	s_cmp_eq_u32 s31, s14
	s_cselect_b32 s15, s1, s15
	s_cselect_b32 s14, s0, s24
	s_cselect_b32 s51, s43, s17
	s_cselect_b32 s50, s42, s16
	s_add_i32 s24, 0, 0x14000
	v_add_u32_e32 v108, s49, v249
	v_add_u32_e32 v140, s24, v249
	ds_read_b128 v[80:83], v108
	ds_read_b128 v[84:87], v108 offset:1024
	ds_read_b128 v[104:107], v108 offset:2048
	ds_read_b128 v[108:111], v108 offset:3072
	ds_read_b128 v[124:127], v140
	ds_read_b128 v[132:135], v140 offset:1024
	ds_read_b128 v[136:139], v140 offset:2048
	ds_read_b128 v[140:143], v140 offset:3072
	v_lshl_add_u64 v[208:209], s[44:45], 0, v[196:197]
	s_add_i32 m0, s20, 0xc000
	ds_read_b128 v[144:147], v251
	ds_read_b128 v[148:151], v251 offset:1024
	ds_read_b128 v[152:155], v251 offset:2048
	ds_read_b128 v[156:159], v251 offset:3072
	ds_read_b128 v[160:163], v251 offset:4096
	ds_read_b128 v[164:167], v251 offset:5120
	ds_read_b128 v[200:203], v251 offset:6144
	ds_read_b128 v[204:207], v251 offset:7168
	global_load_lds_dwordx4 v[208:209], off
	v_lshl_add_u64 v[208:209], s[44:45], 0, v[198:199]
	s_add_i32 m0, s20, 0xe000
	s_nop 0
	global_load_lds_dwordx4 v[208:209], off
	s_cmp_eq_u32 s101, 0
	s_cbranch_scc1 .Lbw5_0s
	s_waitcnt vmcnt(18)
	s_branch .Lbw5_0d

.Lbw5_0d:
	s_waitcnt lgkmcnt(0)
	s_barrier
	s_setprio 1
	s_waitcnt lgkmcnt(0)
	v_mfma_f32_16x16x32_bf16 v[180:183], v[80:83], v[144:147], 0
	v_mfma_f32_16x16x32_bf16 v[176:179], v[104:107], v[144:147], 0
	v_mfma_f32_16x16x32_bf16 v[128:131], v[80:83], v[152:155], 0
	v_mfma_f32_16x16x32_bf16 v[120:123], v[104:107], v[152:155], 0
	v_mfma_f32_16x16x32_bf16 v[100:103], v[80:83], v[160:163], 0
	v_mfma_f32_16x16x32_bf16 v[96:99], v[104:107], v[160:163], 0
	v_mfma_f32_16x16x32_bf16 v[76:79], v[80:83], v[200:203], 0
	v_mfma_f32_16x16x32_bf16 v[72:75], v[104:107], v[200:203], 0
	v_mfma_f32_16x16x32_bf16 v[180:183], v[84:87], v[148:151], v[180:183]
	v_mfma_f32_16x16x32_bf16 v[176:179], v[108:111], v[148:151], v[176:179]
	v_mfma_f32_16x16x32_bf16 v[128:131], v[84:87], v[156:159], v[128:131]
	v_mfma_f32_16x16x32_bf16 v[120:123], v[108:111], v[156:159], v[120:123]
	v_mfma_f32_16x16x32_bf16 v[100:103], v[84:87], v[164:167], v[100:103]
	v_mfma_f32_16x16x32_bf16 v[96:99], v[108:111], v[164:167], v[96:99]
	v_mfma_f32_16x16x32_bf16 v[76:79], v[84:87], v[204:207], v[76:79]
	v_mfma_f32_16x16x32_bf16 v[72:75], v[108:111], v[204:207], v[72:75]
	s_setprio 0
	s_setprio 1
	v_mfma_f32_16x16x32_bf16 v[172:175], v[124:127], v[144:147], 0
	v_mfma_f32_16x16x32_bf16 v[116:119], v[124:127], v[152:155], 0
	v_mfma_f32_16x16x32_bf16 v[112:115], v[136:139], v[152:155], 0
	v_mfma_f32_16x16x32_bf16 v[92:95], v[124:127], v[160:163], 0
	v_mfma_f32_16x16x32_bf16 v[88:91], v[136:139], v[160:163], 0
	v_mfma_f32_16x16x32_bf16 v[68:71], v[124:127], v[200:203], 0
	v_mfma_f32_16x16x32_bf16 v[64:67], v[136:139], v[200:203], 0
	v_mfma_f32_16x16x32_bf16 v[172:175], v[132:135], v[148:151], v[172:175]
	v_mfma_f32_16x16x32_bf16 v[144:147], v[136:139], v[144:147], 0
	v_mfma_f32_16x16x32_bf16 v[116:119], v[132:135], v[156:159], v[116:119]
	v_mfma_f32_16x16x32_bf16 v[112:115], v[140:143], v[156:159], v[112:115]
	v_mfma_f32_16x16x32_bf16 v[92:95], v[132:135], v[164:167], v[92:95]
	v_mfma_f32_16x16x32_bf16 v[88:91], v[140:143], v[164:167], v[88:91]
	v_mfma_f32_16x16x32_bf16 v[68:71], v[132:135], v[204:207], v[68:71]
	v_mfma_f32_16x16x32_bf16 v[64:67], v[140:143], v[204:207], v[64:67]
	v_mfma_f32_16x16x32_bf16 v[144:147], v[140:143], v[148:151], v[144:147]
	s_setprio 0
	s_barrier
	s_add_i32 s49, s49, s19
	v_lshl_add_u64 v[212:213], s[50:51], 0, v[184:185]
	s_mov_b32 m0, s49
	ds_read_b128 v[148:151], v251 offset:16384
	ds_read_b128 v[152:155], v251 offset:17408
	ds_read_b128 v[156:159], v251 offset:18432
	ds_read_b128 v[160:163], v251 offset:19456
	ds_read_b128 v[164:167], v251 offset:20480
	ds_read_b128 v[168:171], v251 offset:21504
	ds_read_b128 v[200:203], v251 offset:22528
	ds_read_b128 v[204:207], v251 offset:23552
	global_load_lds_dwordx4 v[212:213], off
	s_add_i32 m0, s49, 0x2000
	s_add_u32 s50, s50, s8
	v_lshl_add_u64 v[214:215], v[212:213], 0, s[70:71]
	s_addc_u32 s51, s51, 0
	s_add_i32 s24, s24, s19
	global_load_lds_dwordx4 v[214:215], off
	v_lshl_add_u64 v[216:217], s[50:51], 0, v[184:185]
	s_mov_b32 m0, s24
	v_lshl_add_u64 v[218:219], v[216:217], 0, s[70:71]
	global_load_lds_dwordx4 v[216:217], off
	s_add_i32 m0, s24, 0x2000
	v_lshl_add_u64 v[220:221], s[14:15], 0, v[194:195]
	global_load_lds_dwordx4 v[218:219], off
	s_mov_b32 m0, s20
	v_lshl_add_u64 v[222:223], v[220:221], 0, s[70:71]
	global_load_lds_dwordx4 v[220:221], off
	s_mov_b32 m0, s25
	s_nop 0
	global_load_lds_dwordx4 v[222:223], off
	s_cmp_eq_u32 s101, 0
	s_cbranch_scc1 .Lbw5_1s
	s_waitcnt vmcnt(22)
	s_branch .Lbw5_1d

.Lbw5_1d:
	s_waitcnt lgkmcnt(0)
	s_barrier
	s_setprio 1
	s_waitcnt lgkmcnt(0)
	v_mfma_f32_16x16x32_bf16 v[60:63], v[80:83], v[148:151], 0
	v_mfma_f32_16x16x32_bf16 v[56:59], v[104:107], v[148:151], 0
	v_mfma_f32_16x16x32_bf16 v[44:47], v[80:83], v[156:159], 0
	v_mfma_f32_16x16x32_bf16 v[40:43], v[104:107], v[156:159], 0
	v_mfma_f32_16x16x32_bf16 v[28:31], v[80:83], v[164:167], 0
	v_mfma_f32_16x16x32_bf16 v[24:27], v[104:107], v[164:167], 0
	v_mfma_f32_16x16x32_bf16 v[12:15], v[80:83], v[200:203], 0
	v_mfma_f32_16x16x32_bf16 v[8:11], v[104:107], v[200:203], 0
	v_mfma_f32_16x16x32_bf16 v[60:63], v[84:87], v[152:155], v[60:63]
	v_mfma_f32_16x16x32_bf16 v[56:59], v[108:111], v[152:155], v[56:59]
	v_mfma_f32_16x16x32_bf16 v[44:47], v[84:87], v[160:163], v[44:47]
	v_mfma_f32_16x16x32_bf16 v[40:43], v[108:111], v[160:163], v[40:43]
	v_mfma_f32_16x16x32_bf16 v[28:31], v[84:87], v[168:171], v[28:31]
	v_mfma_f32_16x16x32_bf16 v[24:27], v[108:111], v[168:171], v[24:27]
	v_mfma_f32_16x16x32_bf16 v[12:15], v[84:87], v[204:207], v[12:15]
	v_mfma_f32_16x16x32_bf16 v[8:11], v[108:111], v[204:207], v[8:11]
	s_setprio 0
	s_setprio 1
	v_mfma_f32_16x16x32_bf16 v[52:55], v[124:127], v[148:151], 0
	v_mfma_f32_16x16x32_bf16 v[48:51], v[136:139], v[148:151], 0
	v_mfma_f32_16x16x32_bf16 v[36:39], v[124:127], v[156:159], 0
	v_mfma_f32_16x16x32_bf16 v[32:35], v[136:139], v[156:159], 0
	v_mfma_f32_16x16x32_bf16 v[20:23], v[124:127], v[164:167], 0
	v_mfma_f32_16x16x32_bf16 v[16:19], v[136:139], v[164:167], 0
	v_mfma_f32_16x16x32_bf16 v[4:7], v[124:127], v[200:203], 0
	v_mfma_f32_16x16x32_bf16 v[0:3], v[136:139], v[200:203], 0
	v_mfma_f32_16x16x32_bf16 v[52:55], v[132:135], v[152:155], v[52:55]
	v_mfma_f32_16x16x32_bf16 v[48:51], v[140:143], v[152:155], v[48:51]
	v_mfma_f32_16x16x32_bf16 v[36:39], v[132:135], v[160:163], v[36:39]
	v_mfma_f32_16x16x32_bf16 v[32:35], v[140:143], v[160:163], v[32:35]
	v_mfma_f32_16x16x32_bf16 v[20:23], v[132:135], v[168:171], v[20:23]
	v_mfma_f32_16x16x32_bf16 v[16:19], v[140:143], v[168:171], v[16:19]
	v_mfma_f32_16x16x32_bf16 v[4:7], v[132:135], v[204:207], v[4:7]
	v_mfma_f32_16x16x32_bf16 v[0:3], v[140:143], v[204:207], v[0:3]
	s_setprio 0
	s_barrier
	s_add_i32 s24, 0, 0x18000
	s_add_i32 s49, 0, 0x1c000
	v_add_u32_e32 v108, s24, v249
	v_add_u32_e32 v140, s49, v249
	ds_read_b128 v[80:83], v108
	ds_read_b128 v[84:87], v108 offset:1024
	ds_read_b128 v[104:107], v108 offset:2048
	ds_read_b128 v[108:111], v108 offset:3072
	ds_read_b128 v[124:127], v140
	ds_read_b128 v[132:135], v140 offset:1024
	ds_read_b128 v[136:139], v140 offset:2048
	ds_read_b128 v[140:143], v140 offset:3072
	s_add_u32 s14, s14, s8
	s_addc_u32 s15, s15, 0
	s_mov_b32 m0, s26
	v_lshl_add_u64 v[168:169], s[14:15], 0, v[194:195]
	ds_read_b128 v[148:151], v251 offset:32768
	ds_read_b128 v[152:155], v251 offset:33792
	ds_read_b128 v[156:159], v251 offset:34816
	ds_read_b128 v[160:163], v251 offset:35840
	ds_read_b128 v[164:167], v251 offset:36864
	ds_read_b128 v[200:203], v251 offset:37888
	ds_read_b128 v[204:207], v251 offset:38912
	ds_read_b128 v[208:211], v251 offset:39936
	global_load_lds_dwordx4 v[168:169], off
	v_lshl_add_u64 v[168:169], v[168:169], 0, s[70:71]
	s_mov_b32 m0, s27
	s_nop 0
	global_load_lds_dwordx4 v[168:169], off
	s_cmp_eq_u32 s101, 0
	s_cbranch_scc1 .Lbw5_2s
	s_waitcnt vmcnt(18)
	s_branch .Lbw5_2d

.Lbw5_2d:
	s_waitcnt lgkmcnt(0)
	s_barrier
	s_setprio 1
	s_waitcnt lgkmcnt(0)
	v_mfma_f32_16x16x32_bf16 v[168:171], v[80:83], v[148:151], v[180:183]
	v_mfma_f32_16x16x32_bf16 v[180:183], v[84:87], v[152:155], v[168:171]
	v_mfma_f32_16x16x32_bf16 v[168:171], v[104:107], v[148:151], v[176:179]
	v_mfma_f32_16x16x32_bf16 v[128:131], v[80:83], v[156:159], v[128:131]
	v_mfma_f32_16x16x32_bf16 v[120:123], v[104:107], v[156:159], v[120:123]
	v_mfma_f32_16x16x32_bf16 v[100:103], v[80:83], v[164:167], v[100:103]
	v_mfma_f32_16x16x32_bf16 v[96:99], v[104:107], v[164:167], v[96:99]
	v_mfma_f32_16x16x32_bf16 v[76:79], v[80:83], v[204:207], v[76:79]
	v_mfma_f32_16x16x32_bf16 v[72:75], v[104:107], v[204:207], v[72:75]
	v_mfma_f32_16x16x32_bf16 v[176:179], v[108:111], v[152:155], v[168:171]
	v_mfma_f32_16x16x32_bf16 v[128:131], v[84:87], v[160:163], v[128:131]
	v_mfma_f32_16x16x32_bf16 v[120:123], v[108:111], v[160:163], v[120:123]
	v_mfma_f32_16x16x32_bf16 v[100:103], v[84:87], v[200:203], v[100:103]
	v_mfma_f32_16x16x32_bf16 v[96:99], v[108:111], v[200:203], v[96:99]
	v_mfma_f32_16x16x32_bf16 v[76:79], v[84:87], v[208:211], v[76:79]
	v_mfma_f32_16x16x32_bf16 v[72:75], v[108:111], v[208:211], v[72:75]
	s_setprio 0
	s_setprio 1
	v_mfma_f32_16x16x32_bf16 v[168:171], v[124:127], v[148:151], v[172:175]
	v_mfma_f32_16x16x32_bf16 v[144:147], v[136:139], v[148:151], v[144:147]
	v_mfma_f32_16x16x32_bf16 v[116:119], v[124:127], v[156:159], v[116:119]
	v_mfma_f32_16x16x32_bf16 v[112:115], v[136:139], v[156:159], v[112:115]
	v_mfma_f32_16x16x32_bf16 v[92:95], v[124:127], v[164:167], v[92:95]
	v_mfma_f32_16x16x32_bf16 v[88:91], v[136:139], v[164:167], v[88:91]
	v_mfma_f32_16x16x32_bf16 v[68:71], v[124:127], v[204:207], v[68:71]
	v_mfma_f32_16x16x32_bf16 v[64:67], v[136:139], v[204:207], v[64:67]
	v_mfma_f32_16x16x32_bf16 v[172:175], v[132:135], v[152:155], v[168:171]
	v_mfma_f32_16x16x32_bf16 v[168:171], v[140:143], v[152:155], v[144:147]
	v_mfma_f32_16x16x32_bf16 v[116:119], v[132:135], v[160:163], v[116:119]
	v_mfma_f32_16x16x32_bf16 v[112:115], v[140:143], v[160:163], v[112:115]
	v_mfma_f32_16x16x32_bf16 v[92:95], v[132:135], v[200:203], v[92:95]
	v_mfma_f32_16x16x32_bf16 v[88:91], v[140:143], v[200:203], v[88:91]
	v_mfma_f32_16x16x32_bf16 v[68:71], v[132:135], v[208:211], v[68:71]
	v_mfma_f32_16x16x32_bf16 v[64:67], v[140:143], v[208:211], v[64:67]
	s_setprio 0
	s_barrier
	s_add_i32 s14, s24, s19
	v_lshl_add_u64 v[208:209], v[212:213], 0, s[56:57]
	s_mov_b32 m0, s14
	ds_read_b128 v[144:147], v251 offset:49152
	ds_read_b128 v[148:151], v251 offset:50176
	ds_read_b128 v[152:155], v251 offset:51200
	ds_read_b128 v[156:159], v251 offset:52224
	ds_read_b128 v[160:163], v251 offset:53248
	ds_read_b128 v[164:167], v251 offset:54272
	ds_read_b128 v[200:203], v251 offset:55296
	ds_read_b128 v[204:207], v251 offset:56320
	global_load_lds_dwordx4 v[208:209], off
	v_lshl_add_u64 v[208:209], v[214:215], 0, s[56:57]
	s_add_i32 m0, s14, 0x2000
	s_add_i32 s14, s49, s19
	global_load_lds_dwordx4 v[208:209], off
	v_lshl_add_u64 v[208:209], v[216:217], 0, s[56:57]
	s_mov_b32 m0, s14
	s_nop 0
	global_load_lds_dwordx4 v[208:209], off
	v_lshl_add_u64 v[208:209], v[218:219], 0, s[56:57]
	s_add_i32 m0, s14, 0x2000
	s_nop 0
	global_load_lds_dwordx4 v[208:209], off
	v_lshl_add_u64 v[208:209], v[220:221], 0, s[56:57]
	s_mov_b32 m0, s29
	s_nop 0
	global_load_lds_dwordx4 v[208:209], off
	v_lshl_add_u64 v[208:209], v[222:223], 0, s[56:57]
	s_mov_b32 m0, s30
	s_nop 0
	global_load_lds_dwordx4 v[208:209], off
	s_waitcnt vmcnt(14)
	s_waitcnt lgkmcnt(0)
	s_barrier
	s_setprio 1
	s_waitcnt lgkmcnt(0)
	v_mfma_f32_16x16x32_bf16 v[60:63], v[80:83], v[144:147], v[60:63]
	v_mfma_f32_16x16x32_bf16 v[56:59], v[104:107], v[144:147], v[56:59]
	v_mfma_f32_16x16x32_bf16 v[44:47], v[80:83], v[152:155], v[44:47]
	v_mfma_f32_16x16x32_bf16 v[40:43], v[104:107], v[152:155], v[40:43]
	v_mfma_f32_16x16x32_bf16 v[28:31], v[80:83], v[160:163], v[28:31]
	v_mfma_f32_16x16x32_bf16 v[24:27], v[104:107], v[160:163], v[24:27]
	v_mfma_f32_16x16x32_bf16 v[12:15], v[80:83], v[200:203], v[12:15]
	v_mfma_f32_16x16x32_bf16 v[8:11], v[104:107], v[200:203], v[8:11]
	v_mfma_f32_16x16x32_bf16 v[60:63], v[84:87], v[148:151], v[60:63]
	v_mfma_f32_16x16x32_bf16 v[56:59], v[108:111], v[148:151], v[56:59]
	v_mfma_f32_16x16x32_bf16 v[44:47], v[84:87], v[156:159], v[44:47]
	v_mfma_f32_16x16x32_bf16 v[40:43], v[108:111], v[156:159], v[40:43]
	v_mfma_f32_16x16x32_bf16 v[28:31], v[84:87], v[164:167], v[28:31]
	v_mfma_f32_16x16x32_bf16 v[24:27], v[108:111], v[164:167], v[24:27]
	v_mfma_f32_16x16x32_bf16 v[12:15], v[84:87], v[204:207], v[12:15]
	v_mfma_f32_16x16x32_bf16 v[8:11], v[108:111], v[204:207], v[8:11]
	s_setprio 0
	s_setprio 1
	v_mfma_f32_16x16x32_bf16 v[52:55], v[124:127], v[144:147], v[52:55]
	v_mfma_f32_16x16x32_bf16 v[48:51], v[136:139], v[144:147], v[48:51]
	v_mfma_f32_16x16x32_bf16 v[36:39], v[124:127], v[152:155], v[36:39]
	v_mfma_f32_16x16x32_bf16 v[32:35], v[136:139], v[152:155], v[32:35]
	v_mfma_f32_16x16x32_bf16 v[20:23], v[124:127], v[160:163], v[20:23]
	v_mfma_f32_16x16x32_bf16 v[16:19], v[136:139], v[160:163], v[16:19]
	v_mfma_f32_16x16x32_bf16 v[4:7], v[124:127], v[200:203], v[4:7]
	v_mfma_f32_16x16x32_bf16 v[0:3], v[136:139], v[200:203], v[0:3]
	v_mfma_f32_16x16x32_bf16 v[52:55], v[132:135], v[148:151], v[52:55]
	v_mfma_f32_16x16x32_bf16 v[48:51], v[140:143], v[148:151], v[48:51]
	v_mfma_f32_16x16x32_bf16 v[36:39], v[132:135], v[156:159], v[36:39]
	v_mfma_f32_16x16x32_bf16 v[32:35], v[140:143], v[156:159], v[32:35]
	v_mfma_f32_16x16x32_bf16 v[20:23], v[132:135], v[164:167], v[20:23]
	v_mfma_f32_16x16x32_bf16 v[16:19], v[140:143], v[164:167], v[16:19]
	v_mfma_f32_16x16x32_bf16 v[4:7], v[132:135], v[204:207], v[4:7]
	v_mfma_f32_16x16x32_bf16 v[0:3], v[140:143], v[204:207], v[0:3]
	s_setprio 0
	s_barrier
	s_add_u32 s44, s44, 0x100
	s_addc_u32 s45, s45, 0
	s_add_u32 s16, s16, 0x100
	s_addc_u32 s17, s17, 0
	s_cmp_ge_u32 s23, s28
	s_mov_b32 s14, s23

.LBB0_441:
	s_or_b64 exec, exec, s[14:15]
	s_and_b64 vcc, exec, s[38:39]
	s_mov_b64 s[14:15], -1
	s_cbranch_vccnz .LBB0_410
	s_mov_b32 s101, 1
	s_andn2_b64 vcc, exec, s[10:11]
	s_cbranch_vccnz .LBB0_409
	s_mov_b32 s98, 1
	s_branch .LBB0_409

.Lnostb6:
	s_add_u32 s14, s48, 0xfffc0080
	s_addc_u32 s15, s49, -1
	s_add_i32 s70, 0, 0x10000
	s_cmp_eq_u32 s51, 12
	s_cselect_b32 s15, s31, s15
	s_cselect_b32 s14, s43, s14
	v_add_u32_e32 v138, s70, v142
	s_cselect_b32 s61, s13, s17
	s_cselect_b32 s60, s50, s16
	s_add_i32 s84, 0, 0x14000
	ds_read_b128 v[134:137], v138
	ds_read_b128 v[148:151], v138 offset:1024
	ds_read_b128 v[152:155], v138 offset:2048
	ds_read_b128 v[156:159], v138 offset:3072
	v_add_u32_e32 v138, s84, v142
	ds_read_b128 v[160:163], v138
	ds_read_b128 v[164:167], v138 offset:1024
	ds_read_b128 v[168:171], v138 offset:2048
	ds_read_b128 v[172:175], v138 offset:3072
	v_lshl_add_u64 v[138:139], s[48:49], 0, v[132:133]
	s_add_i32 m0, s19, 0xc000
	ds_read_b128 v[176:179], v146
	ds_read_b128 v[180:183], v146 offset:1024
	ds_read_b128 v[194:197], v146 offset:2048
	ds_read_b128 v[198:201], v146 offset:3072
	ds_read_b128 v[202:205], v146 offset:4096
	ds_read_b128 v[206:209], v146 offset:5120
	ds_read_b128 v[210:213], v146 offset:6144
	ds_read_b128 v[214:217], v146 offset:7168
	global_load_lds_dwordx4 v[138:139], off
	v_lshl_add_u64 v[138:139], v[138:139], 0, s[34:35]
	s_add_i32 m0, s19, 0xe000
	s_nop 0
	global_load_lds_dwordx4 v[138:139], off
	s_cmp_eq_u32 s101, 0
	s_cbranch_scc1 .Lbw6_0s
	s_waitcnt vmcnt(18)
	s_branch .Lbw6_0d

.Lbw6_0d:
	s_waitcnt lgkmcnt(0)
	s_barrier
	s_setprio 1
	s_waitcnt lgkmcnt(0)
	v_mfma_f32_16x16x32_bf16 v[124:127], v[134:137], v[176:179], 0
	v_mfma_f32_16x16x32_bf16 v[116:119], v[152:155], v[176:179], 0
	v_mfma_f32_16x16x32_bf16 v[108:111], v[134:137], v[194:197], 0
	v_mfma_f32_16x16x32_bf16 v[100:103], v[152:155], v[194:197], 0
	v_mfma_f32_16x16x32_bf16 v[92:95], v[134:137], v[202:205], 0
	v_mfma_f32_16x16x32_bf16 v[84:87], v[152:155], v[202:205], 0
	v_mfma_f32_16x16x32_bf16 v[76:79], v[134:137], v[210:213], 0
	v_mfma_f32_16x16x32_bf16 v[68:71], v[152:155], v[210:213], 0
	v_mfma_f32_16x16x32_bf16 v[124:127], v[148:151], v[180:183], v[124:127]
	v_mfma_f32_16x16x32_bf16 v[116:119], v[156:159], v[180:183], v[116:119]
	v_mfma_f32_16x16x32_bf16 v[108:111], v[148:151], v[198:201], v[108:111]
	v_mfma_f32_16x16x32_bf16 v[100:103], v[156:159], v[198:201], v[100:103]
	v_mfma_f32_16x16x32_bf16 v[92:95], v[148:151], v[206:209], v[92:95]
	v_mfma_f32_16x16x32_bf16 v[84:87], v[156:159], v[206:209], v[84:87]
	v_mfma_f32_16x16x32_bf16 v[76:79], v[148:151], v[214:217], v[76:79]
	v_mfma_f32_16x16x32_bf16 v[68:71], v[156:159], v[214:217], v[68:71]
	s_setprio 0
	s_setprio 1
	v_mfma_f32_16x16x32_bf16 v[120:123], v[160:163], v[176:179], 0
	v_mfma_f32_16x16x32_bf16 v[112:115], v[168:171], v[176:179], 0
	v_mfma_f32_16x16x32_bf16 v[104:107], v[160:163], v[194:197], 0
	v_mfma_f32_16x16x32_bf16 v[96:99], v[168:171], v[194:197], 0
	v_mfma_f32_16x16x32_bf16 v[88:91], v[160:163], v[202:205], 0
	v_mfma_f32_16x16x32_bf16 v[80:83], v[168:171], v[202:205], 0
	v_mfma_f32_16x16x32_bf16 v[72:75], v[160:163], v[210:213], 0
	v_mfma_f32_16x16x32_bf16 v[64:67], v[168:171], v[210:213], 0
	v_mfma_f32_16x16x32_bf16 v[120:123], v[164:167], v[180:183], v[120:123]
	v_mfma_f32_16x16x32_bf16 v[112:115], v[172:175], v[180:183], v[112:115]
	v_mfma_f32_16x16x32_bf16 v[104:107], v[164:167], v[198:201], v[104:107]
	v_mfma_f32_16x16x32_bf16 v[96:99], v[172:175], v[198:201], v[96:99]
	v_mfma_f32_16x16x32_bf16 v[88:91], v[164:167], v[206:209], v[88:91]
	v_mfma_f32_16x16x32_bf16 v[80:83], v[172:175], v[206:209], v[80:83]
	v_mfma_f32_16x16x32_bf16 v[72:75], v[164:167], v[214:217], v[72:75]
	v_mfma_f32_16x16x32_bf16 v[64:67], v[172:175], v[214:217], v[64:67]
	s_setprio 0
	s_barrier
	v_lshl_add_u64 v[138:139], s[60:61], 0, v[184:185]
	s_add_i32 s60, s70, s6
	s_mov_b32 m0, s60
	ds_read_b128 v[176:179], v146 offset:16384
	ds_read_b128 v[180:183], v146 offset:17408
	ds_read_b128 v[194:197], v146 offset:18432
	ds_read_b128 v[198:201], v146 offset:19456
	ds_read_b128 v[202:205], v146 offset:20480
	ds_read_b128 v[206:209], v146 offset:21504
	ds_read_b128 v[210:213], v146 offset:22528
	ds_read_b128 v[214:217], v146 offset:23552
	global_load_lds_dwordx4 v[138:139], off
	v_lshl_add_u64 v[218:219], v[138:139], 0, s[34:35]
	s_add_i32 m0, s60, 0x2000
	s_add_i32 s60, s84, s6
	global_load_lds_dwordx4 v[218:219], off
	v_lshl_add_u64 v[218:219], v[138:139], 0, s[92:93]
	s_mov_b32 m0, s60
	s_nop 0
	global_load_lds_dwordx4 v[218:219], off
	v_lshl_add_u64 v[218:219], v[138:139], 0, s[52:53]
	s_add_i32 m0, s60, 0x2000
	s_nop 0
	global_load_lds_dwordx4 v[218:219], off
	v_lshl_add_u64 v[218:219], s[14:15], 0, v[128:129]
	s_mov_b32 m0, s19
	v_lshl_add_u64 v[220:221], v[218:219], 0, s[34:35]
	global_load_lds_dwordx4 v[218:219], off
	s_mov_b32 m0, s20
	s_nop 0
	global_load_lds_dwordx4 v[220:221], off
	s_cmp_eq_u32 s101, 0
	s_cbranch_scc1 .Lbw6_1s
	s_waitcnt vmcnt(22)
	s_branch .Lbw6_1d

.Lbw6_1d:
	s_waitcnt lgkmcnt(0)
	s_barrier
	s_setprio 1
	s_waitcnt lgkmcnt(0)
	v_mfma_f32_16x16x32_bf16 v[60:63], v[134:137], v[176:179], 0
	v_mfma_f32_16x16x32_bf16 v[52:55], v[152:155], v[176:179], 0
	v_mfma_f32_16x16x32_bf16 v[44:47], v[134:137], v[194:197], 0
	v_mfma_f32_16x16x32_bf16 v[36:39], v[152:155], v[194:197], 0
	v_mfma_f32_16x16x32_bf16 v[28:31], v[134:137], v[202:205], 0
	v_mfma_f32_16x16x32_bf16 v[20:23], v[152:155], v[202:205], 0
	v_mfma_f32_16x16x32_bf16 v[12:15], v[134:137], v[210:213], 0
	v_mfma_f32_16x16x32_bf16 v[4:7], v[152:155], v[210:213], 0
	v_mfma_f32_16x16x32_bf16 v[60:63], v[148:151], v[180:183], v[60:63]
	v_mfma_f32_16x16x32_bf16 v[52:55], v[156:159], v[180:183], v[52:55]
	v_mfma_f32_16x16x32_bf16 v[44:47], v[148:151], v[198:201], v[44:47]
	v_mfma_f32_16x16x32_bf16 v[36:39], v[156:159], v[198:201], v[36:39]
	v_mfma_f32_16x16x32_bf16 v[28:31], v[148:151], v[206:209], v[28:31]
	v_mfma_f32_16x16x32_bf16 v[20:23], v[156:159], v[206:209], v[20:23]
	v_mfma_f32_16x16x32_bf16 v[12:15], v[148:151], v[214:217], v[12:15]
	v_mfma_f32_16x16x32_bf16 v[4:7], v[156:159], v[214:217], v[4:7]
	s_setprio 0
	s_setprio 1
	v_mfma_f32_16x16x32_bf16 v[56:59], v[160:163], v[176:179], 0
	v_mfma_f32_16x16x32_bf16 v[48:51], v[168:171], v[176:179], 0
	v_mfma_f32_16x16x32_bf16 v[40:43], v[160:163], v[194:197], 0
	v_mfma_f32_16x16x32_bf16 v[32:35], v[168:171], v[194:197], 0
	v_mfma_f32_16x16x32_bf16 v[24:27], v[160:163], v[202:205], 0
	v_mfma_f32_16x16x32_bf16 v[16:19], v[168:171], v[202:205], 0
	v_mfma_f32_16x16x32_bf16 v[8:11], v[160:163], v[210:213], 0
	v_mfma_f32_16x16x32_bf16 v[0:3], v[168:171], v[210:213], 0
	v_mfma_f32_16x16x32_bf16 v[56:59], v[164:167], v[180:183], v[56:59]
	v_mfma_f32_16x16x32_bf16 v[48:51], v[172:175], v[180:183], v[48:51]
	v_mfma_f32_16x16x32_bf16 v[40:43], v[164:167], v[198:201], v[40:43]
	v_mfma_f32_16x16x32_bf16 v[32:35], v[172:175], v[198:201], v[32:35]
	v_mfma_f32_16x16x32_bf16 v[24:27], v[164:167], v[206:209], v[24:27]
	v_mfma_f32_16x16x32_bf16 v[16:19], v[172:175], v[206:209], v[16:19]
	v_mfma_f32_16x16x32_bf16 v[8:11], v[164:167], v[214:217], v[8:11]
	v_mfma_f32_16x16x32_bf16 v[0:3], v[172:175], v[214:217], v[0:3]
	s_setprio 0
	s_barrier
	s_add_i32 s14, 0, 0x18000
	v_add_u32_e32 v147, s14, v142
	s_add_i32 s15, 0, 0x1c000
	ds_read_b128 v[134:137], v147
	ds_read_b128 v[148:151], v147 offset:1024
	ds_read_b128 v[152:155], v147 offset:2048
	ds_read_b128 v[156:159], v147 offset:3072
	v_add_u32_e32 v147, s15, v142
	ds_read_b128 v[160:163], v147
	ds_read_b128 v[164:167], v147 offset:1024
	ds_read_b128 v[168:171], v147 offset:2048
	ds_read_b128 v[172:175], v147 offset:3072
	s_mov_b32 m0, s24
	v_lshl_add_u64 v[220:221], v[218:219], 0, s[92:93]
	ds_read_b128 v[176:179], v146 offset:32768
	ds_read_b128 v[180:183], v146 offset:33792
	ds_read_b128 v[194:197], v146 offset:34816
	ds_read_b128 v[198:201], v146 offset:35840
	ds_read_b128 v[202:205], v146 offset:36864
	ds_read_b128 v[206:209], v146 offset:37888
	ds_read_b128 v[210:213], v146 offset:38912
	ds_read_b128 v[214:217], v146 offset:39936
	global_load_lds_dwordx4 v[220:221], off
	v_lshl_add_u64 v[220:221], v[218:219], 0, s[52:53]
	s_mov_b32 m0, s25
	s_nop 0
	global_load_lds_dwordx4 v[220:221], off
	s_cmp_eq_u32 s101, 0
	s_cbranch_scc1 .Lbw6_2s
	s_waitcnt vmcnt(18)
	s_branch .Lbw6_2d

.Lbw6_2d:
	s_waitcnt lgkmcnt(0)
	s_barrier
	s_setprio 1
	s_waitcnt lgkmcnt(0)
	v_mfma_f32_16x16x32_bf16 v[124:127], v[134:137], v[176:179], v[124:127]
	v_mfma_f32_16x16x32_bf16 v[116:119], v[152:155], v[176:179], v[116:119]
	v_mfma_f32_16x16x32_bf16 v[108:111], v[134:137], v[194:197], v[108:111]
	v_mfma_f32_16x16x32_bf16 v[100:103], v[152:155], v[194:197], v[100:103]
	v_mfma_f32_16x16x32_bf16 v[92:95], v[134:137], v[202:205], v[92:95]
	v_mfma_f32_16x16x32_bf16 v[84:87], v[152:155], v[202:205], v[84:87]
	v_mfma_f32_16x16x32_bf16 v[76:79], v[134:137], v[210:213], v[76:79]
	v_mfma_f32_16x16x32_bf16 v[68:71], v[152:155], v[210:213], v[68:71]
	v_mfma_f32_16x16x32_bf16 v[124:127], v[148:151], v[180:183], v[124:127]
	v_mfma_f32_16x16x32_bf16 v[116:119], v[156:159], v[180:183], v[116:119]
	v_mfma_f32_16x16x32_bf16 v[108:111], v[148:151], v[198:201], v[108:111]
	v_mfma_f32_16x16x32_bf16 v[100:103], v[156:159], v[198:201], v[100:103]
	v_mfma_f32_16x16x32_bf16 v[92:95], v[148:151], v[206:209], v[92:95]
	v_mfma_f32_16x16x32_bf16 v[84:87], v[156:159], v[206:209], v[84:87]
	v_mfma_f32_16x16x32_bf16 v[76:79], v[148:151], v[214:217], v[76:79]
	v_mfma_f32_16x16x32_bf16 v[68:71], v[156:159], v[214:217], v[68:71]
	s_setprio 0
	s_setprio 1
	v_mfma_f32_16x16x32_bf16 v[120:123], v[160:163], v[176:179], v[120:123]
	v_mfma_f32_16x16x32_bf16 v[112:115], v[168:171], v[176:179], v[112:115]
	v_mfma_f32_16x16x32_bf16 v[104:107], v[160:163], v[194:197], v[104:107]
	v_mfma_f32_16x16x32_bf16 v[96:99], v[168:171], v[194:197], v[96:99]
	v_mfma_f32_16x16x32_bf16 v[88:91], v[160:163], v[202:205], v[88:91]
	v_mfma_f32_16x16x32_bf16 v[80:83], v[168:171], v[202:205], v[80:83]
	v_mfma_f32_16x16x32_bf16 v[72:75], v[160:163], v[210:213], v[72:75]
	v_mfma_f32_16x16x32_bf16 v[64:67], v[168:171], v[210:213], v[64:67]
	v_mfma_f32_16x16x32_bf16 v[120:123], v[164:167], v[180:183], v[120:123]
	v_mfma_f32_16x16x32_bf16 v[112:115], v[172:175], v[180:183], v[112:115]
	v_mfma_f32_16x16x32_bf16 v[104:107], v[164:167], v[198:201], v[104:107]
	v_mfma_f32_16x16x32_bf16 v[96:99], v[172:175], v[198:201], v[96:99]
	v_mfma_f32_16x16x32_bf16 v[88:91], v[164:167], v[206:209], v[88:91]
	v_mfma_f32_16x16x32_bf16 v[80:83], v[172:175], v[206:209], v[80:83]
	v_mfma_f32_16x16x32_bf16 v[72:75], v[164:167], v[214:217], v[72:75]
	v_mfma_f32_16x16x32_bf16 v[64:67], v[172:175], v[214:217], v[64:67]
	s_setprio 0
	s_barrier
	s_add_i32 s14, s14, s6
	v_lshl_add_u64 v[220:221], v[138:139], 0, s[56:57]
	s_mov_b32 m0, s14
	ds_read_b128 v[176:179], v146 offset:49152
	ds_read_b128 v[180:183], v146 offset:50176
	ds_read_b128 v[194:197], v146 offset:51200
	ds_read_b128 v[198:201], v146 offset:52224
	ds_read_b128 v[202:205], v146 offset:53248
	ds_read_b128 v[206:209], v146 offset:54272
	ds_read_b128 v[210:213], v146 offset:55296
	ds_read_b128 v[214:217], v146 offset:56320
	global_load_lds_dwordx4 v[220:221], off
	v_lshl_add_u64 v[220:221], v[138:139], 0, s[96:97]
	s_add_i32 m0, s14, 0x2000
	s_add_i32 s14, s15, s6
	global_load_lds_dwordx4 v[220:221], off
	v_lshl_add_u64 v[220:221], v[138:139], 0, s[88:89]
	s_mov_b32 m0, s14
	v_lshl_add_u64 v[138:139], v[138:139], 0, s[68:69]
	global_load_lds_dwordx4 v[220:221], off
	s_add_i32 m0, s14, 0x2000
	s_nop 0
	global_load_lds_dwordx4 v[138:139], off
	v_lshl_add_u64 v[138:139], v[218:219], 0, s[56:57]
	s_mov_b32 m0, s26
	s_nop 0
	global_load_lds_dwordx4 v[138:139], off
	v_lshl_add_u64 v[138:139], v[218:219], 0, s[96:97]
	s_mov_b32 m0, s27
	s_nop 0
	global_load_lds_dwordx4 v[138:139], off
	s_waitcnt vmcnt(14)
	s_waitcnt lgkmcnt(0)
	s_barrier
	s_setprio 1
	s_waitcnt lgkmcnt(0)
	v_mfma_f32_16x16x32_bf16 v[60:63], v[134:137], v[176:179], v[60:63]
	v_mfma_f32_16x16x32_bf16 v[52:55], v[152:155], v[176:179], v[52:55]
	v_mfma_f32_16x16x32_bf16 v[44:47], v[134:137], v[194:197], v[44:47]
	v_mfma_f32_16x16x32_bf16 v[36:39], v[152:155], v[194:197], v[36:39]
	v_mfma_f32_16x16x32_bf16 v[28:31], v[134:137], v[202:205], v[28:31]
	v_mfma_f32_16x16x32_bf16 v[20:23], v[152:155], v[202:205], v[20:23]
	v_mfma_f32_16x16x32_bf16 v[12:15], v[134:137], v[210:213], v[12:15]
	v_mfma_f32_16x16x32_bf16 v[4:7], v[152:155], v[210:213], v[4:7]
	v_mfma_f32_16x16x32_bf16 v[60:63], v[148:151], v[180:183], v[60:63]
	v_mfma_f32_16x16x32_bf16 v[52:55], v[156:159], v[180:183], v[52:55]
	v_mfma_f32_16x16x32_bf16 v[44:47], v[148:151], v[198:201], v[44:47]
	v_mfma_f32_16x16x32_bf16 v[36:39], v[156:159], v[198:201], v[36:39]
	v_mfma_f32_16x16x32_bf16 v[28:31], v[148:151], v[206:209], v[28:31]
	v_mfma_f32_16x16x32_bf16 v[20:23], v[156:159], v[206:209], v[20:23]
	v_mfma_f32_16x16x32_bf16 v[12:15], v[148:151], v[214:217], v[12:15]
	v_mfma_f32_16x16x32_bf16 v[4:7], v[156:159], v[214:217], v[4:7]
	s_setprio 0
	s_setprio 1
	v_mfma_f32_16x16x32_bf16 v[56:59], v[160:163], v[176:179], v[56:59]
	v_mfma_f32_16x16x32_bf16 v[48:51], v[168:171], v[176:179], v[48:51]
	v_mfma_f32_16x16x32_bf16 v[40:43], v[160:163], v[194:197], v[40:43]
	v_mfma_f32_16x16x32_bf16 v[32:35], v[168:171], v[194:197], v[32:35]
	v_mfma_f32_16x16x32_bf16 v[24:27], v[160:163], v[202:205], v[24:27]
	v_mfma_f32_16x16x32_bf16 v[16:19], v[168:171], v[202:205], v[16:19]
	v_mfma_f32_16x16x32_bf16 v[8:11], v[160:163], v[210:213], v[8:11]
	v_mfma_f32_16x16x32_bf16 v[0:3], v[168:171], v[210:213], v[0:3]
	v_mfma_f32_16x16x32_bf16 v[56:59], v[164:167], v[180:183], v[56:59]
	v_mfma_f32_16x16x32_bf16 v[48:51], v[172:175], v[180:183], v[48:51]
	v_mfma_f32_16x16x32_bf16 v[40:43], v[164:167], v[198:201], v[40:43]
	v_mfma_f32_16x16x32_bf16 v[32:35], v[172:175], v[198:201], v[32:35]
	v_mfma_f32_16x16x32_bf16 v[24:27], v[164:167], v[206:209], v[24:27]
	v_mfma_f32_16x16x32_bf16 v[16:19], v[172:175], v[206:209], v[16:19]
	v_mfma_f32_16x16x32_bf16 v[8:11], v[164:167], v[214:217], v[8:11]
	v_mfma_f32_16x16x32_bf16 v[0:3], v[172:175], v[214:217], v[0:3]
	s_setprio 0
	s_barrier
	s_add_i32 s51, s51, 2
	s_add_u32 s48, s48, 0x100
	s_addc_u32 s49, s49, 0
	s_add_u32 s16, s16, 0x100
	s_addc_u32 s17, s17, 0
	s_cmp_gt_u32 s51, 13

.LBB0_467:
	s_mov_b32 s101, 1
	s_andn2_b64 vcc, exec, s[8:9]
	s_cbranch_vccnz .LBB0_454
	s_mov_b32 s98, 1
	s_branch .LBB0_454

.Lnostb7:
	s_add_u32 s14, s46, 0xfffc0080
	s_addc_u32 s15, s47, -1
	s_add_i32 s60, 0, 0x10000
	s_cmp_eq_u32 s49, 12
	s_cselect_b32 s15, s31, s15
	s_cselect_b32 s14, s41, s14
	v_add_u32_e32 v135, s60, v143
	s_cselect_b32 s51, s13, s17
	s_cselect_b32 s50, s48, s16
	s_add_i32 s61, 0, 0x14000
	ds_read_b128 v[136:139], v135
	ds_read_b128 v[148:151], v135 offset:1024
	ds_read_b128 v[152:155], v135 offset:2048
	ds_read_b128 v[156:159], v135 offset:3072
	v_add_u32_e32 v135, s61, v143
	ds_read_b128 v[160:163], v135
	ds_read_b128 v[164:167], v135 offset:1024
	ds_read_b128 v[168:171], v135 offset:2048
	ds_read_b128 v[172:175], v135 offset:3072
	v_lshl_add_u64 v[140:141], s[46:47], 0, v[184:185]
	s_add_i32 m0, s19, 0xc000
	ds_read_b128 v[176:179], v147
	ds_read_b128 v[180:183], v147 offset:1024
	ds_read_b128 v[194:197], v147 offset:2048
	ds_read_b128 v[198:201], v147 offset:3072
	ds_read_b128 v[202:205], v147 offset:4096
	ds_read_b128 v[206:209], v147 offset:5120
	ds_read_b128 v[210:213], v147 offset:6144
	ds_read_b128 v[214:217], v147 offset:7168
	global_load_lds_dwordx4 v[140:141], off
	v_lshl_add_u64 v[140:141], v[140:141], 0, s[34:35]
	s_add_i32 m0, s19, 0xe000
	s_nop 0
	global_load_lds_dwordx4 v[140:141], off
	s_cmp_eq_u32 s101, 0
	s_cbranch_scc1 .Lbw7_0s
	s_waitcnt vmcnt(18)
	s_branch .Lbw7_0d

.Lbw7_0d:
	s_waitcnt lgkmcnt(0)
	s_barrier
	s_setprio 1
	s_waitcnt lgkmcnt(0)
	v_mfma_f32_16x16x32_bf16 v[124:127], v[136:139], v[176:179], 0
	v_mfma_f32_16x16x32_bf16 v[116:119], v[152:155], v[176:179], 0
	v_mfma_f32_16x16x32_bf16 v[108:111], v[136:139], v[194:197], 0
	v_mfma_f32_16x16x32_bf16 v[100:103], v[152:155], v[194:197], 0
	v_mfma_f32_16x16x32_bf16 v[92:95], v[136:139], v[202:205], 0
	v_mfma_f32_16x16x32_bf16 v[84:87], v[152:155], v[202:205], 0
	v_mfma_f32_16x16x32_bf16 v[76:79], v[136:139], v[210:213], 0
	v_mfma_f32_16x16x32_bf16 v[68:71], v[152:155], v[210:213], 0
	v_mfma_f32_16x16x32_bf16 v[124:127], v[148:151], v[180:183], v[124:127]
	v_mfma_f32_16x16x32_bf16 v[116:119], v[156:159], v[180:183], v[116:119]
	v_mfma_f32_16x16x32_bf16 v[108:111], v[148:151], v[198:201], v[108:111]
	v_mfma_f32_16x16x32_bf16 v[100:103], v[156:159], v[198:201], v[100:103]
	v_mfma_f32_16x16x32_bf16 v[92:95], v[148:151], v[206:209], v[92:95]
	v_mfma_f32_16x16x32_bf16 v[84:87], v[156:159], v[206:209], v[84:87]
	v_mfma_f32_16x16x32_bf16 v[76:79], v[148:151], v[214:217], v[76:79]
	v_mfma_f32_16x16x32_bf16 v[68:71], v[156:159], v[214:217], v[68:71]
	s_setprio 0
	s_setprio 1
	v_mfma_f32_16x16x32_bf16 v[120:123], v[160:163], v[176:179], 0
	v_mfma_f32_16x16x32_bf16 v[112:115], v[168:171], v[176:179], 0
	v_mfma_f32_16x16x32_bf16 v[104:107], v[160:163], v[194:197], 0
	v_mfma_f32_16x16x32_bf16 v[96:99], v[168:171], v[194:197], 0
	v_mfma_f32_16x16x32_bf16 v[88:91], v[160:163], v[202:205], 0
	v_mfma_f32_16x16x32_bf16 v[80:83], v[168:171], v[202:205], 0
	v_mfma_f32_16x16x32_bf16 v[72:75], v[160:163], v[210:213], 0
	v_mfma_f32_16x16x32_bf16 v[64:67], v[168:171], v[210:213], 0
	v_mfma_f32_16x16x32_bf16 v[120:123], v[164:167], v[180:183], v[120:123]
	v_mfma_f32_16x16x32_bf16 v[112:115], v[172:175], v[180:183], v[112:115]
	v_mfma_f32_16x16x32_bf16 v[104:107], v[164:167], v[198:201], v[104:107]
	v_mfma_f32_16x16x32_bf16 v[96:99], v[172:175], v[198:201], v[96:99]
	v_mfma_f32_16x16x32_bf16 v[88:91], v[164:167], v[206:209], v[88:91]
	v_mfma_f32_16x16x32_bf16 v[80:83], v[172:175], v[206:209], v[80:83]
	v_mfma_f32_16x16x32_bf16 v[72:75], v[164:167], v[214:217], v[72:75]
	v_mfma_f32_16x16x32_bf16 v[64:67], v[172:175], v[214:217], v[64:67]
	s_setprio 0
	s_barrier
	v_lshl_add_u64 v[140:141], s[50:51], 0, v[128:129]
	s_add_i32 s50, s60, s6
	s_mov_b32 m0, s50
	ds_read_b128 v[176:179], v147 offset:16384
	ds_read_b128 v[180:183], v147 offset:17408
	ds_read_b128 v[194:197], v147 offset:18432
	ds_read_b128 v[198:201], v147 offset:19456
	ds_read_b128 v[202:205], v147 offset:20480
	ds_read_b128 v[206:209], v147 offset:21504
	ds_read_b128 v[210:213], v147 offset:22528
	ds_read_b128 v[214:217], v147 offset:23552
	global_load_lds_dwordx4 v[140:141], off
	v_lshl_add_u64 v[218:219], v[140:141], 0, s[34:35]
	s_add_i32 m0, s50, 0x2000
	s_add_i32 s50, s61, s6
	global_load_lds_dwordx4 v[218:219], off
	v_lshl_add_u64 v[218:219], v[140:141], 0, s[92:93]
	s_mov_b32 m0, s50
	s_nop 0
	global_load_lds_dwordx4 v[218:219], off
	v_lshl_add_u64 v[218:219], v[140:141], 0, s[52:53]
	s_add_i32 m0, s50, 0x2000
	s_nop 0
	global_load_lds_dwordx4 v[218:219], off
	v_lshl_add_u64 v[218:219], s[14:15], 0, v[130:131]
	s_mov_b32 m0, s19
	v_lshl_add_u64 v[220:221], v[218:219], 0, s[34:35]
	global_load_lds_dwordx4 v[218:219], off
	s_mov_b32 m0, s20
	s_nop 0
	global_load_lds_dwordx4 v[220:221], off
	s_cmp_eq_u32 s101, 0
	s_cbranch_scc1 .Lbw7_1s
	s_waitcnt vmcnt(22)
	s_branch .Lbw7_1d

.Lbw7_1d:
	s_waitcnt lgkmcnt(0)
	s_barrier
	s_setprio 1
	s_waitcnt lgkmcnt(0)
	v_mfma_f32_16x16x32_bf16 v[60:63], v[136:139], v[176:179], 0
	v_mfma_f32_16x16x32_bf16 v[52:55], v[152:155], v[176:179], 0
	v_mfma_f32_16x16x32_bf16 v[44:47], v[136:139], v[194:197], 0
	v_mfma_f32_16x16x32_bf16 v[36:39], v[152:155], v[194:197], 0
	v_mfma_f32_16x16x32_bf16 v[28:31], v[136:139], v[202:205], 0
	v_mfma_f32_16x16x32_bf16 v[20:23], v[152:155], v[202:205], 0
	v_mfma_f32_16x16x32_bf16 v[12:15], v[136:139], v[210:213], 0
	v_mfma_f32_16x16x32_bf16 v[4:7], v[152:155], v[210:213], 0
	v_mfma_f32_16x16x32_bf16 v[60:63], v[148:151], v[180:183], v[60:63]
	v_mfma_f32_16x16x32_bf16 v[52:55], v[156:159], v[180:183], v[52:55]
	v_mfma_f32_16x16x32_bf16 v[44:47], v[148:151], v[198:201], v[44:47]
	v_mfma_f32_16x16x32_bf16 v[36:39], v[156:159], v[198:201], v[36:39]
	v_mfma_f32_16x16x32_bf16 v[28:31], v[148:151], v[206:209], v[28:31]
	v_mfma_f32_16x16x32_bf16 v[20:23], v[156:159], v[206:209], v[20:23]
	v_mfma_f32_16x16x32_bf16 v[12:15], v[148:151], v[214:217], v[12:15]
	v_mfma_f32_16x16x32_bf16 v[4:7], v[156:159], v[214:217], v[4:7]
	s_setprio 0
	s_setprio 1
	v_mfma_f32_16x16x32_bf16 v[56:59], v[160:163], v[176:179], 0
	v_mfma_f32_16x16x32_bf16 v[48:51], v[168:171], v[176:179], 0
	v_mfma_f32_16x16x32_bf16 v[40:43], v[160:163], v[194:197], 0
	v_mfma_f32_16x16x32_bf16 v[32:35], v[168:171], v[194:197], 0
	v_mfma_f32_16x16x32_bf16 v[24:27], v[160:163], v[202:205], 0
	v_mfma_f32_16x16x32_bf16 v[16:19], v[168:171], v[202:205], 0
	v_mfma_f32_16x16x32_bf16 v[8:11], v[160:163], v[210:213], 0
	v_mfma_f32_16x16x32_bf16 v[0:3], v[168:171], v[210:213], 0
	v_mfma_f32_16x16x32_bf16 v[56:59], v[164:167], v[180:183], v[56:59]
	v_mfma_f32_16x16x32_bf16 v[48:51], v[172:175], v[180:183], v[48:51]
	v_mfma_f32_16x16x32_bf16 v[40:43], v[164:167], v[198:201], v[40:43]
	v_mfma_f32_16x16x32_bf16 v[32:35], v[172:175], v[198:201], v[32:35]
	v_mfma_f32_16x16x32_bf16 v[24:27], v[164:167], v[206:209], v[24:27]
	v_mfma_f32_16x16x32_bf16 v[16:19], v[172:175], v[206:209], v[16:19]
	v_mfma_f32_16x16x32_bf16 v[8:11], v[164:167], v[214:217], v[8:11]
	v_mfma_f32_16x16x32_bf16 v[0:3], v[172:175], v[214:217], v[0:3]
	s_setprio 0
	s_barrier
	s_add_i32 s14, 0, 0x18000
	v_add_u32_e32 v135, s14, v143
	s_add_i32 s15, 0, 0x1c000
	ds_read_b128 v[136:139], v135
	ds_read_b128 v[148:151], v135 offset:1024
	ds_read_b128 v[152:155], v135 offset:2048
	ds_read_b128 v[156:159], v135 offset:3072
	v_add_u32_e32 v135, s15, v143
	ds_read_b128 v[160:163], v135
	ds_read_b128 v[164:167], v135 offset:1024
	ds_read_b128 v[168:171], v135 offset:2048
	ds_read_b128 v[172:175], v135 offset:3072
	s_mov_b32 m0, s24
	v_lshl_add_u64 v[220:221], v[218:219], 0, s[92:93]
	ds_read_b128 v[176:179], v147 offset:32768
	ds_read_b128 v[180:183], v147 offset:33792
	ds_read_b128 v[194:197], v147 offset:34816
	ds_read_b128 v[198:201], v147 offset:35840
	ds_read_b128 v[202:205], v147 offset:36864
	ds_read_b128 v[206:209], v147 offset:37888
	ds_read_b128 v[210:213], v147 offset:38912
	ds_read_b128 v[214:217], v147 offset:39936
	global_load_lds_dwordx4 v[220:221], off
	v_lshl_add_u64 v[220:221], v[218:219], 0, s[52:53]
	s_mov_b32 m0, s25
	s_nop 0
	global_load_lds_dwordx4 v[220:221], off
	s_cmp_eq_u32 s101, 0
	s_cbranch_scc1 .Lbw7_2s
	s_waitcnt vmcnt(18)
	s_branch .Lbw7_2d

.Lbw7_2d:
	s_waitcnt lgkmcnt(0)
	s_barrier
	s_setprio 1
	s_waitcnt lgkmcnt(0)
	v_mfma_f32_16x16x32_bf16 v[124:127], v[136:139], v[176:179], v[124:127]
	v_mfma_f32_16x16x32_bf16 v[116:119], v[152:155], v[176:179], v[116:119]
	v_mfma_f32_16x16x32_bf16 v[108:111], v[136:139], v[194:197], v[108:111]
	v_mfma_f32_16x16x32_bf16 v[100:103], v[152:155], v[194:197], v[100:103]
	v_mfma_f32_16x16x32_bf16 v[92:95], v[136:139], v[202:205], v[92:95]
	v_mfma_f32_16x16x32_bf16 v[84:87], v[152:155], v[202:205], v[84:87]
	v_mfma_f32_16x16x32_bf16 v[76:79], v[136:139], v[210:213], v[76:79]
	v_mfma_f32_16x16x32_bf16 v[68:71], v[152:155], v[210:213], v[68:71]
	v_mfma_f32_16x16x32_bf16 v[124:127], v[148:151], v[180:183], v[124:127]
	v_mfma_f32_16x16x32_bf16 v[116:119], v[156:159], v[180:183], v[116:119]
	v_mfma_f32_16x16x32_bf16 v[108:111], v[148:151], v[198:201], v[108:111]
	v_mfma_f32_16x16x32_bf16 v[100:103], v[156:159], v[198:201], v[100:103]
	v_mfma_f32_16x16x32_bf16 v[92:95], v[148:151], v[206:209], v[92:95]
	v_mfma_f32_16x16x32_bf16 v[84:87], v[156:159], v[206:209], v[84:87]
	v_mfma_f32_16x16x32_bf16 v[76:79], v[148:151], v[214:217], v[76:79]
	v_mfma_f32_16x16x32_bf16 v[68:71], v[156:159], v[214:217], v[68:71]
	s_setprio 0
	s_setprio 1
	v_mfma_f32_16x16x32_bf16 v[120:123], v[160:163], v[176:179], v[120:123]
	v_mfma_f32_16x16x32_bf16 v[112:115], v[168:171], v[176:179], v[112:115]
	v_mfma_f32_16x16x32_bf16 v[104:107], v[160:163], v[194:197], v[104:107]
	v_mfma_f32_16x16x32_bf16 v[96:99], v[168:171], v[194:197], v[96:99]
	v_mfma_f32_16x16x32_bf16 v[88:91], v[160:163], v[202:205], v[88:91]
	v_mfma_f32_16x16x32_bf16 v[80:83], v[168:171], v[202:205], v[80:83]
	v_mfma_f32_16x16x32_bf16 v[72:75], v[160:163], v[210:213], v[72:75]
	v_mfma_f32_16x16x32_bf16 v[64:67], v[168:171], v[210:213], v[64:67]
	v_mfma_f32_16x16x32_bf16 v[120:123], v[164:167], v[180:183], v[120:123]
	v_mfma_f32_16x16x32_bf16 v[112:115], v[172:175], v[180:183], v[112:115]
	v_mfma_f32_16x16x32_bf16 v[104:107], v[164:167], v[198:201], v[104:107]
	v_mfma_f32_16x16x32_bf16 v[96:99], v[172:175], v[198:201], v[96:99]
	v_mfma_f32_16x16x32_bf16 v[88:91], v[164:167], v[206:209], v[88:91]
	v_mfma_f32_16x16x32_bf16 v[80:83], v[172:175], v[206:209], v[80:83]
	v_mfma_f32_16x16x32_bf16 v[72:75], v[164:167], v[214:217], v[72:75]
	v_mfma_f32_16x16x32_bf16 v[64:67], v[172:175], v[214:217], v[64:67]
	s_setprio 0
	s_barrier
	s_add_i32 s14, s14, s6
	v_lshl_add_u64 v[220:221], v[140:141], 0, s[56:57]
	s_mov_b32 m0, s14
	ds_read_b128 v[176:179], v147 offset:49152
	ds_read_b128 v[180:183], v147 offset:50176
	ds_read_b128 v[194:197], v147 offset:51200
	ds_read_b128 v[198:201], v147 offset:52224
	ds_read_b128 v[202:205], v147 offset:53248
	ds_read_b128 v[206:209], v147 offset:54272
	ds_read_b128 v[210:213], v147 offset:55296
	ds_read_b128 v[214:217], v147 offset:56320
	global_load_lds_dwordx4 v[220:221], off
	v_lshl_add_u64 v[220:221], v[140:141], 0, s[96:97]
	s_add_i32 m0, s14, 0x2000
	s_add_i32 s14, s15, s6
	global_load_lds_dwordx4 v[220:221], off
	v_lshl_add_u64 v[220:221], v[140:141], 0, s[88:89]
	s_mov_b32 m0, s14
	v_lshl_add_u64 v[140:141], v[140:141], 0, s[68:69]
	global_load_lds_dwordx4 v[220:221], off
	s_add_i32 m0, s14, 0x2000
	s_nop 0
	global_load_lds_dwordx4 v[140:141], off
	v_lshl_add_u64 v[140:141], v[218:219], 0, s[56:57]
	s_mov_b32 m0, s26
	s_nop 0
	global_load_lds_dwordx4 v[140:141], off
	v_lshl_add_u64 v[140:141], v[218:219], 0, s[96:97]
	s_mov_b32 m0, s27
	s_nop 0
	global_load_lds_dwordx4 v[140:141], off
	s_waitcnt vmcnt(14)
	s_waitcnt lgkmcnt(0)
	s_barrier
	s_setprio 1
	s_waitcnt lgkmcnt(0)
	v_mfma_f32_16x16x32_bf16 v[60:63], v[136:139], v[176:179], v[60:63]
	v_mfma_f32_16x16x32_bf16 v[52:55], v[152:155], v[176:179], v[52:55]
	v_mfma_f32_16x16x32_bf16 v[44:47], v[136:139], v[194:197], v[44:47]
	v_mfma_f32_16x16x32_bf16 v[36:39], v[152:155], v[194:197], v[36:39]
	v_mfma_f32_16x16x32_bf16 v[28:31], v[136:139], v[202:205], v[28:31]
	v_mfma_f32_16x16x32_bf16 v[20:23], v[152:155], v[202:205], v[20:23]
	v_mfma_f32_16x16x32_bf16 v[12:15], v[136:139], v[210:213], v[12:15]
	v_mfma_f32_16x16x32_bf16 v[4:7], v[152:155], v[210:213], v[4:7]
	v_mfma_f32_16x16x32_bf16 v[60:63], v[148:151], v[180:183], v[60:63]
	v_mfma_f32_16x16x32_bf16 v[52:55], v[156:159], v[180:183], v[52:55]
	v_mfma_f32_16x16x32_bf16 v[44:47], v[148:151], v[198:201], v[44:47]
	v_mfma_f32_16x16x32_bf16 v[36:39], v[156:159], v[198:201], v[36:39]
	v_mfma_f32_16x16x32_bf16 v[28:31], v[148:151], v[206:209], v[28:31]
	v_mfma_f32_16x16x32_bf16 v[20:23], v[156:159], v[206:209], v[20:23]
	v_mfma_f32_16x16x32_bf16 v[12:15], v[148:151], v[214:217], v[12:15]
	v_mfma_f32_16x16x32_bf16 v[4:7], v[156:159], v[214:217], v[4:7]
	s_setprio 0
	s_setprio 1
	v_mfma_f32_16x16x32_bf16 v[56:59], v[160:163], v[176:179], v[56:59]
	v_mfma_f32_16x16x32_bf16 v[48:51], v[168:171], v[176:179], v[48:51]
	v_mfma_f32_16x16x32_bf16 v[40:43], v[160:163], v[194:197], v[40:43]
	v_mfma_f32_16x16x32_bf16 v[32:35], v[168:171], v[194:197], v[32:35]
	v_mfma_f32_16x16x32_bf16 v[24:27], v[160:163], v[202:205], v[24:27]
	v_mfma_f32_16x16x32_bf16 v[16:19], v[168:171], v[202:205], v[16:19]
	v_mfma_f32_16x16x32_bf16 v[8:11], v[160:163], v[210:213], v[8:11]
	v_mfma_f32_16x16x32_bf16 v[0:3], v[168:171], v[210:213], v[0:3]
	v_mfma_f32_16x16x32_bf16 v[56:59], v[164:167], v[180:183], v[56:59]
	v_mfma_f32_16x16x32_bf16 v[48:51], v[172:175], v[180:183], v[48:51]
	v_mfma_f32_16x16x32_bf16 v[40:43], v[164:167], v[198:201], v[40:43]
	v_mfma_f32_16x16x32_bf16 v[32:35], v[172:175], v[198:201], v[32:35]
	v_mfma_f32_16x16x32_bf16 v[24:27], v[164:167], v[206:209], v[24:27]
	v_mfma_f32_16x16x32_bf16 v[16:19], v[172:175], v[206:209], v[16:19]
	v_mfma_f32_16x16x32_bf16 v[8:11], v[164:167], v[214:217], v[8:11]
	v_mfma_f32_16x16x32_bf16 v[0:3], v[172:175], v[214:217], v[0:3]
	s_setprio 0
	s_barrier
	s_add_i32 s49, s49, 2
	s_add_u32 s46, s46, 0x100
	s_addc_u32 s47, s47, 0
	s_add_u32 s16, s16, 0x100
	s_addc_u32 s17, s17, 0
	s_cmp_gt_u32 s49, 13

.LBB0_486:
	s_or_b64 exec, exec, s[14:15]
	s_waitcnt lgkmcnt(0)
	s_barrier
	ds_read2_b32 v[150:151], v145 offset1:16
	ds_read2_b32 v[140:141], v145 offset0:32 offset1:48
	ds_read2_b32 v[138:139], v145 offset0:128 offset1:144
	ds_read2_b32 v[136:137], v145 offset0:160 offset1:176
	v_pk_mul_f32 v[120:121], v[124:125], v[120:121]
	s_waitcnt lgkmcnt(0)
	v_mul_f32_e32 v152, 0xbfb8aa3b, v150
	v_pk_mul_f32 v[154:155], v[124:125], v[152:153] op_sel_hi:[1,0]
	v_pk_mul_f32 v[124:125], v[126:127], v[152:153] op_sel_hi:[1,0]
	v_mul_f32_e32 v150, v150, v150
	v_exp_f32_e32 v124, v124
	v_exp_f32_e32 v125, v125
	v_pk_mul_f32 v[122:123], v[126:127], v[122:123]
	v_pk_mul_f32 v[112:113], v[116:117], v[112:113]
	v_pk_mul_f32 v[122:123], v[122:123], v[150:151] op_sel_hi:[1,0]
	v_pk_add_f32 v[124:125], v[124:125], 1.0 op_sel_hi:[1,0]
	v_exp_f32_e32 v154, v154
	v_rcp_f32_e32 v124, v124
	v_rcp_f32_e32 v125, v125
	v_exp_f32_e32 v155, v155
	v_pk_mul_f32 v[114:115], v[118:119], v[114:115]
	v_pk_mul_f32 v[120:121], v[120:121], v[150:151] op_sel_hi:[1,0]
	v_pk_mul_f32 v[122:123], v[122:123], v[124:125]
	v_pk_mul_f32 v[124:125], v[116:117], v[152:153] op_sel_hi:[1,0]
	v_pk_mul_f32 v[116:117], v[118:119], v[152:153] op_sel_hi:[1,0]
	v_exp_f32_e32 v124, v124
	v_exp_f32_e32 v125, v125
	v_exp_f32_e32 v116, v116
	v_exp_f32_e32 v117, v117
	v_pk_add_f32 v[154:155], v[154:155], 1.0 op_sel_hi:[1,0]
	v_pk_add_f32 v[124:125], v[124:125], 1.0 op_sel_hi:[1,0]
	v_rcp_f32_e32 v154, v154
	v_pk_add_f32 v[116:117], v[116:117], 1.0 op_sel_hi:[1,0]
	v_rcp_f32_e32 v155, v155
	v_rcp_f32_e32 v124, v124
	v_rcp_f32_e32 v125, v125
	v_rcp_f32_e32 v116, v116
	v_rcp_f32_e32 v117, v117
	v_pk_mul_f32 v[112:113], v[112:113], v[150:151] op_sel_hi:[1,0]
	v_pk_mul_f32 v[114:115], v[114:115], v[150:151] op_sel_hi:[1,0]
	v_pk_mul_f32 v[120:121], v[120:121], v[154:155]
	v_pk_mul_f32 v[112:113], v[112:113], v[124:125]
	v_pk_mul_f32 v[114:115], v[114:115], v[116:117]
	v_mov_b32_e32 v116, 0
	v_mov_b32_e32 v117, 0
	v_cvt_pk_fp8_f32 v116, v120, v121
	v_cvt_pk_fp8_f32 v117, v112, v113
	v_lshl_add_u32 v148, s30, 8, v142
	v_lshl_or_b32 v134, s29, 7, v146
	v_cvt_pk_fp8_f32 v116, v122, v123 op_sel:[0,0,1]
	v_cvt_pk_fp8_f32 v117, v114, v115 op_sel:[0,0,1]
	v_mov_b64_e32 v[112:113], s[72:73]
	v_ashrrev_i32_e32 v135, 31, v134
	v_mad_i64_i32 v[114:115], s[14:15], v148, s18, v[112:113]
	v_lshl_add_u64 v[114:115], v[114:115], 0, v[134:135]
	global_store_dwordx2 v[114:115], v[116:117], off
	v_mul_f32_e32 v114, 0xbfb8aa3b, v151
	v_pk_mul_f32 v[118:119], v[108:109], v[114:115] op_sel_hi:[1,0]
	v_pk_mul_f32 v[104:105], v[108:109], v[104:105]
	v_pk_mul_f32 v[108:109], v[110:111], v[114:115] op_sel_hi:[1,0]
	v_mul_f32_e32 v116, v151, v151
	v_exp_f32_e32 v108, v108
	v_exp_f32_e32 v109, v109
	v_pk_mul_f32 v[106:107], v[110:111], v[106:107]
	v_pk_mul_f32 v[96:97], v[100:101], v[96:97]
	v_pk_mul_f32 v[106:107], v[106:107], v[116:117] op_sel_hi:[1,0]
	v_pk_add_f32 v[108:109], v[108:109], 1.0 op_sel_hi:[1,0]
	v_exp_f32_e32 v118, v118
	v_rcp_f32_e32 v108, v108
	v_rcp_f32_e32 v109, v109
	v_exp_f32_e32 v119, v119
	v_pk_mul_f32 v[98:99], v[102:103], v[98:99]
	v_pk_mul_f32 v[104:105], v[104:105], v[116:117] op_sel_hi:[1,0]
	v_pk_mul_f32 v[106:107], v[106:107], v[108:109]
	v_pk_mul_f32 v[108:109], v[100:101], v[114:115] op_sel_hi:[1,0]
	v_pk_mul_f32 v[100:101], v[102:103], v[114:115] op_sel_hi:[1,0]
	v_exp_f32_e32 v108, v108
	v_exp_f32_e32 v109, v109
	v_exp_f32_e32 v100, v100
	v_exp_f32_e32 v101, v101
	v_pk_add_f32 v[118:119], v[118:119], 1.0 op_sel_hi:[1,0]
	v_pk_add_f32 v[108:109], v[108:109], 1.0 op_sel_hi:[1,0]
	v_rcp_f32_e32 v118, v118
	v_pk_add_f32 v[100:101], v[100:101], 1.0 op_sel_hi:[1,0]
	v_rcp_f32_e32 v119, v119
	v_rcp_f32_e32 v108, v108
	v_rcp_f32_e32 v109, v109
	v_rcp_f32_e32 v100, v100
	v_rcp_f32_e32 v101, v101
	v_pk_mul_f32 v[96:97], v[96:97], v[116:117] op_sel_hi:[1,0]
	v_pk_mul_f32 v[98:99], v[98:99], v[116:117] op_sel_hi:[1,0]
	v_pk_mul_f32 v[104:105], v[104:105], v[118:119]
	v_pk_mul_f32 v[96:97], v[96:97], v[108:109]
	v_pk_mul_f32 v[98:99], v[98:99], v[100:101]
	v_mov_b32_e32 v100, 0
	v_mov_b32_e32 v101, 0
	v_cvt_pk_fp8_f32 v100, v104, v105
	v_cvt_pk_fp8_f32 v101, v96, v97
	v_or_b32_e32 v96, 16, v148
	v_mad_i64_i32 v[96:97], s[14:15], v96, s18, v[112:113]
	v_cvt_pk_fp8_f32 v100, v106, v107 op_sel:[0,0,1]
	v_cvt_pk_fp8_f32 v101, v98, v99 op_sel:[0,0,1]
	v_lshl_add_u64 v[96:97], v[96:97], 0, v[134:135]
	v_pk_mul_f32 v[88:89], v[92:93], v[88:89]
	v_mul_f32_e32 v98, v140, v140
	global_store_dwordx2 v[96:97], v[100:101], off
	v_mul_f32_e32 v96, 0xbfb8aa3b, v140
	v_pk_mul_f32 v[100:101], v[92:93], v[96:97] op_sel_hi:[1,0]
	v_pk_mul_f32 v[92:93], v[94:95], v[96:97] op_sel_hi:[1,0]
	v_pk_mul_f32 v[90:91], v[94:95], v[90:91]
	v_exp_f32_e32 v92, v92
	v_exp_f32_e32 v93, v93
	v_pk_mul_f32 v[90:91], v[90:91], v[98:99] op_sel_hi:[1,0]
	v_pk_mul_f32 v[80:81], v[84:85], v[80:81]
	v_exp_f32_e32 v100, v100
	v_pk_add_f32 v[92:93], v[92:93], 1.0 op_sel_hi:[1,0]
	v_exp_f32_e32 v101, v101
	v_rcp_f32_e32 v92, v92
	v_rcp_f32_e32 v93, v93
	v_pk_mul_f32 v[82:83], v[86:87], v[82:83]
	v_pk_add_f32 v[100:101], v[100:101], 1.0 op_sel_hi:[1,0]
	v_pk_mul_f32 v[88:89], v[88:89], v[98:99] op_sel_hi:[1,0]
	v_pk_mul_f32 v[90:91], v[90:91], v[92:93]
	v_pk_mul_f32 v[92:93], v[84:85], v[96:97] op_sel_hi:[1,0]
	v_pk_mul_f32 v[84:85], v[86:87], v[96:97] op_sel_hi:[1,0]
	v_exp_f32_e32 v92, v92
	v_exp_f32_e32 v93, v93
	v_exp_f32_e32 v84, v84
	v_exp_f32_e32 v85, v85
	v_rcp_f32_e32 v100, v100
	v_pk_add_f32 v[92:93], v[92:93], 1.0 op_sel_hi:[1,0]
	v_rcp_f32_e32 v101, v101
	v_pk_add_f32 v[84:85], v[84:85], 1.0 op_sel_hi:[1,0]
	v_rcp_f32_e32 v92, v92
	v_rcp_f32_e32 v93, v93
	v_rcp_f32_e32 v84, v84
	v_rcp_f32_e32 v85, v85
	v_pk_mul_f32 v[80:81], v[80:81], v[98:99] op_sel_hi:[1,0]
	v_pk_mul_f32 v[82:83], v[82:83], v[98:99] op_sel_hi:[1,0]
	v_pk_mul_f32 v[88:89], v[88:89], v[100:101]
	v_pk_mul_f32 v[80:81], v[80:81], v[92:93]
	v_pk_mul_f32 v[82:83], v[82:83], v[84:85]
	v_mov_b32_e32 v84, 0
	v_mov_b32_e32 v85, 0
	v_cvt_pk_fp8_f32 v84, v88, v89
	v_cvt_pk_fp8_f32 v85, v80, v81
	v_or_b32_e32 v80, 32, v148
	v_mad_i64_i32 v[80:81], s[14:15], v80, s18, v[112:113]
	v_cvt_pk_fp8_f32 v84, v90, v91 op_sel:[0,0,1]
	v_cvt_pk_fp8_f32 v85, v82, v83 op_sel:[0,0,1]
	v_lshl_add_u64 v[80:81], v[80:81], 0, v[134:135]
	v_pk_mul_f32 v[72:73], v[76:77], v[72:73]
	v_mul_f32_e32 v82, v141, v141
	global_store_dwordx2 v[80:81], v[84:85], off
	v_mul_f32_e32 v80, 0xbfb8aa3b, v141
	v_pk_mul_f32 v[84:85], v[76:77], v[80:81] op_sel_hi:[1,0]
	v_pk_mul_f32 v[76:77], v[78:79], v[80:81] op_sel_hi:[1,0]
	v_pk_mul_f32 v[74:75], v[78:79], v[74:75]
	v_exp_f32_e32 v76, v76
	v_exp_f32_e32 v77, v77
	v_pk_mul_f32 v[74:75], v[74:75], v[82:83] op_sel_hi:[1,0]
	v_pk_mul_f32 v[64:65], v[68:69], v[64:65]
	v_exp_f32_e32 v84, v84
	v_pk_add_f32 v[76:77], v[76:77], 1.0 op_sel_hi:[1,0]
	v_exp_f32_e32 v85, v85
	v_rcp_f32_e32 v76, v76
	v_rcp_f32_e32 v77, v77
	v_pk_mul_f32 v[66:67], v[70:71], v[66:67]
	v_pk_add_f32 v[84:85], v[84:85], 1.0 op_sel_hi:[1,0]
	v_pk_mul_f32 v[72:73], v[72:73], v[82:83] op_sel_hi:[1,0]
	v_pk_mul_f32 v[74:75], v[74:75], v[76:77]
	v_pk_mul_f32 v[76:77], v[68:69], v[80:81] op_sel_hi:[1,0]
	v_pk_mul_f32 v[68:69], v[70:71], v[80:81] op_sel_hi:[1,0]
	v_exp_f32_e32 v76, v76
	v_exp_f32_e32 v77, v77
	v_exp_f32_e32 v68, v68
	v_exp_f32_e32 v69, v69
	v_rcp_f32_e32 v84, v84
	v_pk_add_f32 v[76:77], v[76:77], 1.0 op_sel_hi:[1,0]
	v_rcp_f32_e32 v85, v85
	v_pk_add_f32 v[68:69], v[68:69], 1.0 op_sel_hi:[1,0]
	v_rcp_f32_e32 v76, v76
	v_rcp_f32_e32 v77, v77
	v_rcp_f32_e32 v68, v68
	v_rcp_f32_e32 v69, v69
	v_pk_mul_f32 v[64:65], v[64:65], v[82:83] op_sel_hi:[1,0]
	v_pk_mul_f32 v[66:67], v[66:67], v[82:83] op_sel_hi:[1,0]
	v_pk_mul_f32 v[72:73], v[72:73], v[84:85]
	v_pk_mul_f32 v[64:65], v[64:65], v[76:77]
	v_pk_mul_f32 v[66:67], v[66:67], v[68:69]
	v_mov_b32_e32 v68, 0
	v_mov_b32_e32 v69, 0
	v_cvt_pk_fp8_f32 v68, v72, v73
	v_cvt_pk_fp8_f32 v69, v64, v65
	v_or_b32_e32 v64, 48, v148
	v_mad_i64_i32 v[64:65], s[14:15], v64, s18, v[112:113]
	v_cvt_pk_fp8_f32 v68, v74, v75 op_sel:[0,0,1]
	v_cvt_pk_fp8_f32 v69, v66, v67 op_sel:[0,0,1]
	v_lshl_add_u64 v[64:65], v[64:65], 0, v[134:135]
	v_pk_mul_f32 v[56:57], v[60:61], v[56:57]
	v_mul_f32_e32 v66, v138, v138
	global_store_dwordx2 v[64:65], v[68:69], off
	v_add_u32_e32 v65, 0x80, v148
	v_mul_f32_e32 v64, 0xbfb8aa3b, v138
	v_pk_mul_f32 v[68:69], v[60:61], v[64:65] op_sel_hi:[1,0]
	v_pk_mul_f32 v[60:61], v[62:63], v[64:65] op_sel_hi:[1,0]
	v_pk_mul_f32 v[58:59], v[62:63], v[58:59]
	v_exp_f32_e32 v60, v60
	v_exp_f32_e32 v61, v61
	v_pk_mul_f32 v[58:59], v[58:59], v[66:67] op_sel_hi:[1,0]
	v_pk_mul_f32 v[48:49], v[52:53], v[48:49]
	v_exp_f32_e32 v68, v68
	v_pk_add_f32 v[60:61], v[60:61], 1.0 op_sel_hi:[1,0]
	v_exp_f32_e32 v69, v69
	v_rcp_f32_e32 v60, v60
	v_rcp_f32_e32 v61, v61
	v_pk_mul_f32 v[50:51], v[54:55], v[50:51]
	v_pk_add_f32 v[68:69], v[68:69], 1.0 op_sel_hi:[1,0]
	v_pk_mul_f32 v[56:57], v[56:57], v[66:67] op_sel_hi:[1,0]
	v_pk_mul_f32 v[58:59], v[58:59], v[60:61]
	v_pk_mul_f32 v[60:61], v[52:53], v[64:65] op_sel_hi:[1,0]
	v_pk_mul_f32 v[52:53], v[54:55], v[64:65] op_sel_hi:[1,0]
	v_exp_f32_e32 v60, v60
	v_exp_f32_e32 v61, v61
	v_exp_f32_e32 v52, v52
	v_exp_f32_e32 v53, v53
	v_rcp_f32_e32 v68, v68
	v_pk_add_f32 v[60:61], v[60:61], 1.0 op_sel_hi:[1,0]
	v_rcp_f32_e32 v69, v69
	v_pk_add_f32 v[52:53], v[52:53], 1.0 op_sel_hi:[1,0]
	v_rcp_f32_e32 v60, v60
	v_rcp_f32_e32 v61, v61
	v_rcp_f32_e32 v52, v52
	v_rcp_f32_e32 v53, v53
	v_pk_mul_f32 v[48:49], v[48:49], v[66:67] op_sel_hi:[1,0]
	v_pk_mul_f32 v[50:51], v[50:51], v[66:67] op_sel_hi:[1,0]
	v_pk_mul_f32 v[56:57], v[56:57], v[68:69]
	v_pk_mul_f32 v[48:49], v[48:49], v[60:61]
	v_pk_mul_f32 v[50:51], v[50:51], v[52:53]
	v_mov_b32_e32 v52, 0
	v_mov_b32_e32 v53, 0
	v_cvt_pk_fp8_f32 v52, v56, v57
	v_cvt_pk_fp8_f32 v53, v48, v49
	v_mad_i64_i32 v[48:49], s[14:15], v65, s18, v[112:113]
	v_cvt_pk_fp8_f32 v52, v58, v59 op_sel:[0,0,1]
	v_cvt_pk_fp8_f32 v53, v50, v51 op_sel:[0,0,1]
	v_lshl_add_u64 v[48:49], v[48:49], 0, v[134:135]
	v_pk_mul_f32 v[40:41], v[44:45], v[40:41]
	v_mul_f32_e32 v50, v139, v139
	global_store_dwordx2 v[48:49], v[52:53], off
	v_mul_f32_e32 v48, 0xbfb8aa3b, v139
	v_pk_mul_f32 v[52:53], v[44:45], v[48:49] op_sel_hi:[1,0]
	v_pk_mul_f32 v[44:45], v[46:47], v[48:49] op_sel_hi:[1,0]
	v_pk_mul_f32 v[42:43], v[46:47], v[42:43]
	v_exp_f32_e32 v44, v44
	v_exp_f32_e32 v45, v45
	v_pk_mul_f32 v[42:43], v[42:43], v[50:51] op_sel_hi:[1,0]
	v_pk_mul_f32 v[32:33], v[36:37], v[32:33]
	v_exp_f32_e32 v52, v52
	v_pk_add_f32 v[44:45], v[44:45], 1.0 op_sel_hi:[1,0]
	v_exp_f32_e32 v53, v53
	v_rcp_f32_e32 v44, v44
	v_rcp_f32_e32 v45, v45
	v_pk_mul_f32 v[34:35], v[38:39], v[34:35]
	v_pk_add_f32 v[52:53], v[52:53], 1.0 op_sel_hi:[1,0]
	v_pk_mul_f32 v[40:41], v[40:41], v[50:51] op_sel_hi:[1,0]
	v_pk_mul_f32 v[42:43], v[42:43], v[44:45]
	v_pk_mul_f32 v[44:45], v[36:37], v[48:49] op_sel_hi:[1,0]
	v_pk_mul_f32 v[36:37], v[38:39], v[48:49] op_sel_hi:[1,0]
	v_exp_f32_e32 v44, v44
	v_exp_f32_e32 v45, v45
	v_exp_f32_e32 v36, v36
	v_exp_f32_e32 v37, v37
	v_rcp_f32_e32 v52, v52
	v_pk_add_f32 v[44:45], v[44:45], 1.0 op_sel_hi:[1,0]
	v_rcp_f32_e32 v53, v53
	v_pk_add_f32 v[36:37], v[36:37], 1.0 op_sel_hi:[1,0]
	v_rcp_f32_e32 v44, v44
	v_rcp_f32_e32 v45, v45
	v_rcp_f32_e32 v36, v36
	v_rcp_f32_e32 v37, v37
	v_pk_mul_f32 v[32:33], v[32:33], v[50:51] op_sel_hi:[1,0]
	v_pk_mul_f32 v[34:35], v[34:35], v[50:51] op_sel_hi:[1,0]
	v_pk_mul_f32 v[40:41], v[40:41], v[52:53]
	v_pk_mul_f32 v[32:33], v[32:33], v[44:45]
	v_pk_mul_f32 v[34:35], v[34:35], v[36:37]
	v_mov_b32_e32 v36, 0
	v_mov_b32_e32 v37, 0
	v_cvt_pk_fp8_f32 v36, v40, v41
	v_cvt_pk_fp8_f32 v37, v32, v33
	v_add_u32_e32 v32, 0x90, v148
	v_mad_i64_i32 v[32:33], s[14:15], v32, s18, v[112:113]
	v_cvt_pk_fp8_f32 v36, v42, v43 op_sel:[0,0,1]
	v_cvt_pk_fp8_f32 v37, v34, v35 op_sel:[0,0,1]
	v_lshl_add_u64 v[32:33], v[32:33], 0, v[134:135]
	v_pk_mul_f32 v[24:25], v[28:29], v[24:25]
	v_mul_f32_e32 v34, v136, v136
	global_store_dwordx2 v[32:33], v[36:37], off
	v_mul_f32_e32 v32, 0xbfb8aa3b, v136
	v_pk_mul_f32 v[36:37], v[28:29], v[32:33] op_sel_hi:[1,0]
	v_pk_mul_f32 v[28:29], v[30:31], v[32:33] op_sel_hi:[1,0]
	v_pk_mul_f32 v[26:27], v[30:31], v[26:27]
	v_exp_f32_e32 v28, v28
	v_exp_f32_e32 v29, v29
	v_pk_mul_f32 v[26:27], v[26:27], v[34:35] op_sel_hi:[1,0]
	v_pk_mul_f32 v[16:17], v[20:21], v[16:17]
	v_exp_f32_e32 v36, v36
	v_pk_add_f32 v[28:29], v[28:29], 1.0 op_sel_hi:[1,0]
	v_exp_f32_e32 v37, v37
	v_rcp_f32_e32 v28, v28
	v_rcp_f32_e32 v29, v29
	v_pk_mul_f32 v[18:19], v[22:23], v[18:19]
	v_pk_add_f32 v[36:37], v[36:37], 1.0 op_sel_hi:[1,0]
	v_pk_mul_f32 v[24:25], v[24:25], v[34:35] op_sel_hi:[1,0]
	v_pk_mul_f32 v[26:27], v[26:27], v[28:29]
	v_pk_mul_f32 v[28:29], v[20:21], v[32:33] op_sel_hi:[1,0]
	v_pk_mul_f32 v[20:21], v[22:23], v[32:33] op_sel_hi:[1,0]
	v_exp_f32_e32 v28, v28
	v_exp_f32_e32 v29, v29
	v_exp_f32_e32 v20, v20
	v_exp_f32_e32 v21, v21
	v_rcp_f32_e32 v36, v36
	v_pk_add_f32 v[28:29], v[28:29], 1.0 op_sel_hi:[1,0]
	v_rcp_f32_e32 v37, v37
	v_pk_add_f32 v[20:21], v[20:21], 1.0 op_sel_hi:[1,0]
	v_rcp_f32_e32 v28, v28
	v_rcp_f32_e32 v29, v29
	v_rcp_f32_e32 v20, v20
	v_rcp_f32_e32 v21, v21
	v_pk_mul_f32 v[16:17], v[16:17], v[34:35] op_sel_hi:[1,0]
	v_pk_mul_f32 v[18:19], v[18:19], v[34:35] op_sel_hi:[1,0]
	v_pk_mul_f32 v[24:25], v[24:25], v[36:37]
	v_pk_mul_f32 v[16:17], v[16:17], v[28:29]
	v_pk_mul_f32 v[18:19], v[18:19], v[20:21]
	v_mov_b32_e32 v20, 0
	v_mov_b32_e32 v21, 0
	v_cvt_pk_fp8_f32 v20, v24, v25
	v_cvt_pk_fp8_f32 v21, v16, v17
	v_add_u32_e32 v16, 0xa0, v148
	v_mad_i64_i32 v[16:17], s[14:15], v16, s18, v[112:113]
	v_cvt_pk_fp8_f32 v20, v26, v27 op_sel:[0,0,1]
	v_cvt_pk_fp8_f32 v21, v18, v19 op_sel:[0,0,1]
	v_lshl_add_u64 v[16:17], v[16:17], 0, v[134:135]
	v_pk_mul_f32 v[8:9], v[12:13], v[8:9]
	v_mul_f32_e32 v18, v137, v137
	global_store_dwordx2 v[16:17], v[20:21], off
	v_mul_f32_e32 v16, 0xbfb8aa3b, v137
	v_pk_mul_f32 v[20:21], v[12:13], v[16:17] op_sel_hi:[1,0]
	v_pk_mul_f32 v[12:13], v[14:15], v[16:17] op_sel_hi:[1,0]
	v_pk_mul_f32 v[10:11], v[14:15], v[10:11]
	v_exp_f32_e32 v12, v12
	v_exp_f32_e32 v13, v13
	v_pk_mul_f32 v[10:11], v[10:11], v[18:19] op_sel_hi:[1,0]
	v_pk_mul_f32 v[0:1], v[4:5], v[0:1]
	v_exp_f32_e32 v20, v20
	v_pk_add_f32 v[12:13], v[12:13], 1.0 op_sel_hi:[1,0]
	v_exp_f32_e32 v21, v21
	v_rcp_f32_e32 v12, v12
	v_rcp_f32_e32 v13, v13
	v_pk_mul_f32 v[2:3], v[6:7], v[2:3]
	v_pk_add_f32 v[20:21], v[20:21], 1.0 op_sel_hi:[1,0]
	v_pk_mul_f32 v[8:9], v[8:9], v[18:19] op_sel_hi:[1,0]
	v_pk_mul_f32 v[10:11], v[10:11], v[12:13]
	v_pk_mul_f32 v[12:13], v[4:5], v[16:17] op_sel_hi:[1,0]
	v_pk_mul_f32 v[4:5], v[6:7], v[16:17] op_sel_hi:[1,0]
	v_exp_f32_e32 v12, v12
	v_exp_f32_e32 v13, v13
	v_exp_f32_e32 v4, v4
	v_exp_f32_e32 v5, v5
	v_rcp_f32_e32 v20, v20
	v_pk_add_f32 v[12:13], v[12:13], 1.0 op_sel_hi:[1,0]
	v_rcp_f32_e32 v21, v21
	v_pk_add_f32 v[4:5], v[4:5], 1.0 op_sel_hi:[1,0]
	v_rcp_f32_e32 v12, v12
	v_rcp_f32_e32 v13, v13
	v_rcp_f32_e32 v4, v4
	v_rcp_f32_e32 v5, v5
	v_pk_mul_f32 v[0:1], v[0:1], v[18:19] op_sel_hi:[1,0]
	v_pk_mul_f32 v[2:3], v[2:3], v[18:19] op_sel_hi:[1,0]
	v_pk_mul_f32 v[8:9], v[8:9], v[20:21]
	v_pk_mul_f32 v[0:1], v[0:1], v[12:13]
	v_pk_mul_f32 v[2:3], v[2:3], v[4:5]
	v_mov_b32_e32 v4, 0
	v_mov_b32_e32 v5, 0
	v_cvt_pk_fp8_f32 v4, v8, v9
	v_cvt_pk_fp8_f32 v5, v0, v1
	v_add_u32_e32 v0, 0xb0, v148
	v_mad_i64_i32 v[0:1], s[14:15], v0, s18, v[112:113]
	v_cvt_pk_fp8_f32 v4, v10, v11 op_sel:[0,0,1]
	v_cvt_pk_fp8_f32 v5, v2, v3 op_sel:[0,0,1]
	v_lshl_add_u64 v[0:1], v[0:1], 0, v[134:135]
	s_mov_b64 s[14:15], -1
	s_andn2_b64 vcc, exec, s[38:39]
	global_store_dwordx2 v[0:1], v[4:5], off
	s_cbranch_vccnz .LBB0_477
	s_lshl_b32 s14, s40, 8
	s_ashr_i32 s15, s14, 31
	v_lshl_add_u64 v[0:1], s[14:15], 2, v[132:133]
	global_load_dword v134, v[0:1], off
	s_mov_b32 s101, 1
	s_andn2_b64 vcc, exec, s[8:9]
	s_cbranch_vccnz .LBB0_476
	s_mov_b32 s98, 1
	s_branch .LBB0_476

.Lnostb8:
	s_add_u32 s14, s46, 0xfffe0080
	s_addc_u32 s15, s47, -1
	s_add_i32 s60, 0, 0x10000
	s_cmp_eq_u32 s51, 4
	s_cselect_b32 s15, s13, s15
	s_cselect_b32 s14, s31, s14
	s_cselect_b32 s17, s11, s50
	s_cselect_b32 s16, s48, s49
	s_add_i32 s61, 0, 0x14000
	v_add_u32_e32 v0, s60, v172
	v_add_u32_e32 v4, s61, v172
	ds_read_b128 v[24:27], v0
	ds_read_b128 v[28:31], v0 offset:1024
	ds_read_b128 v[16:19], v0 offset:2048
	ds_read_b128 v[20:23], v0 offset:3072
	ds_read_b128 v[8:11], v4
	ds_read_b128 v[12:15], v4 offset:1024
	ds_read_b128 v[0:3], v4 offset:2048
	ds_read_b128 v[4:7], v4 offset:3072
	v_lshl_add_u64 v[166:167], s[46:47], 0, v[164:165]
	s_add_i32 m0, s19, 0xc000
	ds_read_b128 v[194:197], v176
	ds_read_b128 v[198:201], v176 offset:1024
	ds_read_b128 v[202:205], v176 offset:2048
	ds_read_b128 v[206:209], v176 offset:3072
	ds_read_b128 v[210:213], v176 offset:4096
	ds_read_b128 v[214:217], v176 offset:5120
	ds_read_b128 v[218:221], v176 offset:6144
	ds_read_b128 v[222:225], v176 offset:7168
	global_load_lds_dwordx4 v[166:167], off
	v_lshl_add_u64 v[166:167], v[166:167], 0, s[94:95]
	s_add_i32 m0, s19, 0xe000
	s_nop 0
	global_load_lds_dwordx4 v[166:167], off
	s_cmp_eq_u32 s101, 0
	s_cbranch_scc1 .Lbw8_0s
	s_waitcnt vmcnt(18)
	s_branch .Lbw8_0d

.Lbw8_0d:
	s_waitcnt lgkmcnt(0)
	s_barrier
	s_setprio 1
	s_waitcnt lgkmcnt(0)
	v_mfma_scale_f32_16x16x128_f8f6f4 v[156:159], v[24:31], v[194:201], 0, v240, v240 op_sel_hi:[0,0,0]
	v_mfma_scale_f32_16x16x128_f8f6f4 v[148:151], v[16:23], v[194:201], 0, v240, v240 op_sel_hi:[0,0,0]
	v_mfma_scale_f32_16x16x128_f8f6f4 v[140:143], v[24:31], v[202:209], 0, v240, v240 op_sel_hi:[0,0,0]
	v_mfma_scale_f32_16x16x128_f8f6f4 v[132:135], v[16:23], v[202:209], 0, v240, v240 op_sel_hi:[0,0,0]
	v_mfma_scale_f32_16x16x128_f8f6f4 v[124:127], v[24:31], v[210:217], 0, v240, v240 op_sel_hi:[0,0,0]
	v_mfma_scale_f32_16x16x128_f8f6f4 v[116:119], v[16:23], v[210:217], 0, v240, v240 op_sel_hi:[0,0,0]
	v_mfma_scale_f32_16x16x128_f8f6f4 v[108:111], v[24:31], v[218:225], 0, v240, v240 op_sel_hi:[0,0,0]
	v_mfma_scale_f32_16x16x128_f8f6f4 v[100:103], v[16:23], v[218:225], 0, v240, v240 op_sel_hi:[0,0,0]
	s_setprio 0
	s_setprio 1
	v_mfma_scale_f32_16x16x128_f8f6f4 v[152:155], v[8:15], v[194:201], 0, v240, v240 op_sel_hi:[0,0,0]
	v_mfma_scale_f32_16x16x128_f8f6f4 v[144:147], v[0:7], v[194:201], 0, v240, v240 op_sel_hi:[0,0,0]
	v_mfma_scale_f32_16x16x128_f8f6f4 v[136:139], v[8:15], v[202:209], 0, v240, v240 op_sel_hi:[0,0,0]
	v_mfma_scale_f32_16x16x128_f8f6f4 v[128:131], v[0:7], v[202:209], 0, v240, v240 op_sel_hi:[0,0,0]
	v_mfma_scale_f32_16x16x128_f8f6f4 v[120:123], v[8:15], v[210:217], 0, v240, v240 op_sel_hi:[0,0,0]
	v_mfma_scale_f32_16x16x128_f8f6f4 v[112:115], v[0:7], v[210:217], 0, v240, v240 op_sel_hi:[0,0,0]
	v_mfma_scale_f32_16x16x128_f8f6f4 v[104:107], v[8:15], v[218:225], 0, v240, v240 op_sel_hi:[0,0,0]
	v_mfma_scale_f32_16x16x128_f8f6f4 v[96:99], v[0:7], v[218:225], 0, v240, v240 op_sel_hi:[0,0,0]
	s_setprio 0
	s_barrier
	v_lshl_add_u64 v[166:167], s[16:17], 0, v[184:185]
	s_add_i32 s16, s60, s6
	s_mov_b32 m0, s16
	ds_read_b128 v[194:197], v176 offset:16384
	ds_read_b128 v[198:201], v176 offset:17408
	ds_read_b128 v[202:205], v176 offset:18432
	ds_read_b128 v[206:209], v176 offset:19456
	ds_read_b128 v[210:213], v176 offset:20480
	ds_read_b128 v[214:217], v176 offset:21504
	ds_read_b128 v[218:221], v176 offset:22528
	ds_read_b128 v[222:225], v176 offset:23552
	global_load_lds_dwordx4 v[166:167], off
	v_lshl_add_u64 v[168:169], v[166:167], 0, s[94:95]
	s_add_i32 m0, s16, 0x2000
	s_add_i32 s16, s61, s6
	global_load_lds_dwordx4 v[168:169], off
	v_lshl_add_u64 v[168:169], v[166:167], 0, s[34:35]
	s_mov_b32 m0, s16
	s_nop 0
	global_load_lds_dwordx4 v[168:169], off
	v_lshl_add_u64 v[168:169], v[166:167], 0, s[90:91]
	s_add_i32 m0, s16, 0x2000
	s_nop 0
	global_load_lds_dwordx4 v[168:169], off
	v_lshl_add_u64 v[168:169], s[14:15], 0, v[160:161]
	s_mov_b32 m0, s19
	v_lshl_add_u64 v[178:179], v[168:169], 0, s[94:95]
	global_load_lds_dwordx4 v[168:169], off
	s_mov_b32 m0, s20
	s_nop 0
	global_load_lds_dwordx4 v[178:179], off
	s_cmp_eq_u32 s101, 0
	s_cbranch_scc1 .Lbw8_1s
	s_waitcnt vmcnt(22)
	s_branch .Lbw8_1d

.Lbw8_1d:
	s_waitcnt lgkmcnt(0)
	s_barrier
	s_setprio 1
	s_waitcnt lgkmcnt(0)
	v_mfma_scale_f32_16x16x128_f8f6f4 v[92:95], v[24:31], v[194:201], 0, v240, v240 op_sel_hi:[0,0,0]
	v_mfma_scale_f32_16x16x128_f8f6f4 v[84:87], v[16:23], v[194:201], 0, v240, v240 op_sel_hi:[0,0,0]
	v_mfma_scale_f32_16x16x128_f8f6f4 v[76:79], v[24:31], v[202:209], 0, v240, v240 op_sel_hi:[0,0,0]
	v_mfma_scale_f32_16x16x128_f8f6f4 v[68:71], v[16:23], v[202:209], 0, v240, v240 op_sel_hi:[0,0,0]
	v_mfma_scale_f32_16x16x128_f8f6f4 v[60:63], v[24:31], v[210:217], 0, v240, v240 op_sel_hi:[0,0,0]
	v_mfma_scale_f32_16x16x128_f8f6f4 v[52:55], v[16:23], v[210:217], 0, v240, v240 op_sel_hi:[0,0,0]
	v_mfma_scale_f32_16x16x128_f8f6f4 v[44:47], v[24:31], v[218:225], 0, v240, v240 op_sel_hi:[0,0,0]
	v_mfma_scale_f32_16x16x128_f8f6f4 v[36:39], v[16:23], v[218:225], 0, v240, v240 op_sel_hi:[0,0,0]
	s_setprio 0
	s_setprio 1
	v_mfma_scale_f32_16x16x128_f8f6f4 v[88:91], v[8:15], v[194:201], 0, v240, v240 op_sel_hi:[0,0,0]
	v_mfma_scale_f32_16x16x128_f8f6f4 v[80:83], v[0:7], v[194:201], 0, v240, v240 op_sel_hi:[0,0,0]
	v_mfma_scale_f32_16x16x128_f8f6f4 v[72:75], v[8:15], v[202:209], 0, v240, v240 op_sel_hi:[0,0,0]
	v_mfma_scale_f32_16x16x128_f8f6f4 v[64:67], v[0:7], v[202:209], 0, v240, v240 op_sel_hi:[0,0,0]
	v_mfma_scale_f32_16x16x128_f8f6f4 v[56:59], v[8:15], v[210:217], 0, v240, v240 op_sel_hi:[0,0,0]
	v_mfma_scale_f32_16x16x128_f8f6f4 v[48:51], v[0:7], v[210:217], 0, v240, v240 op_sel_hi:[0,0,0]
	v_mfma_scale_f32_16x16x128_f8f6f4 v[40:43], v[8:15], v[218:225], 0, v240, v240 op_sel_hi:[0,0,0]
	v_mfma_scale_f32_16x16x128_f8f6f4 v[32:35], v[0:7], v[218:225], 0, v240, v240 op_sel_hi:[0,0,0]
	s_setprio 0
	s_barrier
	s_add_i32 s14, 0, 0x18000
	s_add_i32 s15, 0, 0x1c000
	v_add_u32_e32 v12, s14, v172
	v_add_u32_e32 v28, s15, v172
	ds_read_b128 v[0:3], v12
	ds_read_b128 v[4:7], v12 offset:1024
	ds_read_b128 v[8:11], v12 offset:2048
	ds_read_b128 v[12:15], v12 offset:3072
	ds_read_b128 v[16:19], v28
	ds_read_b128 v[20:23], v28 offset:1024
	ds_read_b128 v[24:27], v28 offset:2048
	ds_read_b128 v[28:31], v28 offset:3072
	s_mov_b32 m0, s24
	v_lshl_add_u64 v[178:179], v[168:169], 0, s[34:35]
	ds_read_b128 v[194:197], v176 offset:32768
	ds_read_b128 v[198:201], v176 offset:33792
	ds_read_b128 v[202:205], v176 offset:34816
	ds_read_b128 v[206:209], v176 offset:35840
	ds_read_b128 v[210:213], v176 offset:36864
	ds_read_b128 v[214:217], v176 offset:37888
	ds_read_b128 v[218:221], v176 offset:38912
	ds_read_b128 v[222:225], v176 offset:39936
	global_load_lds_dwordx4 v[178:179], off
	v_lshl_add_u64 v[178:179], v[168:169], 0, s[90:91]
	s_mov_b32 m0, s25
	s_nop 0
	global_load_lds_dwordx4 v[178:179], off
	s_cmp_eq_u32 s101, 0
	s_cbranch_scc1 .Lbw8_2s
	s_waitcnt vmcnt(18)
	s_branch .Lbw8_2d

.Lbw8_2d:
	s_waitcnt lgkmcnt(0)
	s_barrier
	s_setprio 1
	s_waitcnt lgkmcnt(0)
	v_mfma_scale_f32_16x16x128_f8f6f4 v[156:159], v[0:7], v[194:201], v[156:159], v240, v240 op_sel_hi:[0,0,0]
	v_mfma_scale_f32_16x16x128_f8f6f4 v[148:151], v[8:15], v[194:201], v[148:151], v240, v240 op_sel_hi:[0,0,0]
	v_mfma_scale_f32_16x16x128_f8f6f4 v[140:143], v[0:7], v[202:209], v[140:143], v240, v240 op_sel_hi:[0,0,0]
	v_mfma_scale_f32_16x16x128_f8f6f4 v[132:135], v[8:15], v[202:209], v[132:135], v240, v240 op_sel_hi:[0,0,0]
	v_mfma_scale_f32_16x16x128_f8f6f4 v[124:127], v[0:7], v[210:217], v[124:127], v240, v240 op_sel_hi:[0,0,0]
	v_mfma_scale_f32_16x16x128_f8f6f4 v[116:119], v[8:15], v[210:217], v[116:119], v240, v240 op_sel_hi:[0,0,0]
	v_mfma_scale_f32_16x16x128_f8f6f4 v[108:111], v[0:7], v[218:225], v[108:111], v240, v240 op_sel_hi:[0,0,0]
	v_mfma_scale_f32_16x16x128_f8f6f4 v[100:103], v[8:15], v[218:225], v[100:103], v240, v240 op_sel_hi:[0,0,0]
	s_setprio 0
	s_setprio 1
	v_mfma_scale_f32_16x16x128_f8f6f4 v[152:155], v[16:23], v[194:201], v[152:155], v240, v240 op_sel_hi:[0,0,0]
	v_mfma_scale_f32_16x16x128_f8f6f4 v[144:147], v[24:31], v[194:201], v[144:147], v240, v240 op_sel_hi:[0,0,0]
	v_mfma_scale_f32_16x16x128_f8f6f4 v[136:139], v[16:23], v[202:209], v[136:139], v240, v240 op_sel_hi:[0,0,0]
	v_mfma_scale_f32_16x16x128_f8f6f4 v[128:131], v[24:31], v[202:209], v[128:131], v240, v240 op_sel_hi:[0,0,0]
	v_mfma_scale_f32_16x16x128_f8f6f4 v[120:123], v[16:23], v[210:217], v[120:123], v240, v240 op_sel_hi:[0,0,0]
	v_mfma_scale_f32_16x16x128_f8f6f4 v[112:115], v[24:31], v[210:217], v[112:115], v240, v240 op_sel_hi:[0,0,0]
	v_mfma_scale_f32_16x16x128_f8f6f4 v[104:107], v[16:23], v[218:225], v[104:107], v240, v240 op_sel_hi:[0,0,0]
	v_mfma_scale_f32_16x16x128_f8f6f4 v[96:99], v[24:31], v[218:225], v[96:99], v240, v240 op_sel_hi:[0,0,0]
	s_setprio 0
	s_barrier
	s_add_i32 s14, s14, s6
	v_lshl_add_u64 v[178:179], v[166:167], 0, s[56:57]
	s_mov_b32 m0, s14
	ds_read_b128 v[194:197], v176 offset:49152
	ds_read_b128 v[198:201], v176 offset:50176
	ds_read_b128 v[202:205], v176 offset:51200
	ds_read_b128 v[206:209], v176 offset:52224
	ds_read_b128 v[210:213], v176 offset:53248
	ds_read_b128 v[214:217], v176 offset:54272
	ds_read_b128 v[218:221], v176 offset:55296
	ds_read_b128 v[222:225], v176 offset:56320
	global_load_lds_dwordx4 v[178:179], off
	v_lshl_add_u64 v[178:179], v[166:167], 0, s[58:59]
	s_add_i32 m0, s14, 0x2000
	s_add_i32 s14, s15, s6
	global_load_lds_dwordx4 v[178:179], off
	v_lshl_add_u64 v[178:179], v[166:167], 0, s[96:97]
	s_mov_b32 m0, s14
	v_lshl_add_u64 v[166:167], v[166:167], 0, s[4:5]
	global_load_lds_dwordx4 v[178:179], off
	s_add_i32 m0, s14, 0x2000
	s_nop 0
	global_load_lds_dwordx4 v[166:167], off
	v_lshl_add_u64 v[166:167], v[168:169], 0, s[56:57]
	s_mov_b32 m0, s26
	s_nop 0
	global_load_lds_dwordx4 v[166:167], off
	v_lshl_add_u64 v[166:167], v[168:169], 0, s[58:59]
	s_mov_b32 m0, s27
	s_nop 0
	global_load_lds_dwordx4 v[166:167], off
	s_waitcnt vmcnt(14)
	s_waitcnt lgkmcnt(0)
	s_barrier
	s_setprio 1
	s_waitcnt lgkmcnt(0)
	v_mfma_scale_f32_16x16x128_f8f6f4 v[92:95], v[0:7], v[194:201], v[92:95], v240, v240 op_sel_hi:[0,0,0]
	v_mfma_scale_f32_16x16x128_f8f6f4 v[84:87], v[8:15], v[194:201], v[84:87], v240, v240 op_sel_hi:[0,0,0]
	v_mfma_scale_f32_16x16x128_f8f6f4 v[76:79], v[0:7], v[202:209], v[76:79], v240, v240 op_sel_hi:[0,0,0]
	v_mfma_scale_f32_16x16x128_f8f6f4 v[68:71], v[8:15], v[202:209], v[68:71], v240, v240 op_sel_hi:[0,0,0]
	v_mfma_scale_f32_16x16x128_f8f6f4 v[60:63], v[0:7], v[210:217], v[60:63], v240, v240 op_sel_hi:[0,0,0]
	v_mfma_scale_f32_16x16x128_f8f6f4 v[52:55], v[8:15], v[210:217], v[52:55], v240, v240 op_sel_hi:[0,0,0]
	v_mfma_scale_f32_16x16x128_f8f6f4 v[44:47], v[0:7], v[218:225], v[44:47], v240, v240 op_sel_hi:[0,0,0]
	v_mfma_scale_f32_16x16x128_f8f6f4 v[36:39], v[8:15], v[218:225], v[36:39], v240, v240 op_sel_hi:[0,0,0]
	s_setprio 0
	s_setprio 1
	v_mfma_scale_f32_16x16x128_f8f6f4 v[88:91], v[16:23], v[194:201], v[88:91], v240, v240 op_sel_hi:[0,0,0]
	v_mfma_scale_f32_16x16x128_f8f6f4 v[80:83], v[24:31], v[194:201], v[80:83], v240, v240 op_sel_hi:[0,0,0]
	v_mfma_scale_f32_16x16x128_f8f6f4 v[72:75], v[16:23], v[202:209], v[72:75], v240, v240 op_sel_hi:[0,0,0]
	v_mfma_scale_f32_16x16x128_f8f6f4 v[64:67], v[24:31], v[202:209], v[64:67], v240, v240 op_sel_hi:[0,0,0]
	v_mfma_scale_f32_16x16x128_f8f6f4 v[56:59], v[16:23], v[210:217], v[56:59], v240, v240 op_sel_hi:[0,0,0]
	v_mfma_scale_f32_16x16x128_f8f6f4 v[48:51], v[24:31], v[210:217], v[48:51], v240, v240 op_sel_hi:[0,0,0]
	v_mfma_scale_f32_16x16x128_f8f6f4 v[40:43], v[16:23], v[218:225], v[40:43], v240, v240 op_sel_hi:[0,0,0]
	v_mfma_scale_f32_16x16x128_f8f6f4 v[32:35], v[24:31], v[218:225], v[32:35], v240, v240 op_sel_hi:[0,0,0]
	s_setprio 0
	s_barrier
	s_add_i32 s51, s51, 2
	s_add_u32 s46, s46, 0x100
	s_addc_u32 s47, s47, 0
	s_add_u32 s49, s49, 0x100
	s_addc_u32 s50, s50, 0
	s_cmp_gt_u32 s51, 5

.LBB0_511:
	s_mov_b32 s101, 1
	s_andn2_b64 vcc, exec, s[0:1]
	s_cbranch_vccnz .LBB0_498
	s_mov_b32 s98, 1
	s_branch .LBB0_498

.LBB0_515:
	s_mov_b32 s99, 0
	s_mov_b32 s98, 0
	s_mov_b32 s101, 0
	s_waitcnt vmcnt(0)
	s_waitcnt vmcnt(0) lgkmcnt(0)
	s_barrier
	s_and_saveexec_b64 s[0:1], s[62:63]
	s_cbranch_execz .LBB0_202
	v_readlane_b32 s6, v254, 49
	s_cmp_eq_u32 s100, 1
	s_cbranch_scc0 .Lgbar
	s_add_i32 s9, s6, 1
	s_lshl_b32 s9, s9, 5
	v_readlane_b32 s8, v252, 0
	v_readlane_b32 s10, v252, 45
	v_readlane_b32 s11, v252, 46
	s_and_b32 s8, s8, 7
	s_add_u32 s10, s10, 0xe3600
	s_addc_u32 s11, s11, 0
	s_lshl_b32 s13, 1, s8
	s_lshl_b32 s14, s8, 6
	v_mov_b32_e32 v1, 1
	v_mov_b32_e32 v2, s14
	s_cmp_eq_u32 s6, 2
	s_cbranch_scc1 .Llb_h
	s_cmp_eq_u32 s6, 9
	s_cbranch_scc1 .Llb_h
	s_mov_b32 s16, 0x0e060301
	s_mov_b32 s17, 0xb058281c
	s_cmp_eq_u32 s6, 1
	s_cbranch_scc1 .Llb_tab
	s_mov_b32 s16, 0x0a060301
	s_mov_b32 s17, 0x88482414
	s_cmp_eq_u32 s6, 6
	s_cbranch_scc1 .Llb_tab
	s_mov_b32 s16, 0x0c060301
	s_mov_b32 s17, 0xa070381c
	s_cmp_eq_u32 s6, 8
	s_cbranch_scc1 .Llb_tab
	s_mov_b32 s16, 0xf83c1e07
	s_mov_b32 s17, 0x8040a0d0
	s_cmp_eq_u32 s6, 4
	s_cbranch_scc1 .Llb_tab
	s_mov_b32 s16, 0x783c0e07
	s_mov_b32 s17, 0x8040e0f0
	s_cmp_eq_u32 s6, 11
	s_cbranch_scc1 .Llb_tab
	s_branch .Llb_have
